# P6 gated-delta chunk inverse: off-diagonal 32x32 block of (I+L)^-1 via 16 v_mfma_f32_32x32x2_f32 (f32 operands, f32 accumulate) instead of 1024 scalar-broadcast f32 FMA steps; diagonal blocks unchange
# baseline (speedup 1.0000x reference)
.LBB0_685:
	s_or_b64 exec, exec, s[62:63]
	s_waitcnt lgkmcnt(0)
	v_sub_f32_e32 v43, v131, v43
	v_mul_f32_e32 v43, 0x3fb8aa3b, v43
	v_sub_f32_e32 v42, v131, v42
	v_exp_f32_e32 v43, v43
	v_mul_f32_e32 v42, 0x3fb8aa3b, v42
	v_sub_f32_e32 v41, v131, v41
	v_exp_f32_e32 v42, v42
	v_mul_f32_e32 v41, 0x3fb8aa3b, v41
	v_sub_f32_e32 v40, v131, v40
	v_exp_f32_e32 v41, v41
	v_mul_f32_e32 v40, 0x3fb8aa3b, v40
	v_mul_f32_e32 v44, 0x3db504f3, v49
	v_exp_f32_e32 v40, v40
	v_mul_f32_e32 v43, v44, v43
	v_mul_f32_e32 v44, 0x3db504f3, v48
	v_mul_f32_e32 v42, v44, v42
	v_mul_f32_e32 v44, 0x3db504f3, v47
	v_mul_f32_e32 v41, v44, v41
	v_mul_f32_e32 v44, 0x3db504f3, v46
	v_sub_f32_e32 v45, v162, v131
	v_mul_f32_e32 v40, v44, v40
	v_sub_f32_e32 v44, v162, v130
	v_mul_f32_e32 v45, 0x3fb8aa3b, v45
	v_mul_f32_e32 v44, 0x3fb8aa3b, v44
	v_exp_f32_e32 v45, v45
	v_exp_f32_e32 v44, v44
	v_mul_f32_e32 v17, v17, v163
	v_mul_f32_e32 v33, v33, v163
	v_mul_f32_e32 v17, v17, v45
	v_mul_f32_e32 v211, v33, v44
	v_cndmask_b32_e64 v62, 0, v17, s[60:61]
	v_sub_f32_e32 v17, v160, v130
	v_sub_f32_e32 v33, v160, v131
	v_mul_f32_e32 v17, 0x3fb8aa3b, v17
	v_mul_f32_e32 v33, 0x3fb8aa3b, v33
	v_exp_f32_e32 v17, v17
	v_exp_f32_e32 v33, v33
	v_mul_f32_e32 v32, v32, v161
	v_mul_f32_e32 v16, v16, v161
	v_mul_f32_e32 v212, v32, v17
	v_mul_f32_e32 v16, v16, v33
	v_sub_f32_e32 v17, v158, v131
	v_cndmask_b32_e64 v66, 0, v16, s[58:59]
	v_sub_f32_e32 v16, v158, v130
	v_mul_f32_e32 v17, 0x3fb8aa3b, v17
	v_mul_f32_e32 v16, 0x3fb8aa3b, v16
	v_exp_f32_e32 v17, v17
	v_exp_f32_e32 v16, v16
	v_mul_f32_e32 v15, v15, v159
	v_mul_f32_e32 v31, v31, v159
	v_mul_f32_e32 v15, v15, v17
	v_mul_f32_e32 v213, v31, v16
	v_cndmask_b32_e64 v70, 0, v15, s[56:57]
	v_sub_f32_e32 v15, v156, v130
	v_sub_f32_e32 v16, v156, v131
	v_mul_f32_e32 v15, 0x3fb8aa3b, v15
	v_mul_f32_e32 v16, 0x3fb8aa3b, v16
	v_exp_f32_e32 v15, v15
	v_exp_f32_e32 v16, v16
	v_mul_f32_e32 v17, v30, v157
	v_mul_f32_e32 v14, v14, v157
	v_mul_f32_e32 v214, v17, v15
	v_mul_f32_e32 v14, v14, v16
	v_sub_f32_e32 v15, v154, v130
	v_sub_f32_e32 v16, v154, v131
	v_mul_f32_e32 v15, 0x3fb8aa3b, v15
	v_mul_f32_e32 v16, 0x3fb8aa3b, v16
	v_exp_f32_e32 v15, v15
	v_exp_f32_e32 v16, v16
	v_mul_f32_e32 v17, v29, v155
	v_mul_f32_e32 v13, v13, v155
	v_mul_f32_e32 v215, v17, v15
	v_mul_f32_e32 v13, v13, v16
	v_sub_f32_e32 v15, v152, v131
	v_cndmask_b32_e64 v74, 0, v13, s[52:53]
	v_sub_f32_e32 v13, v152, v130
	v_mul_f32_e32 v15, 0x3fb8aa3b, v15
	v_mul_f32_e32 v13, 0x3fb8aa3b, v13
	v_exp_f32_e32 v15, v15
	v_exp_f32_e32 v13, v13
	v_mul_f32_e32 v12, v12, v153
	v_mul_f32_e32 v16, v28, v153
	v_mul_f32_e32 v12, v12, v15
	v_mul_f32_e32 v216, v16, v13
	v_cndmask_b32_e64 v28, 0, v12, s[50:51]
	v_sub_f32_e32 v12, v150, v130
	v_sub_f32_e32 v13, v150, v131
	v_mul_f32_e32 v12, 0x3fb8aa3b, v12
	v_mul_f32_e32 v13, 0x3fb8aa3b, v13
	v_exp_f32_e32 v12, v12
	v_exp_f32_e32 v13, v13
	v_mul_f32_e32 v15, v27, v151
	v_mul_f32_e32 v11, v11, v151
	v_mul_f32_e32 v217, v15, v12
	v_mul_f32_e32 v11, v11, v13
	v_sub_f32_e32 v12, v148, v131
	v_cndmask_b32_e64 v78, 0, v11, s[48:49]
	v_sub_f32_e32 v11, v148, v130
	v_mul_f32_e32 v12, 0x3fb8aa3b, v12
	v_mul_f32_e32 v11, 0x3fb8aa3b, v11
	v_exp_f32_e32 v12, v12
	v_exp_f32_e32 v11, v11
	v_mul_f32_e32 v10, v10, v149
	v_mul_f32_e32 v13, v26, v149
	v_mul_f32_e32 v10, v10, v12
	v_mul_f32_e32 v218, v13, v11
	v_cndmask_b32_e64 v82, 0, v10, s[46:47]
	v_sub_f32_e32 v10, v146, v130
	v_sub_f32_e32 v11, v146, v131
	v_mul_f32_e32 v10, 0x3fb8aa3b, v10
	v_mul_f32_e32 v11, 0x3fb8aa3b, v11
	v_exp_f32_e32 v10, v10
	v_exp_f32_e32 v11, v11
	v_mul_f32_e32 v12, v25, v147
	v_mul_f32_e32 v9, v9, v147
	v_mul_f32_e32 v219, v12, v10
	v_mul_f32_e32 v9, v9, v11
	v_sub_f32_e32 v10, v144, v131
	v_cndmask_b32_e64 v84, 0, v9, s[44:45]
	v_sub_f32_e32 v9, v144, v130
	v_mul_f32_e32 v10, 0x3fb8aa3b, v10
	v_mul_f32_e32 v9, 0x3fb8aa3b, v9
	v_exp_f32_e32 v10, v10
	v_exp_f32_e32 v9, v9
	v_mul_f32_e32 v8, v8, v145
	v_mul_f32_e32 v11, v24, v145
	v_mul_f32_e32 v8, v8, v10
	v_mul_f32_e32 v220, v11, v9
	v_cndmask_b32_e64 v24, 0, v8, s[42:43]
	v_sub_f32_e32 v8, v142, v130
	v_sub_f32_e32 v9, v142, v131
	v_mul_f32_e32 v8, 0x3fb8aa3b, v8
	v_mul_f32_e32 v9, 0x3fb8aa3b, v9
	v_exp_f32_e32 v8, v8
	v_exp_f32_e32 v9, v9
	v_mul_f32_e32 v10, v23, v143
	v_mul_f32_e32 v7, v7, v143
	v_mul_f32_e32 v221, v10, v8
	v_mul_f32_e32 v7, v7, v9
	v_sub_f32_e32 v8, v140, v131
	v_cndmask_b32_e64 v142, 0, v7, s[40:41]
	v_sub_f32_e32 v7, v140, v130
	v_mul_f32_e32 v8, 0x3fb8aa3b, v8
	v_mul_f32_e32 v7, 0x3fb8aa3b, v7
	v_exp_f32_e32 v8, v8
	v_exp_f32_e32 v7, v7
	v_mul_f32_e32 v6, v6, v141
	v_mul_f32_e32 v9, v22, v141
	v_mul_f32_e32 v6, v6, v8
	v_sub_f32_e32 v8, v138, v131
	v_mul_f32_e32 v222, v9, v7
	v_sub_f32_e32 v7, v138, v130
	v_mul_f32_e32 v8, 0x3fb8aa3b, v8
	v_mul_f32_e32 v7, 0x3fb8aa3b, v7
	v_exp_f32_e32 v8, v8
	v_exp_f32_e32 v7, v7
	v_mul_f32_e32 v5, v5, v139
	v_mul_f32_e32 v9, v21, v139
	v_mul_f32_e32 v5, v5, v8
	v_mul_f32_e32 v223, v9, v7
	v_cndmask_b32_e64 v140, 0, v5, s[8:9]
	v_sub_f32_e32 v5, v136, v130
	v_sub_f32_e32 v7, v136, v131
	v_mul_f32_e32 v5, 0x3fb8aa3b, v5
	v_mul_f32_e32 v7, 0x3fb8aa3b, v7
	v_exp_f32_e32 v5, v5
	v_exp_f32_e32 v7, v7
	v_mul_f32_e32 v8, v20, v137
	v_mul_f32_e32 v4, v4, v137
	v_mul_f32_e32 v224, v8, v5
	v_mul_f32_e32 v4, v4, v7
	v_sub_f32_e32 v5, v134, v131
	v_cndmask_b32_e64 v144, 0, v4, s[6:7]
	v_sub_f32_e32 v4, v134, v130
	v_mul_f32_e32 v5, 0x3fb8aa3b, v5
	v_mul_f32_e32 v4, 0x3fb8aa3b, v4
	v_exp_f32_e32 v5, v5
	v_exp_f32_e32 v4, v4
	v_mul_f32_e32 v3, v3, v135
	v_mul_f32_e32 v7, v19, v135
	v_mul_f32_e32 v3, v3, v5
	v_mul_f32_e32 v225, v7, v4
	v_cndmask_b32_e64 v146, v3, 0, s[4:5]
	v_sub_f32_e32 v3, v132, v130
	v_sub_f32_e32 v4, v132, v131
	v_mul_f32_e32 v3, 0x3fb8aa3b, v3
	v_mul_f32_e32 v4, 0x3fb8aa3b, v4
	v_exp_f32_e32 v3, v3
	v_exp_f32_e32 v4, v4
	v_mul_f32_e32 v5, v18, v133
	v_mul_f32_e32 v2, v2, v133
	v_mul_f32_e32 v226, v5, v3
	v_mul_f32_e32 v2, v2, v4
	v_cvt_pk_bf16_f32 v4, v40, v41
	v_cvt_pk_bf16_f32 v5, v42, v43
	global_store_dwordx2 v[34:35], v[4:5], off offset:48
	v_cvt_pk_bf16_f32 v4, v36, v38
	v_cvt_pk_bf16_f32 v5, v37, v39
	global_store_dwordx2 v[34:35], v[4:5], off offset:112
	v_cndmask_b32_e64 v14, 0, v14, s[54:55]
	v_cndmask_b32_e64 v6, 0, v6, s[38:39]
	v_cndmask_b32_e64 v2, 0, v2, s[0:1]
	v_lshlrev_b64 v[86:87], 1, v[128:129]
	s_add_u32 s0, s94, s28
	v_lshl_add_u64 v[4:5], v[122:123], 0, v[86:87]
	s_addc_u32 s1, s95, s29
	v_lshl_add_u64 v[98:99], s[0:1], 0, v[4:5]
	s_mov_b32 s4, 0x9000000
	v_add_co_u32_e32 v4, vcc, s4, v98
	s_mov_b32 s4, 0x9001000
	s_nop 0
	v_addc_co_u32_e32 v5, vcc, 0, v99, vcc
	v_add_co_u32_e32 v8, vcc, s4, v98
	v_lshlrev_b32_e32 v90, 4, v126
	s_nop 0
	v_addc_co_u32_e32 v9, vcc, 0, v99, vcc
	v_cmp_eq_u32_e32 vcc, 63, v126
	global_load_dwordx4 v[58:61], v[4:5], off offset:32
	global_load_dwordx4 v[54:57], v[4:5], off offset:64
	global_load_dwordx4 v[18:21], v[8:9], off offset:-4096
	global_load_dwordx4 v[50:53], v[4:5], off offset:96
	global_load_dwordx4 v[46:49], v[8:9], off
	global_load_dwordx4 v[42:45], v[8:9], off offset:32
	global_load_dwordx4 v[38:41], v[8:9], off offset:64
	global_load_dwordx4 v[34:37], v[8:9], off offset:96
	v_cndmask_b32_e64 v89, 0, 1.0, vcc
	v_cmp_eq_u32_e32 vcc, 62, v126
	v_add_u32_e32 v92, 0x1000, v90
	v_ashrrev_i32_e32 v93, 31, v92
	v_cndmask_b32_e64 v3, 0, 1.0, vcc
	v_cmp_eq_u32_e32 vcc, 61, v126
	v_lshl_add_u64 v[120:121], v[92:93], 1, s[0:1]
	v_add_u32_e32 v92, 0x1400, v90
	v_cndmask_b32_e64 v4, 0, 1.0, vcc
	v_cmp_eq_u32_e32 vcc, 60, v126
	v_ashrrev_i32_e32 v93, 31, v92
	v_lshl_add_u64 v[112:113], v[92:93], 1, s[0:1]
	v_cndmask_b32_e64 v8, 0, 1.0, vcc
	v_cmp_eq_u32_e32 vcc, 59, v126
	v_add_u32_e32 v92, 0x800, v90
	v_ashrrev_i32_e32 v91, 31, v90
	v_cndmask_b32_e64 v5, 0, 1.0, vcc
	v_cmp_eq_u32_e32 vcc, 58, v126
	v_ashrrev_i32_e32 v93, 31, v92
	v_add_u32_e32 v100, 0x1800, v90
	v_cndmask_b32_e64 v9, 0, 1.0, vcc
	v_cmp_eq_u32_e32 vcc, 57, v126
	v_lshl_add_u64 v[108:109], v[92:93], 1, s[0:1]
	v_add_u32_e32 v92, 0xc00, v90
	v_cndmask_b32_e64 v95, 0, 1.0, vcc
	v_cmp_eq_u32_e32 vcc, 56, v126
	s_nop 7
	s_mov_b32 s54, 62
	s_nop 0
	v_readlane_b32 s4, v62, s54
	s_nop 1
	v_fma_f32 v3, -s4, v89, v3
	s_mov_b32 s55, 61
	v_cndmask_b32_e64 v181, 0, 1.0, vcc
	v_cmp_eq_u32_e32 vcc, 55, v126
	v_add_f32_e32 v88, 0, v3
	s_nop 0
	v_readlane_b32 s4, v66, s55
	s_nop 1
	v_fma_f32 v4, -s4, v88, v4
	v_ashrrev_i32_e32 v101, 31, v100
	v_cndmask_b32_e64 v11, 0, 1.0, vcc
	v_cmp_eq_u32_e32 vcc, 54, v126
	s_nop 0
	v_readlane_b32 s4, v62, s55
	s_nop 1
	v_fma_f32 v4, -s4, v89, v4
	v_lshl_add_u64 v[106:107], v[100:101], 1, s[0:1]
	v_ashrrev_i32_e32 v93, 31, v92
	v_cndmask_b32_e64 v97, 0, 1.0, vcc
	v_cmp_eq_u32_e32 vcc, 53, v126
	s_mov_b32 s56, 60
	v_lshl_add_u64 v[102:103], v[92:93], 1, s[0:1]
	v_cndmask_b32_e64 v13, 0, 1.0, vcc
	v_cmp_eq_u32_e32 vcc, 52, v126
	v_mov_b32_e32 v93, v123
	v_mov_b32_e32 v92, v123
	v_cndmask_b32_e64 v105, 0, 1.0, vcc
	v_cmp_eq_u32_e32 vcc, 51, v126
	s_mov_b32 s57, 59
	s_mov_b32 s53, 26
	v_cndmask_b32_e64 v17, 0, 1.0, vcc
	v_cmp_eq_u32_e32 vcc, 50, v126
	s_mov_b32 s58, 58
	v_mov_b32_e32 v94, v123
	v_cndmask_b32_e64 v111, 0, 1.0, vcc
	v_cmp_eq_u32_e32 vcc, 49, v126
	s_mov_b32 s52, 25
	s_mov_b32 s59, 57
	v_cndmask_b32_e64 v23, 0, 1.0, vcc
	v_cmp_eq_u32_e32 vcc, 48, v126
	v_mul_f32_e32 v10, 0x3fb8aa3b, v166
	v_mov_b32_e32 v180, v123
	v_cndmask_b32_e64 v115, 0, 1.0, vcc
	v_cmp_eq_u32_e32 vcc, 47, v126
	v_exp_f32_e32 v10, v10
	s_mov_b32 s51, 24
	v_cndmask_b32_e64 v27, 0, 1.0, vcc
	v_cmp_eq_u32_e32 vcc, 46, v126
	s_mov_b32 s60, 56
	v_mul_f32_e32 v210, v193, v10
	v_cndmask_b32_e64 v117, 0, 1.0, vcc
	v_cmp_eq_u32_e32 vcc, 45, v126
	v_mov_b32_e32 v10, v123
	s_mov_b32 s70, 23
	v_cndmask_b32_e64 v31, 0, 1.0, vcc
	v_cmp_eq_u32_e32 vcc, 44, v126
	s_mov_b32 s61, 55
	v_mov_b32_e32 v96, v123
	v_cndmask_b32_e64 v119, 0, 1.0, vcc
	v_cmp_eq_u32_e32 vcc, 43, v126
	s_mov_b32 s62, 54
	s_mov_b32 s71, 22
	v_cndmask_b32_e64 v33, 0, 1.0, vcc
	v_cmp_eq_u32_e32 vcc, 42, v126
	v_mov_b32_e32 v12, v123
	s_mov_b32 s63, 53
	v_cndmask_b32_e64 v129, 0, 1.0, vcc
	v_cmp_eq_u32_e32 vcc, 41, v126
	s_mov_b32 s72, 21
	v_mov_b32_e32 v104, v123
	v_cndmask_b32_e64 v65, 0, 1.0, vcc
	v_cmp_eq_u32_e32 vcc, 40, v126
	s_mov_b32 s73, 20
	v_mov_b32_e32 v16, v123
	v_cndmask_b32_e64 v131, 0, 1.0, vcc
	v_cmp_eq_u32_e32 vcc, 39, v126
	s_mov_b32 s64, 51
	s_mov_b32 s50, 19
	v_cndmask_b32_e64 v69, 0, 1.0, vcc
	v_cmp_eq_u32_e32 vcc, 38, v126
	v_mov_b32_e32 v110, v123
	s_mov_b32 s49, 18
	v_cndmask_b32_e64 v133, 0, 1.0, vcc
	v_cmp_eq_u32_e32 vcc, 37, v126
	s_mov_b32 s65, 50
	v_mov_b32_e32 v22, v123
	v_cndmask_b32_e64 v73, 0, 1.0, vcc
	v_cmp_eq_u32_e32 vcc, 36, v126
	s_mov_b32 s48, 17
	v_mov_b32_e32 v114, v123
	v_cndmask_b32_e64 v135, 0, 1.0, vcc
	v_cmp_eq_u32_e32 vcc, 35, v126
	s_mov_b32 s47, 16
	v_mov_b32_e32 v26, v123
	v_cndmask_b32_e64 v77, 0, 1.0, vcc
	v_cmp_eq_u32_e32 vcc, 34, v126
	s_mov_b32 s45, 15
	s_mov_b32 s66, 47
	v_cndmask_b32_e64 v137, 0, 1.0, vcc
	v_cmp_eq_u32_e32 vcc, 33, v126
	v_mov_b32_e32 v116, v123
	s_mov_b32 s39, 14
	v_cndmask_b32_e64 v81, 0, 1.0, vcc
	v_cmp_eq_u32_e32 vcc, 32, v126
	v_mov_b32_e32 v30, v123
	s_mov_b32 s38, 13
	v_cndmask_b32_e64 v139, 0, 1.0, vcc
	v_cmp_eq_u32_e32 vcc, 31, v126
	v_mov_b32_e32 v118, v123
	s_mov_b32 s43, 12
	v_cndmask_b32_e64 v153, 0, 1.0, vcc
	v_cmp_eq_u32_e32 vcc, 30, v126
	v_mov_b32_e32 v32, v123
	s_mov_b32 s67, 43
	v_cndmask_b32_e64 v141, 0, 1.0, vcc
	v_cmp_eq_u32_e32 vcc, 29, v126
	s_mov_b32 s42, 11
	v_mov_b32_e32 v128, v123
	v_cndmask_b32_e64 v159, 0, 1.0, vcc
	v_cmp_eq_u32_e32 vcc, 28, v126
	s_mov_b32 s46, 10
	s_lshl_b32 s4, s20, 4
	v_cndmask_b32_e64 v143, 0, 1.0, vcc
	v_cmp_eq_u32_e32 vcc, 27, v126
	v_mov_b32_e32 v64, v123
	s_or_b32 s4, s37, s4
	v_cndmask_b32_e64 v167, 0, 1.0, vcc
	v_cmp_eq_u32_e32 vcc, 26, v126
	s_mov_b32 s37, 9
	v_mov_b32_e32 v130, v123
	v_cndmask_b32_e64 v145, 0, 1.0, vcc
	v_cmp_eq_u32_e32 vcc, 25, v126
	s_mov_b32 s40, 8
	v_mov_b32_e32 v68, v123
	v_cndmask_b32_e64 v171, 0, 1.0, vcc
	v_cmp_eq_u32_e32 vcc, 24, v126
	s_mov_b32 s44, 7
	s_mov_b32 s68, 39
	v_cndmask_b32_e64 v147, 0, 1.0, vcc
	v_cmp_eq_u32_e32 vcc, 23, v126
	v_mov_b32_e32 v132, v123
	v_mov_b32_e32 v72, v123
	v_cndmask_b32_e64 v175, 0, 1.0, vcc
	v_cmp_eq_u32_e32 vcc, 22, v126
	v_mov_b32_e32 v134, v123
	v_mov_b32_e32 v76, v123
	v_cndmask_b32_e64 v149, 0, 1.0, vcc
	v_cmp_eq_u32_e32 vcc, 21, v126
	s_mov_b32 s69, 35
	s_mov_b32 s12, 3
	v_cndmask_b32_e64 v179, 0, 1.0, vcc
	v_cmp_eq_u32_e32 vcc, 20, v126
	v_mov_b32_e32 v136, v123
	v_mov_b32_e32 v80, v123
	v_cndmask_b32_e64 v151, 0, 1.0, vcc
	v_cmp_eq_u32_e32 vcc, 19, v126
	v_mov_b32_e32 v138, v123
	v_mov_b32_e32 v152, v123
	v_cndmask_b32_e64 v177, 0, 1.0, vcc
	v_cmp_eq_u32_e32 vcc, 18, v126
	s_mov_b32 s41, 31
	s_mov_b32 s20, 63
	v_cndmask_b32_e64 v157, 0, 1.0, vcc
	v_cmp_eq_u32_e32 vcc, 17, v126
	v_mov_b32_e32 v158, v123
	v_mov_b32_e32 v166, v123
	v_cndmask_b32_e64 v173, 0, 1.0, vcc
	v_cmp_eq_u32_e32 vcc, 16, v126
	v_mov_b32_e32 v170, v123
	v_mov_b32_e32 v174, v123
	v_cndmask_b32_e64 v165, 0, 1.0, vcc
	v_cmp_eq_u32_e32 vcc, 15, v126
	v_mov_b32_e32 v148, v123
	v_mov_b32_e32 v178, v123
	v_cndmask_b32_e64 v169, 0, 1.0, vcc
	v_cmp_eq_u32_e32 vcc, 14, v126
	v_mov_b32_e32 v150, v123
	v_mov_b32_e32 v176, v123
	v_cndmask_b32_e64 v163, 0, 1.0, vcc
	v_cmp_eq_u32_e32 vcc, 13, v126
	v_mov_b32_e32 v156, v123
	v_mov_b32_e32 v172, v123
	v_cndmask_b32_e64 v161, 0, 1.0, vcc
	v_cmp_eq_u32_e32 vcc, 12, v126
	v_mov_b32_e32 v164, v123
	v_mov_b32_e32 v168, v123
	v_cndmask_b32_e64 v155, 0, 1.0, vcc
	v_cmp_eq_u32_e32 vcc, 11, v126
	v_mov_b32_e32 v162, v123
	v_mov_b32_e32 v160, v123
	v_cndmask_b32_e64 v85, 0, 1.0, vcc
	v_cmp_eq_u32_e32 vcc, 10, v126
	v_mov_b32_e32 v154, v123
	s_ashr_i32 s5, s4, 31
	v_cndmask_b32_e64 v83, 0, 1.0, vcc
	v_cmp_eq_u32_e32 vcc, 9, v126
	s_nop 1
	v_cndmask_b32_e64 v79, 0, 1.0, vcc
	v_cmp_eq_u32_e32 vcc, 8, v126
	s_nop 1
	v_cndmask_b32_e64 v75, 0, 1.0, vcc
	v_cmp_eq_u32_e32 vcc, 7, v126
	s_nop 1
	v_cndmask_b32_e64 v71, 0, 1.0, vcc
	v_cmp_eq_u32_e32 vcc, 6, v126
	s_nop 1
	v_cndmask_b32_e64 v67, 0, 1.0, vcc
	v_cmp_eq_u32_e32 vcc, 5, v126
	s_nop 1
	v_cndmask_b32_e64 v63, 0, 1.0, vcc
	v_cmp_eq_u32_e32 vcc, 4, v126
	s_nop 1
	v_cndmask_b32_e64 v29, 0, 1.0, vcc
	v_cmp_eq_u32_e32 vcc, 3, v126
	s_nop 1
	v_cndmask_b32_e64 v25, 0, 1.0, vcc
	v_cmp_eq_u32_e32 vcc, 2, v126
	s_nop 1
	v_cndmask_b32_e64 v15, 0, 1.0, vcc
	v_cmp_eq_u32_e32 vcc, 1, v126
	s_nop 1
	v_cndmask_b32_e64 v7, 0, 1.0, vcc
	v_cmp_eq_u32_e32 vcc, 0, v126
	v_lshl_add_u64 v[126:127], v[90:91], 1, s[0:1]
	v_add_u32_e32 v90, 0x1c00, v90
	v_ashrrev_i32_e32 v91, 31, v90
	v_lshl_add_u64 v[100:101], v[90:91], 1, s[0:1]
	v_add_f32_e32 v91, 0, v4
	s_nop 0
	v_readlane_b32 s6, v70, s56
	s_nop 1
	v_fma_f32 v8, -s6, v91, v8
	v_mov_b32_e32 v4, v123
	s_nop 0
	v_readlane_b32 s6, v66, s56
	s_nop 1
	v_fma_f32 v8, -s6, v88, v8
	v_cndmask_b32_e64 v3, 0, 1.0, vcc
	s_nop 0
	v_readlane_b32 s6, v62, s56
	s_nop 1
	v_fma_f32 v8, -s6, v89, v8
	s_nop 0
	v_add_f32_e32 v90, 0, v8
	s_nop 0
	v_readlane_b32 s6, v14, s57
	v_readlane_b32 s7, v70, s57
	v_readlane_b32 s8, v66, s57
	v_readlane_b32 s9, v62, s57
	v_fma_f32 v5, -s6, v90, v5
	v_fma_f32 v93, -s7, v91, v93
	v_fma_f32 v92, -s8, v88, v92
	v_fma_f32 v4, -s9, v89, v4
	v_mov_b32_e32 v8, v123
	v_pk_add_f32 v[4:5], v[92:93], v[4:5]
	v_mov_b32_e32 v93, v123
	v_mov_b32_e32 v92, v123
	v_pk_add_f32 v[4:5], v[4:5], v[4:5] op_sel:[0,1] op_sel_hi:[1,0]
	s_nop 0
	s_nop 0
	v_readlane_b32 s6, v62, s53
	v_readlane_b32 s7, v14, s58
	v_readlane_b32 s8, v70, s58
	v_readlane_b32 s9, v66, s58
	v_fma_f32 v9, -s6, v4, v9
	v_fma_f32 v93, -s7, v90, v93
	v_fma_f32 v92, -s8, v91, v92
	v_fma_f32 v8, -s9, v88, v8
	s_nop 0
	s_nop 0
	v_readlane_b32 s6, v62, s58
	s_nop 1
	v_fma_f32 v9, -s6, v89, v9
	s_nop 0
	v_pk_add_f32 v[8:9], v[92:93], v[8:9]
	s_nop 0
	v_pk_add_f32 v[92:93], v[8:9], v[8:9] op_sel:[0,1] op_sel_hi:[1,0]
	v_mov_b32_e32 v9, v123
	v_mov_b32_e32 v8, v123
	s_nop 0
	v_readlane_b32 s6, v66, s52
	v_readlane_b32 s7, v62, s52
	v_readlane_b32 s8, v14, s59
	v_readlane_b32 s9, v70, s59
	v_fma_f32 v95, -s6, v92, v95
	v_fma_f32 v9, -s7, v4, v9
	v_fma_f32 v8, -s8, v90, v8
	v_fma_f32 v94, -s9, v91, v94
	v_mov_b32_e32 v93, v4
	s_nop 0
	v_readlane_b32 s6, v66, s59
	s_nop 1
	v_fma_f32 v95, -s6, v88, v95
	s_nop 0
	s_nop 0
	v_readlane_b32 s6, v62, s59
	s_nop 1
	v_fma_f32 v95, -s6, v89, v95
	s_nop 0
	v_pk_add_f32 v[8:9], v[8:9], v[94:95]
	v_mov_b32_e32 v95, v123
	v_mov_b32_e32 v94, v123
	v_pk_add_f32 v[8:9], v[8:9], v[8:9] op_sel:[0,1] op_sel_hi:[1,0]
	s_nop 0
	s_nop 0
	v_readlane_b32 s6, v70, s51
	v_readlane_b32 s7, v66, s51
	v_readlane_b32 s8, v62, s51
	v_readlane_b32 s9, v14, s60
	v_fma_f32 v181, -s6, v8, v181
	v_fma_f32 v95, -s7, v92, v95
	v_fma_f32 v94, -s8, v4, v94
	v_fma_f32 v180, -s9, v90, v180
	s_nop 0
	s_nop 0
	v_readlane_b32 s6, v70, s60
	s_nop 1
	v_fma_f32 v181, -s6, v91, v181
	s_nop 0
	s_nop 0
	v_readlane_b32 s6, v66, s60
	s_nop 1
	v_fma_f32 v181, -s6, v88, v181
	s_nop 0
	s_nop 0
	v_readlane_b32 s6, v62, s60
	s_nop 1
	v_fma_f32 v181, -s6, v89, v181
	s_nop 0
	v_pk_add_f32 v[94:95], v[94:95], v[180:181]
	v_mov_b32_e32 v181, v123
	v_mov_b32_e32 v180, v123
	v_pk_add_f32 v[94:95], v[94:95], v[94:95] op_sel:[0,1] op_sel_hi:[1,0]
	s_nop 0
	s_nop 0
	v_readlane_b32 s6, v14, s70
	v_readlane_b32 s7, v70, s70
	v_readlane_b32 s8, v66, s70
	v_readlane_b32 s9, v62, s70
	v_fma_f32 v11, -s6, v94, v11
	v_fma_f32 v181, -s7, v8, v181
	v_fma_f32 v180, -s8, v92, v180
	v_fma_f32 v10, -s9, v4, v10
	v_mov_b32_e32 v95, v8
	s_nop 0
	v_readlane_b32 s6, v14, s61
	v_readlane_b32 s7, v70, s61
	v_readlane_b32 s8, v66, s61
	v_readlane_b32 s9, v62, s61
	v_fma_f32 v11, -s6, v90, v11
	v_fma_f32 v181, -s7, v91, v181
	v_fma_f32 v180, -s8, v88, v180
	v_fma_f32 v10, -s9, v89, v10
	s_nop 0
	v_pk_add_f32 v[10:11], v[180:181], v[10:11]
	v_mov_b32_e32 v181, v123
	v_mov_b32_e32 v180, v123
	v_pk_add_f32 v[10:11], v[10:11], v[10:11] op_sel:[0,1] op_sel_hi:[1,0]
	s_nop 0
	s_nop 0
	v_readlane_b32 s6, v74, s62
	v_readlane_b32 s7, v14, s71
	v_readlane_b32 s8, v70, s71
	v_readlane_b32 s9, v66, s71
	v_fma_f32 v97, -s6, v10, v97
	v_fma_f32 v181, -s7, v94, v181
	v_fma_f32 v180, -s8, v8, v180
	v_fma_f32 v96, -s9, v92, v96
	s_nop 0
	s_nop 0
	v_readlane_b32 s6, v62, s71
	v_readlane_b32 s7, v14, s62
	v_readlane_b32 s8, v70, s62
	v_readlane_b32 s9, v66, s62
	v_fma_f32 v97, -s6, v4, v97
	v_fma_f32 v181, -s7, v90, v181
	v_fma_f32 v180, -s8, v91, v180
	v_fma_f32 v96, -s9, v88, v96
	s_nop 0
	s_nop 0
	v_readlane_b32 s6, v62, s62
	s_nop 1
	v_fma_f32 v97, -s6, v89, v97
	s_nop 0
	v_pk_add_f32 v[96:97], v[180:181], v[96:97]
	v_mov_b32_e32 v181, v123
	v_mov_b32_e32 v180, v123
	v_pk_add_f32 v[96:97], v[96:97], v[96:97] op_sel:[0,1] op_sel_hi:[1,0]
	s_nop 0
	s_nop 0
	v_readlane_b32 s6, v28, s63
	v_readlane_b32 s7, v74, s63
	v_readlane_b32 s8, v14, s72
	v_readlane_b32 s9, v70, s72
	v_fma_f32 v13, -s6, v96, v13
	v_fma_f32 v181, -s7, v10, v181
	v_fma_f32 v180, -s8, v94, v180
	v_fma_f32 v12, -s9, v8, v12
	v_mov_b32_e32 v97, v10
	s_nop 0
	v_readlane_b32 s6, v66, s72
	v_readlane_b32 s7, v62, s72
	v_readlane_b32 s8, v14, s63
	v_readlane_b32 s9, v70, s63
	v_fma_f32 v13, -s6, v92, v13
	v_fma_f32 v181, -s7, v4, v181
	v_fma_f32 v180, -s8, v90, v180
	v_fma_f32 v12, -s9, v91, v12
	s_nop 0
	s_nop 0
	v_readlane_b32 s6, v66, s63
	s_nop 1
	v_fma_f32 v13, -s6, v88, v13
	s_nop 0
	s_nop 0
	v_readlane_b32 s6, v62, s63
	s_nop 1
	v_fma_f32 v13, -s6, v89, v13
	s_nop 0
	v_pk_add_f32 v[12:13], v[180:181], v[12:13]
	v_mov_b32_e32 v181, v123
	v_mov_b32_e32 v180, v123
	v_pk_add_f32 v[12:13], v[12:13], v[12:13] op_sel:[0,1] op_sel_hi:[1,0]
	s_nop 0
	s_nop 0
	v_readlane_b32 s6, v78, s22
	v_readlane_b32 s7, v28, s22
	v_readlane_b32 s8, v74, s22
	v_readlane_b32 s9, v14, s73
	v_fma_f32 v105, -s6, v12, v105
	v_fma_f32 v181, -s7, v96, v181
	v_fma_f32 v180, -s8, v10, v180
	v_fma_f32 v104, -s9, v94, v104
	s_nop 0
	s_nop 0
	v_readlane_b32 s6, v70, s73
	v_readlane_b32 s7, v66, s73
	v_readlane_b32 s8, v62, s73
	v_readlane_b32 s9, v14, s22
	v_fma_f32 v105, -s6, v8, v105
	v_fma_f32 v181, -s7, v92, v181
	v_fma_f32 v180, -s8, v4, v180
	v_fma_f32 v104, -s9, v90, v104
	s_nop 0
	s_nop 0
	v_readlane_b32 s6, v70, s22
	s_nop 1
	v_fma_f32 v105, -s6, v91, v105
	s_nop 0
	s_nop 0
	v_readlane_b32 s6, v66, s22
	s_nop 1
	v_fma_f32 v105, -s6, v88, v105
	s_nop 0
	s_nop 0
	v_readlane_b32 s6, v62, s22
	s_nop 1
	v_fma_f32 v105, -s6, v89, v105
	s_nop 0
	v_pk_add_f32 v[104:105], v[180:181], v[104:105]
	v_mov_b32_e32 v181, v123
	v_mov_b32_e32 v180, v123
	v_pk_add_f32 v[104:105], v[104:105], v[104:105] op_sel:[0,1] op_sel_hi:[1,0]
	s_nop 0
	s_nop 0
	v_readlane_b32 s6, v82, s64
	v_readlane_b32 s7, v78, s64
	v_readlane_b32 s8, v28, s64
	v_readlane_b32 s9, v74, s64
	v_fma_f32 v17, -s6, v104, v17
	v_fma_f32 v181, -s7, v12, v181
	v_fma_f32 v180, -s8, v96, v180
	v_fma_f32 v16, -s9, v10, v16
	v_mov_b32_e32 v105, v12
	s_nop 0
	v_readlane_b32 s6, v14, s50
	v_readlane_b32 s7, v70, s50
	v_readlane_b32 s8, v66, s50
	v_readlane_b32 s9, v62, s50
	v_fma_f32 v17, -s6, v94, v17
	v_fma_f32 v181, -s7, v8, v181
	v_fma_f32 v180, -s8, v92, v180
	v_fma_f32 v16, -s9, v4, v16
	s_nop 0
	s_nop 0
	v_readlane_b32 s6, v14, s64
	v_readlane_b32 s7, v70, s64
	v_readlane_b32 s8, v66, s64
	v_readlane_b32 s9, v62, s64
	v_fma_f32 v17, -s6, v90, v17
	v_fma_f32 v181, -s7, v91, v181
	v_fma_f32 v180, -s8, v88, v180
	v_fma_f32 v16, -s9, v89, v16
	s_nop 0
	v_pk_add_f32 v[16:17], v[180:181], v[16:17]
	v_mov_b32_e32 v181, v123
	v_mov_b32_e32 v180, v123
	v_pk_add_f32 v[16:17], v[16:17], v[16:17] op_sel:[0,1] op_sel_hi:[1,0]
	s_nop 0
	s_nop 0
	v_readlane_b32 s6, v74, s49
	v_readlane_b32 s7, v82, s65
	v_readlane_b32 s8, v78, s65
	v_readlane_b32 s9, v28, s65
	v_fma_f32 v111, -s6, v16, v111
	v_fma_f32 v181, -s7, v104, v181
	v_fma_f32 v180, -s8, v12, v180
	v_fma_f32 v110, -s9, v96, v110
	s_nop 0
	s_nop 0
	v_readlane_b32 s6, v74, s65
	v_readlane_b32 s7, v14, s49
	v_readlane_b32 s8, v70, s49
	v_readlane_b32 s9, v66, s49
	v_fma_f32 v111, -s6, v10, v111
	v_fma_f32 v181, -s7, v94, v181
	v_fma_f32 v180, -s8, v8, v180
	v_fma_f32 v110, -s9, v92, v110
	s_nop 0
	s_nop 0
	v_readlane_b32 s6, v62, s49
	v_readlane_b32 s7, v14, s65
	v_readlane_b32 s8, v70, s65
	v_readlane_b32 s9, v66, s65
	v_fma_f32 v111, -s6, v4, v111
	v_fma_f32 v181, -s7, v90, v181
	v_fma_f32 v180, -s8, v91, v180
	v_fma_f32 v110, -s9, v88, v110
	s_nop 0
	s_nop 0
	v_readlane_b32 s6, v62, s65
	s_nop 1
	v_fma_f32 v111, -s6, v89, v111
	s_nop 0
	v_pk_add_f32 v[110:111], v[180:181], v[110:111]
	v_mov_b32_e32 v181, v123
	v_mov_b32_e32 v180, v123
	v_pk_add_f32 v[110:111], v[110:111], v[110:111] op_sel:[0,1] op_sel_hi:[1,0]
	s_nop 0
	s_nop 0
	v_readlane_b32 s6, v28, s48
	v_readlane_b32 s7, v74, s48
	v_readlane_b32 s8, v82, s21
	v_readlane_b32 s9, v78, s21
	v_fma_f32 v23, -s6, v110, v23
	v_fma_f32 v181, -s7, v16, v181
	v_fma_f32 v180, -s8, v104, v180
	v_fma_f32 v22, -s9, v12, v22
	v_mov_b32_e32 v111, v16
	s_nop 0
	v_readlane_b32 s6, v28, s21
	v_readlane_b32 s7, v74, s21
	v_readlane_b32 s8, v14, s48
	v_readlane_b32 s9, v70, s48
	v_fma_f32 v23, -s6, v96, v23
	v_fma_f32 v181, -s7, v10, v181
	v_fma_f32 v180, -s8, v94, v180
	v_fma_f32 v22, -s9, v8, v22
	s_nop 0
	s_nop 0
	v_readlane_b32 s6, v66, s48
	v_readlane_b32 s7, v62, s48
	v_readlane_b32 s8, v14, s21
	v_readlane_b32 s9, v70, s21
	v_fma_f32 v23, -s6, v92, v23
	v_fma_f32 v181, -s7, v4, v181
	v_fma_f32 v180, -s8, v90, v180
	v_fma_f32 v22, -s9, v91, v22
	s_nop 0
	s_nop 0
	v_readlane_b32 s6, v66, s21
	s_nop 1
	v_fma_f32 v23, -s6, v88, v23
	s_nop 0
	s_nop 0
	v_readlane_b32 s6, v62, s21
	s_nop 1
	v_fma_f32 v23, -s6, v89, v23
	s_nop 0
	v_pk_add_f32 v[22:23], v[180:181], v[22:23]
	v_mov_b32_e32 v181, v123
	v_mov_b32_e32 v180, v123
	v_pk_add_f32 v[22:23], v[22:23], v[22:23] op_sel:[0,1] op_sel_hi:[1,0]
	s_nop 0
	s_nop 0
	v_readlane_b32 s6, v78, s47
	v_readlane_b32 s7, v28, s47
	v_readlane_b32 s8, v74, s47
	v_readlane_b32 s9, v82, s34
	v_fma_f32 v115, -s6, v22, v115
	v_fma_f32 v181, -s7, v110, v181
	v_fma_f32 v180, -s8, v16, v180
	v_fma_f32 v114, -s9, v104, v114
	s_nop 0
	s_nop 0
	v_readlane_b32 s6, v78, s34
	v_readlane_b32 s7, v28, s34
	v_readlane_b32 s8, v74, s34
	v_readlane_b32 s9, v14, s47
	v_fma_f32 v115, -s6, v12, v115
	v_fma_f32 v181, -s7, v96, v181
	v_fma_f32 v180, -s8, v10, v180
	v_fma_f32 v114, -s9, v94, v114
	s_nop 0
	s_nop 0
	v_readlane_b32 s6, v70, s47
	v_readlane_b32 s7, v66, s47
	v_readlane_b32 s8, v62, s47
	v_readlane_b32 s9, v14, s34
	v_fma_f32 v115, -s6, v8, v115
	v_fma_f32 v181, -s7, v92, v181
	v_fma_f32 v180, -s8, v4, v180
	v_fma_f32 v114, -s9, v90, v114
	s_nop 0
	s_nop 0
	v_readlane_b32 s6, v70, s34
	s_nop 1
	v_fma_f32 v115, -s6, v91, v115
	s_nop 0
	s_nop 0
	v_readlane_b32 s6, v66, s34
	s_nop 1
	v_fma_f32 v115, -s6, v88, v115
	s_nop 0
	s_nop 0
	v_readlane_b32 s6, v62, s34
	s_nop 1
	v_fma_f32 v115, -s6, v89, v115
	s_nop 0
	v_pk_add_f32 v[114:115], v[180:181], v[114:115]
	v_mov_b32_e32 v181, v123
	v_mov_b32_e32 v180, v123
	v_pk_add_f32 v[114:115], v[114:115], v[114:115] op_sel:[0,1] op_sel_hi:[1,0]
	s_nop 0
	s_nop 0
	v_readlane_b32 s6, v82, s45
	v_readlane_b32 s7, v78, s45
	v_readlane_b32 s8, v28, s45
	v_readlane_b32 s9, v74, s45
	v_fma_f32 v27, -s6, v114, v27
	v_fma_f32 v181, -s7, v22, v181
	v_fma_f32 v180, -s8, v110, v180
	v_fma_f32 v26, -s9, v16, v26
	v_mov_b32_e32 v115, v22
	s_nop 0
	v_readlane_b32 s6, v82, s66
	v_readlane_b32 s7, v78, s66
	v_readlane_b32 s8, v28, s66
	v_readlane_b32 s9, v74, s66
	v_fma_f32 v27, -s6, v104, v27
	v_fma_f32 v181, -s7, v12, v181
	v_fma_f32 v180, -s8, v96, v180
	v_fma_f32 v26, -s9, v10, v26
	s_nop 0
	s_nop 0
	v_readlane_b32 s6, v14, s45
	v_readlane_b32 s7, v70, s45
	v_readlane_b32 s8, v66, s45
	v_readlane_b32 s9, v62, s45
	v_fma_f32 v27, -s6, v94, v27
	v_fma_f32 v181, -s7, v8, v181
	v_fma_f32 v180, -s8, v92, v180
	v_fma_f32 v26, -s9, v4, v26
	s_nop 0
	s_nop 0
	v_readlane_b32 s6, v14, s66
	v_readlane_b32 s7, v70, s66
	v_readlane_b32 s8, v66, s66
	v_readlane_b32 s9, v62, s66
	v_fma_f32 v27, -s6, v90, v27
	v_fma_f32 v181, -s7, v91, v181
	v_fma_f32 v180, -s8, v88, v180
	v_fma_f32 v26, -s9, v89, v26
	s_nop 0
	v_pk_add_f32 v[26:27], v[180:181], v[26:27]
	v_mov_b32_e32 v181, v123
	v_mov_b32_e32 v180, v123
	v_pk_add_f32 v[26:27], v[26:27], v[26:27] op_sel:[0,1] op_sel_hi:[1,0]
	s_nop 0
	s_nop 0
	v_readlane_b32 s6, v84, s14
	v_readlane_b32 s7, v82, s39
	v_readlane_b32 s8, v78, s39
	v_readlane_b32 s9, v28, s39
	v_fma_f32 v117, -s6, v26, v117
	v_fma_f32 v181, -s7, v114, v181
	v_fma_f32 v180, -s8, v22, v180
	v_fma_f32 v116, -s9, v110, v116
	s_nop 0
	s_nop 0
	v_readlane_b32 s6, v74, s39
	v_readlane_b32 s7, v82, s14
	v_readlane_b32 s8, v78, s14
	v_readlane_b32 s9, v28, s14
	v_fma_f32 v117, -s6, v16, v117
	v_fma_f32 v181, -s7, v104, v181
	v_fma_f32 v180, -s8, v12, v180
	v_fma_f32 v116, -s9, v96, v116
	s_nop 0
	s_nop 0
	v_readlane_b32 s6, v74, s14
	v_readlane_b32 s7, v14, s39
	v_readlane_b32 s8, v70, s39
	v_readlane_b32 s9, v66, s39
	v_fma_f32 v117, -s6, v10, v117
	v_fma_f32 v181, -s7, v94, v181
	v_fma_f32 v180, -s8, v8, v180
	v_fma_f32 v116, -s9, v92, v116
	s_nop 0
	s_nop 0
	v_readlane_b32 s6, v62, s39
	v_readlane_b32 s7, v14, s14
	v_readlane_b32 s8, v70, s14
	v_readlane_b32 s9, v66, s14
	v_fma_f32 v117, -s6, v4, v117
	v_fma_f32 v181, -s7, v90, v181
	v_fma_f32 v180, -s8, v91, v180
	v_fma_f32 v116, -s9, v88, v116
	s_nop 0
	s_nop 0
	v_readlane_b32 s6, v62, s14
	s_nop 1
	v_fma_f32 v117, -s6, v89, v117
	s_nop 0
	v_pk_add_f32 v[116:117], v[180:181], v[116:117]
	v_mov_b32_e32 v181, v123
	v_mov_b32_e32 v180, v123
	v_pk_add_f32 v[116:117], v[116:117], v[116:117] op_sel:[0,1] op_sel_hi:[1,0]
	s_nop 0
	s_nop 0
	v_readlane_b32 s6, v24, s11
	v_readlane_b32 s7, v84, s11
	v_readlane_b32 s8, v82, s38
	v_readlane_b32 s9, v78, s38
	v_fma_f32 v31, -s6, v116, v31
	v_fma_f32 v181, -s7, v26, v181
	v_fma_f32 v180, -s8, v114, v180
	v_fma_f32 v30, -s9, v22, v30
	v_mov_b32_e32 v117, v26
	s_nop 0
	v_readlane_b32 s6, v28, s38
	v_readlane_b32 s7, v74, s38
	v_readlane_b32 s8, v82, s11
	v_readlane_b32 s9, v78, s11
	v_fma_f32 v31, -s6, v110, v31
	v_fma_f32 v181, -s7, v16, v181
	v_fma_f32 v180, -s8, v104, v180
	v_fma_f32 v30, -s9, v12, v30
	s_nop 0
	s_nop 0
	v_readlane_b32 s6, v28, s11
	v_readlane_b32 s7, v74, s11
	v_readlane_b32 s8, v14, s38
	v_readlane_b32 s9, v70, s38
	v_fma_f32 v31, -s6, v96, v31
	v_fma_f32 v181, -s7, v10, v181
	v_fma_f32 v180, -s8, v94, v180
	v_fma_f32 v30, -s9, v8, v30
	s_nop 0
	s_nop 0
	v_readlane_b32 s6, v66, s38
	v_readlane_b32 s7, v62, s38
	v_readlane_b32 s8, v14, s11
	v_readlane_b32 s9, v70, s11
	v_fma_f32 v31, -s6, v92, v31
	v_fma_f32 v181, -s7, v4, v181
	v_fma_f32 v180, -s8, v90, v180
	v_fma_f32 v30, -s9, v91, v30
	s_nop 0
	s_nop 0
	v_readlane_b32 s6, v66, s11
	s_nop 1
	v_fma_f32 v31, -s6, v88, v31
	s_nop 0
	s_nop 0
	v_readlane_b32 s6, v62, s11
	s_nop 1
	v_fma_f32 v31, -s6, v89, v31
	s_nop 0
	v_pk_add_f32 v[30:31], v[180:181], v[30:31]
	v_mov_b32_e32 v181, v123
	v_mov_b32_e32 v180, v123
	v_pk_add_f32 v[30:31], v[30:31], v[30:31] op_sel:[0,1] op_sel_hi:[1,0]
	s_nop 0
	s_nop 0
	v_readlane_b32 s6, v142, s27
	v_readlane_b32 s7, v24, s27
	v_readlane_b32 s8, v84, s27
	v_readlane_b32 s9, v82, s43
	v_fma_f32 v119, -s6, v30, v119
	v_fma_f32 v181, -s7, v116, v181
	v_fma_f32 v180, -s8, v26, v180
	v_fma_f32 v118, -s9, v114, v118
	s_nop 0
	s_nop 0
	v_readlane_b32 s6, v78, s43
	v_readlane_b32 s7, v28, s43
	v_readlane_b32 s8, v74, s43
	v_readlane_b32 s9, v82, s27
	v_fma_f32 v119, -s6, v22, v119
	v_fma_f32 v181, -s7, v110, v181
	v_fma_f32 v180, -s8, v16, v180
	v_fma_f32 v118, -s9, v104, v118
	s_nop 0
	s_nop 0
	v_readlane_b32 s6, v78, s27
	v_readlane_b32 s7, v28, s27
	v_readlane_b32 s8, v74, s27
	v_readlane_b32 s9, v14, s43
	v_fma_f32 v119, -s6, v12, v119
	v_fma_f32 v181, -s7, v96, v181
	v_fma_f32 v180, -s8, v10, v180
	v_fma_f32 v118, -s9, v94, v118
	s_nop 0
	s_nop 0
	v_readlane_b32 s6, v70, s43
	v_readlane_b32 s7, v66, s43
	v_readlane_b32 s8, v62, s43
	v_readlane_b32 s9, v14, s27
	v_fma_f32 v119, -s6, v8, v119
	v_fma_f32 v181, -s7, v92, v181
	v_fma_f32 v180, -s8, v4, v180
	v_fma_f32 v118, -s9, v90, v118
	s_nop 0
	s_nop 0
	v_readlane_b32 s6, v70, s27
	s_nop 1
	v_fma_f32 v119, -s6, v91, v119
	s_nop 0
	s_nop 0
	v_readlane_b32 s6, v66, s27
	s_nop 1
	v_fma_f32 v119, -s6, v88, v119
	s_nop 0
	s_nop 0
	v_readlane_b32 s6, v62, s27
	s_nop 1
	v_fma_f32 v119, -s6, v89, v119
	s_nop 0
	v_pk_add_f32 v[118:119], v[180:181], v[118:119]
	v_mov_b32_e32 v181, v123
	v_mov_b32_e32 v180, v123
	v_pk_add_f32 v[118:119], v[118:119], v[118:119] op_sel:[0,1] op_sel_hi:[1,0]
	s_nop 0
	s_nop 0
	v_readlane_b32 s6, v6, s67
	v_readlane_b32 s7, v142, s67
	v_readlane_b32 s8, v24, s67
	v_readlane_b32 s9, v84, s67
	v_fma_f32 v33, -s6, v118, v33
	v_fma_f32 v181, -s7, v30, v181
	v_fma_f32 v180, -s8, v116, v180
	v_fma_f32 v32, -s9, v26, v32
	v_mov_b32_e32 v119, v30
	s_nop 0
	v_readlane_b32 s6, v82, s42
	v_readlane_b32 s7, v78, s42
	v_readlane_b32 s8, v28, s42
	v_readlane_b32 s9, v74, s42
	v_fma_f32 v33, -s6, v114, v33
	v_fma_f32 v181, -s7, v22, v181
	v_fma_f32 v180, -s8, v110, v180
	v_fma_f32 v32, -s9, v16, v32
	s_nop 0
	s_nop 0
	v_readlane_b32 s6, v82, s67
	v_readlane_b32 s7, v78, s67
	v_readlane_b32 s8, v28, s67
	v_readlane_b32 s9, v74, s67
	v_fma_f32 v33, -s6, v104, v33
	v_fma_f32 v181, -s7, v12, v181
	v_fma_f32 v180, -s8, v96, v180
	v_fma_f32 v32, -s9, v10, v32
	s_nop 0
	s_nop 0
	v_readlane_b32 s6, v14, s42
	v_readlane_b32 s7, v70, s42
	v_readlane_b32 s8, v66, s42
	v_readlane_b32 s9, v62, s42
	v_fma_f32 v33, -s6, v94, v33
	v_fma_f32 v181, -s7, v8, v181
	v_fma_f32 v180, -s8, v92, v180
	v_fma_f32 v32, -s9, v4, v32
	s_nop 0
	s_nop 0
	v_readlane_b32 s6, v14, s67
	v_readlane_b32 s7, v70, s67
	v_readlane_b32 s8, v66, s67
	v_readlane_b32 s9, v62, s67
	v_fma_f32 v33, -s6, v90, v33
	v_fma_f32 v181, -s7, v91, v181
	v_fma_f32 v180, -s8, v88, v180
	v_fma_f32 v32, -s9, v89, v32
	s_nop 0
	v_pk_add_f32 v[32:33], v[180:181], v[32:33]
	v_mov_b32_e32 v181, v123
	v_mov_b32_e32 v180, v123
	v_pk_add_f32 v[32:33], v[32:33], v[32:33] op_sel:[0,1] op_sel_hi:[1,0]
	s_nop 0
	s_nop 0
	v_readlane_b32 s6, v84, s46
	v_readlane_b32 s7, v6, s2
	v_readlane_b32 s8, v142, s2
	v_readlane_b32 s9, v24, s2
	v_fma_f32 v129, -s6, v32, v129
	v_fma_f32 v181, -s7, v118, v181
	v_fma_f32 v180, -s8, v30, v180
	v_fma_f32 v128, -s9, v116, v128
	s_nop 0
	s_nop 0
	v_readlane_b32 s6, v84, s2
	v_readlane_b32 s7, v82, s46
	v_readlane_b32 s8, v78, s46
	v_readlane_b32 s9, v28, s46
	v_fma_f32 v129, -s6, v26, v129
	v_fma_f32 v181, -s7, v114, v181
	v_fma_f32 v180, -s8, v22, v180
	v_fma_f32 v128, -s9, v110, v128
	s_nop 0
	s_nop 0
	v_readlane_b32 s6, v74, s46
	v_readlane_b32 s7, v82, s2
	v_readlane_b32 s8, v78, s2
	v_readlane_b32 s9, v28, s2
	v_fma_f32 v129, -s6, v16, v129
	v_fma_f32 v181, -s7, v104, v181
	v_fma_f32 v180, -s8, v12, v180
	v_fma_f32 v128, -s9, v96, v128
	s_nop 0
	s_nop 0
	v_readlane_b32 s6, v74, s2
	v_readlane_b32 s7, v14, s46
	v_readlane_b32 s8, v70, s46
	v_readlane_b32 s9, v66, s46
	v_fma_f32 v129, -s6, v10, v129
	v_fma_f32 v181, -s7, v94, v181
	v_fma_f32 v180, -s8, v8, v180
	v_fma_f32 v128, -s9, v92, v128
	s_nop 0
	s_nop 0
	v_readlane_b32 s6, v62, s46
	v_readlane_b32 s7, v14, s2
	v_readlane_b32 s8, v70, s2
	v_readlane_b32 s9, v66, s2
	v_fma_f32 v129, -s6, v4, v129
	v_fma_f32 v181, -s7, v90, v181
	v_fma_f32 v180, -s8, v91, v180
	v_fma_f32 v128, -s9, v88, v128
	s_nop 0
	s_nop 0
	v_readlane_b32 s6, v62, s2
	s_nop 1
	v_fma_f32 v129, -s6, v89, v129
	s_nop 0
	v_pk_add_f32 v[128:129], v[180:181], v[128:129]
	v_mov_b32_e32 v181, v123
	v_mov_b32_e32 v180, v123
	v_pk_add_f32 v[128:129], v[128:129], v[128:129] op_sel:[0,1] op_sel_hi:[1,0]
	s_nop 0
	s_nop 0
	v_readlane_b32 s6, v24, s37
	v_readlane_b32 s7, v84, s37
	v_readlane_b32 s8, v6, s18
	v_readlane_b32 s9, v142, s18
	v_fma_f32 v65, -s6, v128, v65
	v_fma_f32 v181, -s7, v32, v181
	v_fma_f32 v180, -s8, v118, v180
	v_fma_f32 v64, -s9, v30, v64
	v_mov_b32_e32 v129, v32
	s_nop 0
	v_readlane_b32 s6, v24, s18
	v_readlane_b32 s7, v84, s18
	v_readlane_b32 s8, v82, s37
	v_readlane_b32 s9, v78, s37
	v_fma_f32 v65, -s6, v116, v65
	v_fma_f32 v181, -s7, v26, v181
	v_fma_f32 v180, -s8, v114, v180
	v_fma_f32 v64, -s9, v22, v64
	s_nop 0
	s_nop 0
	v_readlane_b32 s6, v28, s37
	v_readlane_b32 s7, v74, s37
	v_readlane_b32 s8, v82, s18
	v_readlane_b32 s9, v78, s18
	v_fma_f32 v65, -s6, v110, v65
	v_fma_f32 v181, -s7, v16, v181
	v_fma_f32 v180, -s8, v104, v180
	v_fma_f32 v64, -s9, v12, v64
	s_nop 0
	s_nop 0
	v_readlane_b32 s6, v28, s18
	v_readlane_b32 s7, v74, s18
	v_readlane_b32 s8, v14, s37
	v_readlane_b32 s9, v70, s37
	v_fma_f32 v65, -s6, v96, v65
	v_fma_f32 v181, -s7, v10, v181
	v_fma_f32 v180, -s8, v94, v180
	v_fma_f32 v64, -s9, v8, v64
	s_nop 0
	s_nop 0
	v_readlane_b32 s6, v66, s37
	v_readlane_b32 s7, v62, s37
	v_readlane_b32 s8, v14, s18
	v_readlane_b32 s9, v70, s18
	v_fma_f32 v65, -s6, v92, v65
	v_fma_f32 v181, -s7, v4, v181
	v_fma_f32 v180, -s8, v90, v180
	v_fma_f32 v64, -s9, v91, v64
	s_nop 0
	s_nop 0
	v_readlane_b32 s6, v66, s18
	s_nop 1
	v_fma_f32 v65, -s6, v88, v65
	s_nop 0
	s_nop 0
	v_readlane_b32 s6, v62, s18
	s_nop 1
	v_fma_f32 v65, -s6, v89, v65
	s_nop 0
	v_pk_add_f32 v[64:65], v[180:181], v[64:65]
	v_mov_b32_e32 v181, v123
	v_mov_b32_e32 v180, v123
	v_pk_add_f32 v[64:65], v[64:65], v[64:65] op_sel:[0,1] op_sel_hi:[1,0]
	s_nop 0
	s_nop 0
	v_readlane_b32 s6, v142, s40
	v_readlane_b32 s7, v24, s40
	v_readlane_b32 s8, v84, s40
	v_readlane_b32 s9, v6, s19
	v_fma_f32 v131, -s6, v64, v131
	v_fma_f32 v181, -s7, v128, v181
	v_fma_f32 v180, -s8, v32, v180
	v_fma_f32 v130, -s9, v118, v130
	s_nop 0
	s_nop 0
	v_readlane_b32 s6, v142, s19
	v_readlane_b32 s7, v24, s19
	v_readlane_b32 s8, v84, s19
	v_readlane_b32 s9, v82, s40
	v_fma_f32 v131, -s6, v30, v131
	v_fma_f32 v181, -s7, v116, v181
	v_fma_f32 v180, -s8, v26, v180
	v_fma_f32 v130, -s9, v114, v130
	s_nop 0
	s_nop 0
	v_readlane_b32 s6, v78, s40
	v_readlane_b32 s7, v28, s40
	v_readlane_b32 s8, v74, s40
	v_readlane_b32 s9, v82, s19
	v_fma_f32 v131, -s6, v22, v131
	v_fma_f32 v181, -s7, v110, v181
	v_fma_f32 v180, -s8, v16, v180
	v_fma_f32 v130, -s9, v104, v130
	s_nop 0
	s_nop 0
	v_readlane_b32 s6, v78, s19
	v_readlane_b32 s7, v28, s19
	v_readlane_b32 s8, v74, s19
	v_readlane_b32 s9, v14, s40
	v_fma_f32 v131, -s6, v12, v131
	v_fma_f32 v181, -s7, v96, v181
	v_fma_f32 v180, -s8, v10, v180
	v_fma_f32 v130, -s9, v94, v130
	s_nop 0
	s_nop 0
	v_readlane_b32 s6, v70, s40
	v_readlane_b32 s7, v66, s40
	v_readlane_b32 s8, v62, s40
	v_readlane_b32 s9, v14, s19
	v_fma_f32 v131, -s6, v8, v131
	v_fma_f32 v181, -s7, v92, v181
	v_fma_f32 v180, -s8, v4, v180
	v_fma_f32 v130, -s9, v90, v130
	s_nop 0
	s_nop 0
	v_readlane_b32 s6, v70, s19
	s_nop 1
	v_fma_f32 v131, -s6, v91, v131
	s_nop 0
	s_nop 0
	v_readlane_b32 s6, v66, s19
	s_nop 1
	v_fma_f32 v131, -s6, v88, v131
	s_nop 0
	s_nop 0
	v_readlane_b32 s6, v62, s19
	s_nop 1
	v_fma_f32 v131, -s6, v89, v131
	s_nop 0
	v_pk_add_f32 v[130:131], v[180:181], v[130:131]
	v_mov_b32_e32 v181, v123
	v_mov_b32_e32 v180, v123
	v_pk_add_f32 v[130:131], v[130:131], v[130:131] op_sel:[0,1] op_sel_hi:[1,0]
	s_nop 0
	s_nop 0
	v_readlane_b32 s6, v6, s44
	v_readlane_b32 s7, v142, s44
	v_readlane_b32 s8, v24, s44
	v_readlane_b32 s9, v84, s44
	v_fma_f32 v69, -s6, v130, v69
	v_fma_f32 v181, -s7, v64, v181
	v_fma_f32 v180, -s8, v128, v180
	v_fma_f32 v68, -s9, v32, v68
	v_mov_b32_e32 v131, v64
	s_nop 0
	v_readlane_b32 s6, v6, s68
	v_readlane_b32 s7, v142, s68
	v_readlane_b32 s8, v24, s68
	v_readlane_b32 s9, v84, s68
	v_fma_f32 v69, -s6, v118, v69
	v_fma_f32 v181, -s7, v30, v181
	v_fma_f32 v180, -s8, v116, v180
	v_fma_f32 v68, -s9, v26, v68
	s_nop 0
	s_nop 0
	v_readlane_b32 s6, v82, s44
	v_readlane_b32 s7, v78, s44
	v_readlane_b32 s8, v28, s44
	v_readlane_b32 s9, v74, s44
	v_fma_f32 v69, -s6, v114, v69
	v_fma_f32 v181, -s7, v22, v181
	v_fma_f32 v180, -s8, v110, v180
	v_fma_f32 v68, -s9, v16, v68
	s_nop 0
	s_nop 0
	v_readlane_b32 s6, v82, s68
	v_readlane_b32 s7, v78, s68
	v_readlane_b32 s8, v28, s68
	v_readlane_b32 s9, v74, s68
	v_fma_f32 v69, -s6, v104, v69
	v_fma_f32 v181, -s7, v12, v181
	v_fma_f32 v180, -s8, v96, v180
	v_fma_f32 v68, -s9, v10, v68
	s_nop 0
	s_nop 0
	v_readlane_b32 s6, v14, s44
	v_readlane_b32 s7, v70, s44
	v_readlane_b32 s8, v66, s44
	v_readlane_b32 s9, v62, s44
	v_fma_f32 v69, -s6, v94, v69
	v_fma_f32 v181, -s7, v8, v181
	v_fma_f32 v180, -s8, v92, v180
	v_fma_f32 v68, -s9, v4, v68
	s_nop 0
	s_nop 0
	v_readlane_b32 s6, v14, s68
	v_readlane_b32 s7, v70, s68
	v_readlane_b32 s8, v66, s68
	v_readlane_b32 s9, v62, s68
	v_fma_f32 v69, -s6, v90, v69
	v_fma_f32 v181, -s7, v91, v181
	v_fma_f32 v180, -s8, v88, v180
	v_fma_f32 v68, -s9, v89, v68
	s_nop 0
	v_pk_add_f32 v[68:69], v[180:181], v[68:69]
	v_mov_b32_e32 v181, v123
	v_mov_b32_e32 v180, v123
	v_pk_add_f32 v[68:69], v[68:69], v[68:69] op_sel:[0,1] op_sel_hi:[1,0]
	s_nop 0
	s_nop 0
	v_readlane_b32 s6, v140, s3
	v_readlane_b32 s7, v6, s35
	v_readlane_b32 s8, v142, s35
	v_readlane_b32 s9, v24, s35
	v_fma_f32 v133, -s6, v68, v133
	v_fma_f32 v181, -s7, v130, v181
	v_fma_f32 v180, -s8, v64, v180
	v_fma_f32 v132, -s9, v128, v132
	s_nop 0
	s_nop 0
	v_readlane_b32 s6, v84, s35
	v_readlane_b32 s7, v6, s3
	v_readlane_b32 s8, v142, s3
	v_readlane_b32 s9, v24, s3
	v_fma_f32 v133, -s6, v32, v133
	v_fma_f32 v181, -s7, v118, v181
	v_fma_f32 v180, -s8, v30, v180
	v_fma_f32 v132, -s9, v116, v132
	s_nop 0
	s_nop 0
	v_readlane_b32 s6, v84, s3
	v_readlane_b32 s7, v82, s35
	v_readlane_b32 s8, v78, s35
	v_readlane_b32 s9, v28, s35
	v_fma_f32 v133, -s6, v26, v133
	v_fma_f32 v181, -s7, v114, v181
	v_fma_f32 v180, -s8, v22, v180
	v_fma_f32 v132, -s9, v110, v132
	s_nop 0
	s_nop 0
	v_readlane_b32 s6, v74, s35
	v_readlane_b32 s7, v82, s3
	v_readlane_b32 s8, v78, s3
	v_readlane_b32 s9, v28, s3
	v_fma_f32 v133, -s6, v16, v133
	v_fma_f32 v181, -s7, v104, v181
	v_fma_f32 v180, -s8, v12, v180
	v_fma_f32 v132, -s9, v96, v132
	s_nop 0
	s_nop 0
	v_readlane_b32 s6, v74, s3
	v_readlane_b32 s7, v14, s35
	v_readlane_b32 s8, v70, s35
	v_readlane_b32 s9, v66, s35
	v_fma_f32 v133, -s6, v10, v133
	v_fma_f32 v181, -s7, v94, v181
	v_fma_f32 v180, -s8, v8, v180
	v_fma_f32 v132, -s9, v92, v132
	s_nop 0
	s_nop 0
	v_readlane_b32 s6, v62, s35
	v_readlane_b32 s7, v14, s3
	v_readlane_b32 s8, v70, s3
	v_readlane_b32 s9, v66, s3
	v_fma_f32 v133, -s6, v4, v133
	v_fma_f32 v181, -s7, v90, v181
	v_fma_f32 v180, -s8, v91, v180
	v_fma_f32 v132, -s9, v88, v132
	s_nop 0
	s_nop 0
	v_readlane_b32 s6, v62, s3
	s_nop 1
	v_fma_f32 v133, -s6, v89, v133
	s_nop 0
	v_pk_add_f32 v[132:133], v[180:181], v[132:133]
	v_mov_b32_e32 v181, v123
	v_mov_b32_e32 v180, v123
	v_pk_add_f32 v[132:133], v[132:133], v[132:133] op_sel:[0,1] op_sel_hi:[1,0]
	s_nop 0
	s_nop 0
	v_readlane_b32 s6, v144, s16
	v_readlane_b32 s7, v140, s16
	v_readlane_b32 s8, v6, s30
	v_readlane_b32 s9, v142, s30
	v_fma_f32 v73, -s6, v132, v73
	v_fma_f32 v181, -s7, v68, v181
	v_fma_f32 v180, -s8, v130, v180
	v_fma_f32 v72, -s9, v64, v72
	v_mov_b32_e32 v133, v68
	s_nop 0
	v_readlane_b32 s6, v24, s30
	v_readlane_b32 s7, v84, s30
	v_readlane_b32 s8, v6, s16
	v_readlane_b32 s9, v142, s16
	v_fma_f32 v73, -s6, v128, v73
	v_fma_f32 v181, -s7, v32, v181
	v_fma_f32 v180, -s8, v118, v180
	v_fma_f32 v72, -s9, v30, v72
	s_nop 0
	s_nop 0
	v_readlane_b32 s6, v24, s16
	v_readlane_b32 s7, v84, s16
	v_readlane_b32 s8, v82, s30
	v_readlane_b32 s9, v78, s30
	v_fma_f32 v73, -s6, v116, v73
	v_fma_f32 v181, -s7, v26, v181
	v_fma_f32 v180, -s8, v114, v180
	v_fma_f32 v72, -s9, v22, v72
	s_nop 0
	s_nop 0
	v_readlane_b32 s6, v28, s30
	v_readlane_b32 s7, v74, s30
	v_readlane_b32 s8, v82, s16
	v_readlane_b32 s9, v78, s16
	v_fma_f32 v73, -s6, v110, v73
	v_fma_f32 v181, -s7, v16, v181
	v_fma_f32 v180, -s8, v104, v180
	v_fma_f32 v72, -s9, v12, v72
	s_nop 0
	s_nop 0
	v_readlane_b32 s6, v28, s16
	v_readlane_b32 s7, v74, s16
	v_readlane_b32 s8, v14, s30
	v_readlane_b32 s9, v70, s30
	v_fma_f32 v73, -s6, v96, v73
	v_fma_f32 v181, -s7, v10, v181
	v_fma_f32 v180, -s8, v94, v180
	v_fma_f32 v72, -s9, v8, v72
	s_nop 0
	s_nop 0
	v_readlane_b32 s6, v66, s30
	v_readlane_b32 s7, v62, s30
	v_readlane_b32 s8, v14, s16
	v_readlane_b32 s9, v70, s16
	v_fma_f32 v73, -s6, v92, v73
	v_fma_f32 v181, -s7, v4, v181
	v_fma_f32 v180, -s8, v90, v180
	v_fma_f32 v72, -s9, v91, v72
	s_nop 0
	s_nop 0
	v_readlane_b32 s6, v66, s16
	s_nop 1
	v_fma_f32 v73, -s6, v88, v73
	s_nop 0
	s_nop 0
	v_readlane_b32 s6, v62, s16
	s_nop 1
	v_fma_f32 v73, -s6, v89, v73
	s_nop 0
	v_pk_add_f32 v[72:73], v[180:181], v[72:73]
	v_mov_b32_e32 v181, v123
	v_mov_b32_e32 v180, v123
	v_pk_add_f32 v[72:73], v[72:73], v[72:73] op_sel:[0,1] op_sel_hi:[1,0]
	s_nop 0
	s_nop 0
	v_readlane_b32 s6, v146, s17
	v_readlane_b32 s7, v144, s17
	v_readlane_b32 s8, v140, s17
	v_readlane_b32 s9, v6, s36
	v_fma_f32 v135, -s6, v72, v135
	v_fma_f32 v181, -s7, v132, v181
	v_fma_f32 v180, -s8, v68, v180
	v_fma_f32 v134, -s9, v130, v134
	s_nop 0
	s_nop 0
	v_readlane_b32 s6, v142, s36
	v_readlane_b32 s7, v24, s36
	v_readlane_b32 s8, v84, s36
	v_readlane_b32 s9, v6, s17
	v_fma_f32 v135, -s6, v64, v135
	v_fma_f32 v181, -s7, v128, v181
	v_fma_f32 v180, -s8, v32, v180
	v_fma_f32 v134, -s9, v118, v134
	s_nop 0
	s_nop 0
	v_readlane_b32 s6, v142, s17
	v_readlane_b32 s7, v24, s17
	v_readlane_b32 s8, v84, s17
	v_readlane_b32 s9, v82, s36
	v_fma_f32 v135, -s6, v30, v135
	v_fma_f32 v181, -s7, v116, v181
	v_fma_f32 v180, -s8, v26, v180
	v_fma_f32 v134, -s9, v114, v134
	s_nop 0
	s_nop 0
	v_readlane_b32 s6, v78, s36
	v_readlane_b32 s7, v28, s36
	v_readlane_b32 s8, v74, s36
	v_readlane_b32 s9, v82, s17
	v_fma_f32 v135, -s6, v22, v135
	v_fma_f32 v181, -s7, v110, v181
	v_fma_f32 v180, -s8, v16, v180
	v_fma_f32 v134, -s9, v104, v134
	s_nop 0
	s_nop 0
	v_readlane_b32 s6, v78, s17
	v_readlane_b32 s7, v28, s17
	v_readlane_b32 s8, v74, s17
	v_readlane_b32 s9, v14, s36
	v_fma_f32 v135, -s6, v12, v135
	v_fma_f32 v181, -s7, v96, v181
	v_fma_f32 v180, -s8, v10, v180
	v_fma_f32 v134, -s9, v94, v134
	s_nop 0
	s_nop 0
	v_readlane_b32 s6, v70, s36
	v_readlane_b32 s7, v66, s36
	v_readlane_b32 s8, v62, s36
	v_readlane_b32 s9, v14, s17
	v_fma_f32 v135, -s6, v8, v135
	v_fma_f32 v181, -s7, v92, v181
	v_fma_f32 v180, -s8, v4, v180
	v_fma_f32 v134, -s9, v90, v134
	s_nop 0
	s_nop 0
	v_readlane_b32 s6, v70, s17
	s_nop 1
	v_fma_f32 v135, -s6, v91, v135
	s_nop 0
	s_nop 0
	v_readlane_b32 s6, v66, s17
	s_nop 1
	v_fma_f32 v135, -s6, v88, v135
	s_nop 0
	s_nop 0
	v_readlane_b32 s6, v62, s17
	s_nop 1
	v_fma_f32 v135, -s6, v89, v135
	s_nop 0
	v_pk_add_f32 v[134:135], v[180:181], v[134:135]
	v_mov_b32_e32 v181, v123
	v_mov_b32_e32 v180, v123
	v_pk_add_f32 v[134:135], v[134:135], v[134:135] op_sel:[0,1] op_sel_hi:[1,0]
	s_nop 0
	s_nop 0
	v_readlane_b32 s6, v2, s69
	v_readlane_b32 s7, v146, s69
	v_readlane_b32 s8, v144, s69
	v_readlane_b32 s9, v140, s69
	v_fma_f32 v77, -s6, v134, v77
	v_fma_f32 v181, -s7, v72, v181
	v_fma_f32 v180, -s8, v132, v180
	v_fma_f32 v76, -s9, v68, v76
	v_mov_b32_e32 v135, v72
	s_nop 0
	v_readlane_b32 s6, v6, s12
	v_readlane_b32 s7, v142, s12
	v_readlane_b32 s8, v24, s12
	v_readlane_b32 s9, v84, s12
	v_fma_f32 v77, -s6, v130, v77
	v_fma_f32 v181, -s7, v64, v181
	v_fma_f32 v180, -s8, v128, v180
	v_fma_f32 v76, -s9, v32, v76
	s_nop 0
	s_nop 0
	v_readlane_b32 s6, v6, s69
	v_readlane_b32 s7, v142, s69
	v_readlane_b32 s8, v24, s69
	v_readlane_b32 s9, v84, s69
	v_fma_f32 v77, -s6, v118, v77
	v_fma_f32 v181, -s7, v30, v181
	v_fma_f32 v180, -s8, v116, v180
	v_fma_f32 v76, -s9, v26, v76
	s_nop 0
	s_nop 0
	v_readlane_b32 s6, v82, s12
	v_readlane_b32 s7, v78, s12
	v_readlane_b32 s8, v28, s12
	v_readlane_b32 s9, v74, s12
	v_fma_f32 v77, -s6, v114, v77
	v_fma_f32 v181, -s7, v22, v181
	v_fma_f32 v180, -s8, v110, v180
	v_fma_f32 v76, -s9, v16, v76
	s_nop 0
	s_nop 0
	v_readlane_b32 s6, v82, s69
	v_readlane_b32 s7, v78, s69
	v_readlane_b32 s8, v28, s69
	v_readlane_b32 s9, v74, s69
	v_fma_f32 v77, -s6, v104, v77
	v_fma_f32 v181, -s7, v12, v181
	v_fma_f32 v180, -s8, v96, v180
	v_fma_f32 v76, -s9, v10, v76
	s_nop 0
	s_nop 0
	v_readlane_b32 s6, v14, s12
	v_readlane_b32 s7, v70, s12
	v_readlane_b32 s8, v66, s12
	v_readlane_b32 s9, v62, s12
	v_fma_f32 v77, -s6, v94, v77
	v_fma_f32 v181, -s7, v8, v181
	v_fma_f32 v180, -s8, v92, v180
	v_fma_f32 v76, -s9, v4, v76
	s_nop 0
	s_nop 0
	v_readlane_b32 s6, v14, s69
	v_readlane_b32 s7, v70, s69
	v_readlane_b32 s8, v66, s69
	v_readlane_b32 s9, v62, s69
	v_fma_f32 v77, -s6, v90, v77
	v_fma_f32 v181, -s7, v91, v181
	v_fma_f32 v180, -s8, v88, v180
	v_fma_f32 v76, -s9, v89, v76
	s_nop 0
	v_pk_add_f32 v[76:77], v[180:181], v[76:77]
	v_mov_b32_e32 v181, v123
	v_mov_b32_e32 v180, v123
	v_pk_add_f32 v[76:77], v[76:77], v[76:77] op_sel:[0,1] op_sel_hi:[1,0]
	s_nop 0
	s_nop 0
	v_readlane_b32 s6, v140, s15
	v_readlane_b32 s7, v2, s23
	v_readlane_b32 s8, v146, s23
	v_readlane_b32 s9, v144, s23
	v_fma_f32 v137, -s6, v76, v137
	v_fma_f32 v181, -s7, v134, v181
	v_fma_f32 v180, -s8, v72, v180
	v_fma_f32 v136, -s9, v132, v136
	s_nop 0
	s_nop 0
	v_readlane_b32 s6, v140, s23
	v_readlane_b32 s7, v6, s15
	v_readlane_b32 s8, v142, s15
	v_readlane_b32 s9, v24, s15
	v_fma_f32 v137, -s6, v68, v137
	v_fma_f32 v181, -s7, v130, v181
	v_fma_f32 v180, -s8, v64, v180
	v_fma_f32 v136, -s9, v128, v136
	s_nop 0
	s_nop 0
	v_readlane_b32 s6, v84, s15
	v_readlane_b32 s7, v6, s23
	v_readlane_b32 s8, v142, s23
	v_readlane_b32 s9, v24, s23
	v_fma_f32 v137, -s6, v32, v137
	v_fma_f32 v181, -s7, v118, v181
	v_fma_f32 v180, -s8, v30, v180
	v_fma_f32 v136, -s9, v116, v136
	s_nop 0
	s_nop 0
	v_readlane_b32 s6, v84, s23
	v_readlane_b32 s7, v82, s15
	v_readlane_b32 s8, v78, s15
	v_readlane_b32 s9, v28, s15
	v_fma_f32 v137, -s6, v26, v137
	v_fma_f32 v181, -s7, v114, v181
	v_fma_f32 v180, -s8, v22, v180
	v_fma_f32 v136, -s9, v110, v136
	s_nop 0
	s_nop 0
	v_readlane_b32 s6, v74, s15
	v_readlane_b32 s7, v82, s23
	v_readlane_b32 s8, v78, s23
	v_readlane_b32 s9, v28, s23
	v_fma_f32 v137, -s6, v16, v137
	v_fma_f32 v181, -s7, v104, v181
	v_fma_f32 v180, -s8, v12, v180
	v_fma_f32 v136, -s9, v96, v136
	s_nop 0
	s_nop 0
	v_readlane_b32 s6, v74, s23
	v_readlane_b32 s7, v14, s15
	v_readlane_b32 s8, v70, s15
	v_readlane_b32 s9, v66, s15
	v_fma_f32 v137, -s6, v10, v137
	v_fma_f32 v181, -s7, v94, v181
	v_fma_f32 v180, -s8, v8, v180
	v_fma_f32 v136, -s9, v92, v136
	s_nop 0
	s_nop 0
	v_readlane_b32 s6, v62, s15
	v_readlane_b32 s7, v14, s23
	v_readlane_b32 s8, v70, s23
	v_readlane_b32 s9, v66, s23
	v_fma_f32 v137, -s6, v4, v137
	v_fma_f32 v181, -s7, v90, v181
	v_fma_f32 v180, -s8, v91, v180
	v_fma_f32 v136, -s9, v88, v136
	s_nop 0
	s_nop 0
	v_readlane_b32 s6, v62, s23
	s_nop 1
	v_fma_f32 v137, -s6, v89, v137
	s_nop 0
	v_pk_add_f32 v[136:137], v[180:181], v[136:137]
	v_mov_b32_e32 v181, v123
	v_mov_b32_e32 v180, v123
	v_pk_add_f32 v[136:137], v[136:137], v[136:137] op_sel:[0,1] op_sel_hi:[1,0]
	s_nop 0
	s_nop 0
	v_readlane_b32 s6, v144, s26
	v_readlane_b32 s7, v140, s26
	v_readlane_b32 s8, v2, s10
	v_readlane_b32 s9, v146, s10
	v_fma_f32 v81, -s6, v136, v81
	v_fma_f32 v181, -s7, v76, v181
	v_fma_f32 v180, -s8, v134, v180
	v_fma_f32 v80, -s9, v72, v80
	v_mov_b32_e32 v137, v76
	s_nop 0
	v_readlane_b32 s6, v144, s10
	v_readlane_b32 s7, v140, s10
	v_readlane_b32 s8, v6, s26
	v_readlane_b32 s9, v142, s26
	v_fma_f32 v81, -s6, v132, v81
	v_fma_f32 v181, -s7, v68, v181
	v_fma_f32 v180, -s8, v130, v180
	v_fma_f32 v80, -s9, v64, v80
	s_nop 0
	s_nop 0
	v_readlane_b32 s6, v24, s26
	v_readlane_b32 s7, v84, s26
	v_readlane_b32 s8, v6, s10
	v_readlane_b32 s9, v142, s10
	v_fma_f32 v81, -s6, v128, v81
	v_fma_f32 v181, -s7, v32, v181
	v_fma_f32 v180, -s8, v118, v180
	v_fma_f32 v80, -s9, v30, v80
	s_nop 0
	s_nop 0
	v_readlane_b32 s6, v24, s10
	v_readlane_b32 s7, v84, s10
	v_readlane_b32 s8, v82, s26
	v_readlane_b32 s9, v78, s26
	v_fma_f32 v81, -s6, v116, v81
	v_fma_f32 v181, -s7, v26, v181
	v_fma_f32 v180, -s8, v114, v180
	v_fma_f32 v80, -s9, v22, v80
	s_nop 0
	s_nop 0
	v_readlane_b32 s6, v28, s26
	v_readlane_b32 s7, v74, s26
	v_readlane_b32 s8, v82, s10
	v_readlane_b32 s9, v78, s10
	v_fma_f32 v81, -s6, v110, v81
	v_fma_f32 v181, -s7, v16, v181
	v_fma_f32 v180, -s8, v104, v180
	v_fma_f32 v80, -s9, v12, v80
	s_nop 0
	s_nop 0
	v_readlane_b32 s6, v28, s10
	v_readlane_b32 s7, v74, s10
	v_readlane_b32 s8, v14, s26
	v_readlane_b32 s9, v70, s26
	v_fma_f32 v81, -s6, v96, v81
	v_fma_f32 v181, -s7, v10, v181
	v_fma_f32 v180, -s8, v94, v180
	v_fma_f32 v80, -s9, v8, v80
	s_nop 0
	s_nop 0
	v_readlane_b32 s6, v66, s26
	v_readlane_b32 s7, v62, s26
	v_readlane_b32 s8, v14, s10
	v_readlane_b32 s9, v70, s10
	v_fma_f32 v81, -s6, v92, v81
	v_fma_f32 v181, -s7, v4, v181
	v_fma_f32 v180, -s8, v90, v180
	v_fma_f32 v80, -s9, v91, v80
	s_nop 0
	s_nop 0
	v_readlane_b32 s6, v66, s10
	s_nop 1
	v_fma_f32 v81, -s6, v88, v81
	s_nop 0
	s_nop 0
	v_readlane_b32 s6, v62, s10
	s_nop 1
	v_fma_f32 v81, -s6, v89, v81
	s_nop 0
	v_pk_add_f32 v[80:81], v[180:181], v[80:81]
	v_mov_b32_e32 v181, v123
	v_mov_b32_e32 v180, v123
	v_pk_add_f32 v[80:81], v[80:81], v[80:81] op_sel:[0,1] op_sel_hi:[1,0]
	s_nop 0
	s_nop 0
	v_readlane_b32 s6, v146, s13
	v_readlane_b32 s7, v144, s13
	v_readlane_b32 s8, v140, s13
	v_readlane_b32 s9, v2, s31
	v_fma_f32 v139, -s6, v80, v139
	v_fma_f32 v181, -s7, v136, v181
	v_fma_f32 v180, -s8, v76, v180
	v_fma_f32 v138, -s9, v134, v138
	v_mov_b32_e32 v2, v123
	s_nop 0
	v_readlane_b32 s6, v146, s31
	v_readlane_b32 s7, v144, s31
	v_readlane_b32 s8, v140, s31
	v_readlane_b32 s9, v6, s13
	v_fma_f32 v139, -s6, v72, v139
	v_fma_f32 v181, -s7, v132, v181
	v_fma_f32 v180, -s8, v68, v180
	v_fma_f32 v138, -s9, v130, v138
	v_mov_b32_e32 v140, v123
	s_nop 0
	v_readlane_b32 s6, v142, s13
	v_readlane_b32 s7, v24, s13
	v_readlane_b32 s8, v84, s13
	v_readlane_b32 s9, v6, s31
	v_fma_f32 v139, -s6, v64, v139
	v_fma_f32 v181, -s7, v128, v181
	v_fma_f32 v180, -s8, v32, v180
	v_fma_f32 v138, -s9, v118, v138
	v_mov_b32_e32 v144, v123
	s_nop 0
	v_readlane_b32 s6, v142, s31
	v_readlane_b32 s7, v24, s31
	v_readlane_b32 s8, v84, s31
	v_readlane_b32 s9, v82, s13
	v_fma_f32 v139, -s6, v30, v139
	v_fma_f32 v181, -s7, v116, v181
	v_fma_f32 v180, -s8, v26, v180
	v_fma_f32 v138, -s9, v114, v138
	v_mov_b32_e32 v142, v123
	s_nop 0
	v_readlane_b32 s6, v78, s13
	v_readlane_b32 s7, v28, s13
	v_readlane_b32 s8, v74, s13
	v_readlane_b32 s9, v82, s31
	v_fma_f32 v139, -s6, v22, v139
	v_fma_f32 v181, -s7, v110, v181
	v_fma_f32 v180, -s8, v16, v180
	v_fma_f32 v138, -s9, v104, v138
	v_mov_b32_e32 v146, v123
	s_nop 0
	v_readlane_b32 s6, v78, s31
	v_readlane_b32 s7, v28, s31
	v_readlane_b32 s8, v74, s31
	v_readlane_b32 s9, v14, s13
	v_fma_f32 v139, -s6, v12, v139
	v_fma_f32 v181, -s7, v96, v181
	v_fma_f32 v180, -s8, v10, v180
	v_fma_f32 v138, -s9, v94, v138
	v_mov_b32_e32 v84, v123
	s_nop 0
	v_readlane_b32 s6, v70, s13
	v_readlane_b32 s7, v66, s13
	v_readlane_b32 s8, v62, s13
	v_readlane_b32 s9, v14, s31
	v_fma_f32 v139, -s6, v8, v139
	v_fma_f32 v181, -s7, v92, v181
	v_fma_f32 v180, -s8, v4, v180
	v_fma_f32 v138, -s9, v90, v138
	v_mov_b32_e32 v82, v123
	s_nop 0
	v_readlane_b32 s6, v70, s31
	s_nop 1
	v_fma_f32 v139, -s6, v91, v139
	v_mov_b32_e32 v78, v123
	s_nop 0
	v_readlane_b32 s6, v66, s31
	s_nop 1
	v_fma_f32 v139, -s6, v88, v139
	v_mov_b32_e32 v74, v123
	s_nop 0
	v_readlane_b32 s6, v62, s31
	s_nop 1
	v_fma_f32 v139, -s6, v89, v139
	v_mov_b32_e32 v70, v123
	v_pk_add_f32 v[138:139], v[180:181], v[138:139]
	v_mov_b32_e32 v181, v123
	v_mov_b32_e32 v180, v123
	v_pk_add_f32 v[138:139], v[138:139], v[138:139] op_sel:[0,1] op_sel_hi:[1,0]
	v_mov_b32_e32 v66, v123
	v_readlane_b32 s98, v251, 55
	s_nop 3
	s_mul_i32 s98, s98, 9
	s_add_i32 s98, s98, 0x4000
	v_mbcnt_lo_u32_b32 v255, -1, 0
	v_mbcnt_hi_u32_b32 v255, -1, v255
	v_and_b32_e32 v253, 31, v255
	v_lshrrev_b32_e32 v254, 5, v255
	v_cmp_lt_u32_e64 s[96:97], 31, v255
	v_mul_u32_u24_e32 v248, 0x210, v254
	v_lshl_add_u32 v248, v253, 2, v248
	v_add_u32_e32 v248, s98, v248
	v_mul_u32_u24_e32 v249, 0x84, v253
	v_add_u32_e32 v249, s98, v249
	v_lshlrev_b32_e32 v255, 2, v253
	v_add_u32_e32 v255, 0x1080, v255
	v_add_u32_e32 v255, s98, v255
	ds_write_b32 v255, v123
	s_add_i32 s98, s98, 0x1080
	v_mov_b32_e32 v253, s98
	s_nop 1
	v_cndmask_b32_e64 v249, v253, v249, s[96:97]
	v_mov_b32_e32 v244, v134
	v_mov_b32_e32 v245, v138
	s_nop 1
	v_permlane32_swap_b32_e32 v245, v244
	s_nop 1
	v_mfma_f32_32x32x2_f32 v[228:243], v244, v226, 0
	v_mov_b32_e32 v246, v72
	v_mov_b32_e32 v247, v80
	s_nop 1
	v_permlane32_swap_b32_e32 v247, v246
	s_nop 1
	v_mfma_f32_32x32x2_f32 v[228:243], v246, v225, v[228:243]
	v_mov_b32_e32 v244, v132
	v_mov_b32_e32 v245, v136
	s_nop 1
	v_permlane32_swap_b32_e32 v245, v244
	s_nop 1
	v_mfma_f32_32x32x2_f32 v[228:243], v244, v224, v[228:243]
	v_mov_b32_e32 v246, v68
	v_mov_b32_e32 v247, v76
	s_nop 1
	v_permlane32_swap_b32_e32 v247, v246
	s_nop 1
	v_mfma_f32_32x32x2_f32 v[228:243], v246, v223, v[228:243]
	v_mov_b32_e32 v244, v118
	v_mov_b32_e32 v245, v130
	s_nop 1
	v_permlane32_swap_b32_e32 v245, v244
	s_nop 1
	v_mfma_f32_32x32x2_f32 v[228:243], v244, v222, v[228:243]
	v_mov_b32_e32 v246, v30
	v_mov_b32_e32 v247, v64
	s_nop 1
	v_permlane32_swap_b32_e32 v247, v246
	s_nop 1
	v_mfma_f32_32x32x2_f32 v[228:243], v246, v221, v[228:243]
	v_mov_b32_e32 v244, v116
	v_mov_b32_e32 v245, v128
	s_nop 1
	v_permlane32_swap_b32_e32 v245, v244
	s_nop 1
	v_mfma_f32_32x32x2_f32 v[228:243], v244, v220, v[228:243]
	v_mov_b32_e32 v246, v26
	v_mov_b32_e32 v247, v32
	s_nop 1
	v_permlane32_swap_b32_e32 v247, v246
	s_nop 1
	v_mfma_f32_32x32x2_f32 v[228:243], v246, v219, v[228:243]
	v_mov_b32_e32 v244, v104
	v_mov_b32_e32 v245, v114
	s_nop 1
	v_permlane32_swap_b32_e32 v245, v244
	s_nop 1
	v_mfma_f32_32x32x2_f32 v[228:243], v244, v218, v[228:243]
	v_mov_b32_e32 v246, v12
	v_mov_b32_e32 v247, v22
	s_nop 1
	v_permlane32_swap_b32_e32 v247, v246
	s_nop 1
	v_mfma_f32_32x32x2_f32 v[228:243], v246, v217, v[228:243]
	v_mov_b32_e32 v244, v96
	v_mov_b32_e32 v245, v110
	s_nop 1
	v_permlane32_swap_b32_e32 v245, v244
	s_nop 1
	v_mfma_f32_32x32x2_f32 v[228:243], v244, v216, v[228:243]
	v_mov_b32_e32 v246, v10
	v_mov_b32_e32 v247, v16
	s_nop 1
	v_permlane32_swap_b32_e32 v247, v246
	s_nop 1
	v_mfma_f32_32x32x2_f32 v[228:243], v246, v215, v[228:243]
	v_mov_b32_e32 v244, v90
	v_mov_b32_e32 v245, v94
	s_nop 1
	v_permlane32_swap_b32_e32 v245, v244
	s_nop 1
	v_mfma_f32_32x32x2_f32 v[228:243], v244, v214, v[228:243]
	v_mov_b32_e32 v246, v91
	v_mov_b32_e32 v247, v8
	s_nop 1
	v_permlane32_swap_b32_e32 v247, v246
	s_nop 1
	v_mfma_f32_32x32x2_f32 v[228:243], v246, v213, v[228:243]
	v_mov_b32_e32 v244, v88
	v_mov_b32_e32 v245, v92
	s_nop 1
	v_permlane32_swap_b32_e32 v245, v244
	s_nop 1
	v_mfma_f32_32x32x2_f32 v[228:243], v244, v212, v[228:243]
	v_mov_b32_e32 v246, v89
	v_mov_b32_e32 v247, v4
	s_nop 1
	v_permlane32_swap_b32_e32 v247, v246
	s_nop 1
	v_mfma_f32_32x32x2_f32 v[228:243], v246, v211, v[228:243]
	s_nop 15
	s_nop 3
	ds_write_b32 v248, v228 offset:0
	ds_write_b32 v248, v229 offset:132
	ds_write_b32 v248, v230 offset:264
	ds_write_b32 v248, v231 offset:396
	ds_write_b32 v248, v232 offset:1056
	ds_write_b32 v248, v233 offset:1188
	ds_write_b32 v248, v234 offset:1320
	ds_write_b32 v248, v235 offset:1452
	ds_write_b32 v248, v236 offset:2112
	ds_write_b32 v248, v237 offset:2244
	ds_write_b32 v248, v238 offset:2376
	ds_write_b32 v248, v239 offset:2508
	ds_write_b32 v248, v240 offset:3168
	ds_write_b32 v248, v241 offset:3300
	ds_write_b32 v248, v242 offset:3432
	ds_write_b32 v248, v243 offset:3564
	s_waitcnt lgkmcnt(0)
	ds_read_b32 v246, v249 offset:124
	s_waitcnt lgkmcnt(0)
	v_sub_f32_e32 v153, v153, v246
	ds_read_b32 v247, v249 offset:120
	s_nop 0
	v_mov_b32_e32 v62, v123
	s_nop 0
	v_mov_b32_e32 v28, v123
	s_nop 0
	v_mov_b32_e32 v24, v123
	s_nop 0
	v_mov_b32_e32 v14, v123
	s_nop 0
	v_mov_b32_e32 v6, v123
	s_nop 0
	v_mov_b32_e32 v139, v80
	s_nop 0
	s_nop 0
	s_nop 0
	s_mov_b32 s20, 30
	v_pk_add_f32 v[152:153], v[180:181], v[152:153]
	v_mov_b32_e32 v181, v123
	v_mov_b32_e32 v180, v123
	v_pk_add_f32 v[152:153], v[152:153], v[152:153] op_sel:[0,1] op_sel_hi:[1,0]
	s_nop 0
	s_waitcnt lgkmcnt(0)
	v_sub_f32_e32 v141, v141, v247
	ds_read_b32 v246, v249 offset:116
	s_nop 0
	v_readlane_b32 s6, v209, s54
	s_nop 1
	v_fma_f32 v141, -s6, v152, v141
	s_nop 0
	s_nop 0
	s_nop 0
	s_nop 0
	s_nop 0
	s_nop 0
	s_nop 0
	s_nop 0
	s_nop 0
	s_nop 0
	s_nop 0
	s_nop 0
	s_nop 0
	s_nop 0
	s_mov_b32 s20, 29
	s_nop 0
	s_nop 1
	s_nop 0
	v_pk_add_f32 v[140:141], v[180:181], v[140:141]
	v_mov_b32_e32 v181, v123
	v_mov_b32_e32 v180, v123
	v_pk_add_f32 v[140:141], v[140:141], v[140:141] op_sel:[0,1] op_sel_hi:[1,0]
	s_nop 0
	s_waitcnt lgkmcnt(0)
	v_sub_f32_e32 v159, v159, v246
	ds_read_b32 v247, v249 offset:112
	s_nop 0
	v_readlane_b32 s6, v207, s55
	v_readlane_b32 s7, v209, s55
	s_nop 0
	v_fma_f32 v159, -s6, v140, v159
	v_fma_f32 v181, -s7, v152, v181
	v_mov_b32_e32 v141, v152
	s_nop 0
	s_nop 0
	s_nop 0
	s_nop 0
	s_nop 0
	s_nop 0
	s_nop 0
	s_nop 0
	s_nop 0
	s_nop 0
	s_nop 0
	s_nop 0
	s_nop 0
	s_mov_b32 s20, 28
	s_nop 0
	s_nop 1
	s_nop 0
	s_nop 0
	s_nop 1
	s_nop 0
	v_pk_add_f32 v[158:159], v[180:181], v[158:159]
	v_mov_b32_e32 v181, v123
	v_mov_b32_e32 v180, v123
	v_pk_add_f32 v[158:159], v[158:159], v[158:159] op_sel:[0,1] op_sel_hi:[1,0]
	s_nop 0
	s_waitcnt lgkmcnt(0)
	v_sub_f32_e32 v143, v143, v247
	ds_read_b32 v246, v249 offset:108
	s_nop 0
	v_readlane_b32 s6, v208, s56
	v_readlane_b32 s7, v207, s56
	v_readlane_b32 s8, v209, s56
	v_fma_f32 v143, -s6, v158, v143
	v_fma_f32 v181, -s7, v140, v181
	v_fma_f32 v180, -s8, v152, v180
	s_nop 0
	s_nop 0
	s_nop 0
	s_nop 0
	s_nop 0
	s_nop 0
	s_nop 0
	s_nop 0
	s_nop 0
	s_nop 0
	s_nop 0
	s_nop 0
	s_nop 0
	s_nop 0
	s_mov_b32 s20, 27
	s_nop 0
	s_nop 1
	s_nop 0
	s_nop 0
	s_nop 1
	s_nop 0
	s_nop 0
	s_nop 1
	s_nop 0
	v_pk_add_f32 v[142:143], v[180:181], v[142:143]
	v_mov_b32_e32 v181, v123
	v_mov_b32_e32 v180, v123
	v_pk_add_f32 v[142:143], v[142:143], v[142:143] op_sel:[0,1] op_sel_hi:[1,0]
	s_nop 0
	s_waitcnt lgkmcnt(0)
	v_sub_f32_e32 v167, v167, v246
	ds_read_b32 v247, v249 offset:104
	s_nop 0
	v_readlane_b32 s6, v205, s57
	v_readlane_b32 s7, v208, s57
	v_readlane_b32 s8, v207, s57
	v_readlane_b32 s9, v209, s57
	v_fma_f32 v167, -s6, v142, v167
	v_fma_f32 v181, -s7, v158, v181
	v_fma_f32 v180, -s8, v140, v180
	v_fma_f32 v166, -s9, v152, v166
	v_mov_b32_e32 v143, v158
	s_nop 0
	s_nop 0
	s_nop 0
	s_nop 0
	s_nop 0
	s_nop 0
	s_nop 0
	s_nop 0
	s_nop 0
	s_nop 0
	s_nop 0
	s_nop 0
	s_nop 0
	s_nop 0
	s_nop 0
	s_nop 0
	v_pk_add_f32 v[166:167], v[180:181], v[166:167]
	v_mov_b32_e32 v181, v123
	v_mov_b32_e32 v180, v123
	v_pk_add_f32 v[166:167], v[166:167], v[166:167] op_sel:[0,1] op_sel_hi:[1,0]
	s_nop 0
	s_waitcnt lgkmcnt(0)
	v_sub_f32_e32 v145, v145, v247
	ds_read_b32 v246, v249 offset:100
	s_nop 0
	v_readlane_b32 s6, v209, s53
	v_readlane_b32 s7, v205, s58
	v_readlane_b32 s8, v208, s58
	v_readlane_b32 s9, v207, s58
	v_fma_f32 v145, -s6, v166, v145
	v_fma_f32 v181, -s7, v142, v181
	v_fma_f32 v180, -s8, v158, v180
	v_fma_f32 v144, -s9, v140, v144
	s_nop 0
	s_nop 0
	v_readlane_b32 s6, v209, s58
	s_nop 1
	v_fma_f32 v145, -s6, v152, v145
	s_nop 0
	s_nop 0
	s_nop 0
	s_nop 0
	s_nop 0
	s_nop 0
	s_nop 0
	s_nop 0
	s_nop 0
	s_nop 0
	s_nop 0
	s_nop 0
	s_nop 0
	s_nop 0
	s_nop 0
	s_nop 0
	s_nop 1
	s_nop 0
	v_pk_add_f32 v[144:145], v[180:181], v[144:145]
	v_mov_b32_e32 v181, v123
	v_mov_b32_e32 v180, v123
	v_pk_add_f32 v[144:145], v[144:145], v[144:145] op_sel:[0,1] op_sel_hi:[1,0]
	s_nop 0
	s_waitcnt lgkmcnt(0)
	v_sub_f32_e32 v171, v171, v246
	ds_read_b32 v247, v249 offset:96
	s_nop 0
	v_readlane_b32 s6, v207, s52
	v_readlane_b32 s7, v209, s52
	v_readlane_b32 s8, v205, s59
	v_readlane_b32 s9, v208, s59
	v_fma_f32 v171, -s6, v144, v171
	v_fma_f32 v181, -s7, v166, v181
	v_fma_f32 v180, -s8, v142, v180
	v_fma_f32 v170, -s9, v158, v170
	v_mov_b32_e32 v145, v166
	s_nop 0
	v_readlane_b32 s6, v207, s59
	v_readlane_b32 s7, v209, s59
	s_nop 0
	v_fma_f32 v171, -s6, v140, v171
	v_fma_f32 v181, -s7, v152, v181
	s_nop 0
	s_nop 0
	s_nop 0
	s_nop 0
	s_nop 0
	s_nop 0
	s_nop 0
	s_nop 0
	s_nop 0
	s_nop 0
	s_nop 0
	s_nop 0
	s_nop 0
	s_nop 0
	s_nop 0
	s_nop 0
	s_nop 1
	s_nop 0
	s_nop 0
	s_nop 1
	s_nop 0
	v_pk_add_f32 v[170:171], v[180:181], v[170:171]
	v_mov_b32_e32 v181, v123
	v_mov_b32_e32 v180, v123
	v_pk_add_f32 v[170:171], v[170:171], v[170:171] op_sel:[0,1] op_sel_hi:[1,0]
	s_nop 0
	s_waitcnt lgkmcnt(0)
	v_sub_f32_e32 v147, v147, v247
	ds_read_b32 v246, v249 offset:92
	s_nop 0
	v_readlane_b32 s6, v208, s51
	v_readlane_b32 s7, v207, s51
	v_readlane_b32 s8, v209, s51
	v_readlane_b32 s9, v205, s60
	v_fma_f32 v147, -s6, v170, v147
	v_fma_f32 v181, -s7, v144, v181
	v_fma_f32 v180, -s8, v166, v180
	v_fma_f32 v146, -s9, v142, v146
	s_nop 0
	s_nop 0
	v_readlane_b32 s6, v208, s60
	v_readlane_b32 s7, v207, s60
	v_readlane_b32 s8, v209, s60
	v_fma_f32 v147, -s6, v158, v147
	v_fma_f32 v181, -s7, v140, v181
	v_fma_f32 v180, -s8, v152, v180
	s_nop 0
	s_nop 0
	s_nop 0
	s_nop 0
	s_nop 0
	s_nop 0
	s_nop 0
	s_nop 0
	s_nop 0
	s_nop 0
	s_nop 0
	s_nop 0
	s_nop 0
	s_nop 0
	s_nop 0
	s_nop 0
	s_nop 1
	s_nop 0
	s_nop 0
	s_nop 1
	s_nop 0
	s_nop 0
	s_nop 1
	s_nop 0
	v_pk_add_f32 v[146:147], v[180:181], v[146:147]
	v_mov_b32_e32 v181, v123
	v_mov_b32_e32 v180, v123
	v_pk_add_f32 v[146:147], v[146:147], v[146:147] op_sel:[0,1] op_sel_hi:[1,0]
	s_nop 0
	s_waitcnt lgkmcnt(0)
	v_sub_f32_e32 v175, v175, v246
	ds_read_b32 v247, v249 offset:88
	s_nop 0
	v_readlane_b32 s6, v205, s70
	v_readlane_b32 s7, v208, s70
	v_readlane_b32 s8, v207, s70
	v_readlane_b32 s9, v209, s70
	v_fma_f32 v175, -s6, v146, v175
	v_fma_f32 v181, -s7, v170, v181
	v_fma_f32 v180, -s8, v144, v180
	v_fma_f32 v174, -s9, v166, v174
	v_mov_b32_e32 v147, v170
	s_nop 0
	v_readlane_b32 s6, v205, s61
	v_readlane_b32 s7, v208, s61
	v_readlane_b32 s8, v207, s61
	v_readlane_b32 s9, v209, s61
	v_fma_f32 v175, -s6, v142, v175
	v_fma_f32 v181, -s7, v158, v181
	v_fma_f32 v180, -s8, v140, v180
	v_fma_f32 v174, -s9, v152, v174
	s_nop 0
	s_nop 0
	s_nop 0
	s_nop 0
	s_nop 0
	s_nop 0
	s_nop 0
	s_nop 0
	s_nop 0
	s_nop 0
	s_nop 0
	s_nop 0
	s_nop 0
	s_nop 0
	s_nop 0
	s_nop 0
	s_nop 0
	v_pk_add_f32 v[174:175], v[180:181], v[174:175]
	v_mov_b32_e32 v181, v123
	v_mov_b32_e32 v180, v123
	v_pk_add_f32 v[174:175], v[174:175], v[174:175] op_sel:[0,1] op_sel_hi:[1,0]
	s_nop 0
	s_waitcnt lgkmcnt(0)
	v_sub_f32_e32 v149, v149, v247
	ds_read_b32 v246, v249 offset:84
	s_nop 0
	v_readlane_b32 s6, v206, s62
	v_readlane_b32 s7, v205, s71
	v_readlane_b32 s8, v208, s71
	v_readlane_b32 s9, v207, s71
	v_fma_f32 v149, -s6, v174, v149
	v_fma_f32 v181, -s7, v146, v181
	v_fma_f32 v180, -s8, v170, v180
	v_fma_f32 v148, -s9, v144, v148
	s_nop 0
	s_nop 0
	v_readlane_b32 s6, v209, s71
	v_readlane_b32 s7, v205, s62
	v_readlane_b32 s8, v208, s62
	v_readlane_b32 s9, v207, s62
	v_fma_f32 v149, -s6, v166, v149
	v_fma_f32 v181, -s7, v142, v181
	v_fma_f32 v180, -s8, v158, v180
	v_fma_f32 v148, -s9, v140, v148
	s_nop 0
	s_nop 0
	v_readlane_b32 s6, v209, s62
	s_nop 1
	v_fma_f32 v149, -s6, v152, v149
	s_nop 0
	s_nop 0
	s_nop 0
	s_nop 0
	s_nop 0
	s_nop 0
	s_nop 0
	s_nop 0
	s_nop 0
	s_nop 0
	s_nop 0
	s_nop 0
	s_nop 0
	s_nop 0
	s_nop 0
	s_nop 0
	s_nop 1
	s_nop 0
	v_pk_add_f32 v[148:149], v[180:181], v[148:149]
	v_mov_b32_e32 v181, v123
	v_mov_b32_e32 v180, v123
	v_pk_add_f32 v[148:149], v[148:149], v[148:149] op_sel:[0,1] op_sel_hi:[1,0]
	s_nop 0
	s_waitcnt lgkmcnt(0)
	v_sub_f32_e32 v179, v179, v246
	ds_read_b32 v247, v249 offset:80
	s_nop 0
	v_readlane_b32 s6, v203, s63
	v_readlane_b32 s7, v206, s63
	v_readlane_b32 s8, v205, s72
	v_readlane_b32 s9, v208, s72
	v_fma_f32 v179, -s6, v148, v179
	v_fma_f32 v181, -s7, v174, v181
	v_fma_f32 v180, -s8, v146, v180
	v_fma_f32 v178, -s9, v170, v178
	v_mov_b32_e32 v149, v174
	s_nop 0
	v_readlane_b32 s6, v207, s72
	v_readlane_b32 s7, v209, s72
	v_readlane_b32 s8, v205, s63
	v_readlane_b32 s9, v208, s63
	v_fma_f32 v179, -s6, v144, v179
	v_fma_f32 v181, -s7, v166, v181
	v_fma_f32 v180, -s8, v142, v180
	v_fma_f32 v178, -s9, v158, v178
	s_nop 0
	s_nop 0
	v_readlane_b32 s6, v207, s63
	v_readlane_b32 s7, v209, s63
	s_nop 0
	v_fma_f32 v179, -s6, v140, v179
	v_fma_f32 v181, -s7, v152, v181
	s_nop 0
	s_nop 0
	s_nop 0
	s_nop 0
	s_nop 0
	s_nop 0
	s_nop 0
	s_nop 0
	s_nop 0
	s_nop 0
	s_nop 0
	s_nop 0
	s_nop 0
	s_nop 0
	s_nop 0
	s_nop 0
	s_nop 1
	s_nop 0
	s_nop 0
	s_nop 1
	s_nop 0
	v_pk_add_f32 v[178:179], v[180:181], v[178:179]
	v_mov_b32_e32 v181, v123
	v_mov_b32_e32 v180, v123
	v_pk_add_f32 v[178:179], v[178:179], v[178:179] op_sel:[0,1] op_sel_hi:[1,0]
	s_nop 0
	s_waitcnt lgkmcnt(0)
	v_sub_f32_e32 v151, v151, v247
	ds_read_b32 v246, v249 offset:76
	s_nop 0
	v_readlane_b32 s6, v204, s22
	v_readlane_b32 s7, v203, s22
	v_readlane_b32 s8, v206, s22
	v_readlane_b32 s9, v205, s73
	v_fma_f32 v151, -s6, v178, v151
	v_fma_f32 v181, -s7, v148, v181
	v_fma_f32 v180, -s8, v174, v180
	v_fma_f32 v150, -s9, v146, v150
	s_nop 0
	s_nop 0
	v_readlane_b32 s6, v208, s73
	v_readlane_b32 s7, v207, s73
	v_readlane_b32 s8, v209, s73
	v_readlane_b32 s9, v205, s22
	v_fma_f32 v151, -s6, v170, v151
	v_fma_f32 v181, -s7, v144, v181
	v_fma_f32 v180, -s8, v166, v180
	v_fma_f32 v150, -s9, v142, v150
	s_nop 0
	s_nop 0
	v_readlane_b32 s6, v208, s22
	v_readlane_b32 s7, v207, s22
	v_readlane_b32 s8, v209, s22
	v_fma_f32 v151, -s6, v158, v151
	v_fma_f32 v181, -s7, v140, v181
	v_fma_f32 v180, -s8, v152, v180
	s_nop 0
	s_nop 0
	s_nop 0
	s_nop 0
	s_nop 0
	s_nop 0
	s_nop 0
	s_nop 0
	s_nop 0
	s_nop 0
	s_nop 0
	s_nop 0
	s_nop 0
	s_nop 0
	s_nop 0
	s_nop 0
	s_nop 1
	s_nop 0
	s_nop 0
	s_nop 1
	s_nop 0
	s_nop 0
	s_nop 1
	s_nop 0
	v_pk_add_f32 v[150:151], v[180:181], v[150:151]
	v_mov_b32_e32 v181, v123
	v_mov_b32_e32 v180, v123
	v_pk_add_f32 v[150:151], v[150:151], v[150:151] op_sel:[0,1] op_sel_hi:[1,0]
	s_nop 0
	s_waitcnt lgkmcnt(0)
	v_sub_f32_e32 v177, v177, v246
	ds_read_b32 v247, v249 offset:72
	s_nop 0
	v_readlane_b32 s6, v201, s64
	v_readlane_b32 s7, v204, s64
	v_readlane_b32 s8, v203, s64
	v_readlane_b32 s9, v206, s64
	v_fma_f32 v177, -s6, v150, v177
	v_fma_f32 v181, -s7, v178, v181
	v_fma_f32 v180, -s8, v148, v180
	v_fma_f32 v176, -s9, v174, v176
	v_mov_b32_e32 v151, v178
	s_nop 0
	v_readlane_b32 s6, v205, s50
	v_readlane_b32 s7, v208, s50
	v_readlane_b32 s8, v207, s50
	v_readlane_b32 s9, v209, s50
	v_fma_f32 v177, -s6, v146, v177
	v_fma_f32 v181, -s7, v170, v181
	v_fma_f32 v180, -s8, v144, v180
	v_fma_f32 v176, -s9, v166, v176
	s_nop 0
	s_nop 0
	v_readlane_b32 s6, v205, s64
	v_readlane_b32 s7, v208, s64
	v_readlane_b32 s8, v207, s64
	v_readlane_b32 s9, v209, s64
	v_fma_f32 v177, -s6, v142, v177
	v_fma_f32 v181, -s7, v158, v181
	v_fma_f32 v180, -s8, v140, v180
	v_fma_f32 v176, -s9, v152, v176
	s_nop 0
	s_nop 0
	s_nop 0
	s_nop 0
	s_nop 0
	s_nop 0
	s_nop 0
	s_nop 0
	s_nop 0
	s_nop 0
	s_nop 0
	s_nop 0
	s_nop 0
	s_nop 0
	s_nop 0
	s_nop 0
	s_nop 0
	v_pk_add_f32 v[176:177], v[180:181], v[176:177]
	v_mov_b32_e32 v181, v123
	v_mov_b32_e32 v180, v123
	v_pk_add_f32 v[176:177], v[176:177], v[176:177] op_sel:[0,1] op_sel_hi:[1,0]
	s_nop 0
	s_waitcnt lgkmcnt(0)
	v_sub_f32_e32 v157, v157, v247
	ds_read_b32 v246, v249 offset:68
	s_nop 0
	v_readlane_b32 s6, v206, s49
	v_readlane_b32 s7, v201, s65
	v_readlane_b32 s8, v204, s65
	v_readlane_b32 s9, v203, s65
	v_fma_f32 v157, -s6, v176, v157
	v_fma_f32 v181, -s7, v150, v181
	v_fma_f32 v180, -s8, v178, v180
	v_fma_f32 v156, -s9, v148, v156
	s_nop 0
	s_nop 0
	v_readlane_b32 s6, v206, s65
	v_readlane_b32 s7, v205, s49
	v_readlane_b32 s8, v208, s49
	v_readlane_b32 s9, v207, s49
	v_fma_f32 v157, -s6, v174, v157
	v_fma_f32 v181, -s7, v146, v181
	v_fma_f32 v180, -s8, v170, v180
	v_fma_f32 v156, -s9, v144, v156
	s_nop 0
	s_nop 0
	v_readlane_b32 s6, v209, s49
	v_readlane_b32 s7, v205, s65
	v_readlane_b32 s8, v208, s65
	v_readlane_b32 s9, v207, s65
	v_fma_f32 v157, -s6, v166, v157
	v_fma_f32 v181, -s7, v142, v181
	v_fma_f32 v180, -s8, v158, v180
	v_fma_f32 v156, -s9, v140, v156
	s_nop 0
	s_nop 0
	v_readlane_b32 s6, v209, s65
	s_nop 1
	v_fma_f32 v157, -s6, v152, v157
	s_nop 0
	s_nop 0
	s_nop 0
	s_nop 0
	s_nop 0
	s_nop 0
	s_nop 0
	s_nop 0
	s_nop 0
	s_nop 0
	s_nop 0
	s_nop 0
	s_nop 0
	s_nop 0
	s_nop 0
	s_nop 0
	s_nop 1
	s_nop 0
	v_pk_add_f32 v[156:157], v[180:181], v[156:157]
	v_mov_b32_e32 v181, v123
	v_mov_b32_e32 v180, v123
	v_pk_add_f32 v[156:157], v[156:157], v[156:157] op_sel:[0,1] op_sel_hi:[1,0]
	s_nop 0
	s_waitcnt lgkmcnt(0)
	v_sub_f32_e32 v173, v173, v246
	ds_read_b32 v247, v249 offset:64
	s_nop 0
	v_readlane_b32 s6, v203, s48
	v_readlane_b32 s7, v206, s48
	v_readlane_b32 s8, v201, s21
	v_readlane_b32 s9, v204, s21
	v_fma_f32 v173, -s6, v156, v173
	v_fma_f32 v181, -s7, v176, v181
	v_fma_f32 v180, -s8, v150, v180
	v_fma_f32 v172, -s9, v178, v172
	v_mov_b32_e32 v157, v176
	s_nop 0
	v_readlane_b32 s6, v203, s21
	v_readlane_b32 s7, v206, s21
	v_readlane_b32 s8, v205, s48
	v_readlane_b32 s9, v208, s48
	v_fma_f32 v173, -s6, v148, v173
	v_fma_f32 v181, -s7, v174, v181
	v_fma_f32 v180, -s8, v146, v180
	v_fma_f32 v172, -s9, v170, v172
	s_nop 0
	s_nop 0
	v_readlane_b32 s6, v207, s48
	v_readlane_b32 s7, v209, s48
	v_readlane_b32 s8, v205, s21
	v_readlane_b32 s9, v208, s21
	v_fma_f32 v173, -s6, v144, v173
	v_fma_f32 v181, -s7, v166, v181
	v_fma_f32 v180, -s8, v142, v180
	v_fma_f32 v172, -s9, v158, v172
	s_nop 0
	s_nop 0
	v_readlane_b32 s6, v207, s21
	v_readlane_b32 s7, v209, s21
	s_nop 0
	v_fma_f32 v173, -s6, v140, v173
	v_fma_f32 v181, -s7, v152, v181
	s_nop 0
	s_nop 0
	s_nop 0
	s_nop 0
	s_nop 0
	s_nop 0
	s_nop 0
	s_nop 0
	s_nop 0
	s_nop 0
	s_nop 0
	s_nop 0
	s_nop 0
	s_nop 0
	s_nop 0
	s_nop 0
	s_nop 1
	s_nop 0
	s_nop 0
	s_nop 1
	s_nop 0
	v_pk_add_f32 v[172:173], v[180:181], v[172:173]
	v_mov_b32_e32 v181, v123
	v_mov_b32_e32 v180, v123
	v_pk_add_f32 v[172:173], v[172:173], v[172:173] op_sel:[0,1] op_sel_hi:[1,0]
	s_nop 0
	s_waitcnt lgkmcnt(0)
	v_sub_f32_e32 v165, v165, v247
	ds_read_b32 v246, v249 offset:60
	s_nop 0
	v_readlane_b32 s6, v204, s47
	v_readlane_b32 s7, v203, s47
	v_readlane_b32 s8, v206, s47
	v_readlane_b32 s9, v201, s34
	v_fma_f32 v165, -s6, v172, v165
	v_fma_f32 v181, -s7, v156, v181
	v_fma_f32 v180, -s8, v176, v180
	v_fma_f32 v164, -s9, v150, v164
	s_nop 0
	s_nop 0
	v_readlane_b32 s6, v204, s34
	v_readlane_b32 s7, v203, s34
	v_readlane_b32 s8, v206, s34
	v_readlane_b32 s9, v205, s47
	v_fma_f32 v165, -s6, v178, v165
	v_fma_f32 v181, -s7, v148, v181
	v_fma_f32 v180, -s8, v174, v180
	v_fma_f32 v164, -s9, v146, v164
	s_nop 0
	s_nop 0
	v_readlane_b32 s6, v208, s47
	v_readlane_b32 s7, v207, s47
	v_readlane_b32 s8, v209, s47
	v_readlane_b32 s9, v205, s34
	v_fma_f32 v165, -s6, v170, v165
	v_fma_f32 v181, -s7, v144, v181
	v_fma_f32 v180, -s8, v166, v180
	v_fma_f32 v164, -s9, v142, v164
	s_nop 0
	s_nop 0
	v_readlane_b32 s6, v208, s34
	v_readlane_b32 s7, v207, s34
	v_readlane_b32 s8, v209, s34
	v_fma_f32 v165, -s6, v158, v165
	v_fma_f32 v181, -s7, v140, v181
	v_fma_f32 v180, -s8, v152, v180
	s_nop 0
	s_nop 0
	s_nop 0
	s_nop 0
	s_nop 0
	s_nop 0
	s_nop 0
	s_nop 0
	s_nop 0
	s_nop 0
	s_nop 0
	s_nop 0
	s_nop 0
	s_nop 0
	s_nop 0
	s_nop 0
	s_nop 1
	s_nop 0
	s_nop 0
	s_nop 1
	s_nop 0
	s_nop 0
	s_nop 1
	s_nop 0
	v_pk_add_f32 v[164:165], v[180:181], v[164:165]
	v_mov_b32_e32 v181, v123
	v_mov_b32_e32 v180, v123
	v_pk_add_f32 v[164:165], v[164:165], v[164:165] op_sel:[0,1] op_sel_hi:[1,0]
	s_nop 0
	s_waitcnt lgkmcnt(0)
	v_sub_f32_e32 v169, v169, v246
	ds_read_b32 v247, v249 offset:56
	s_nop 0
	v_readlane_b32 s6, v201, s45
	v_readlane_b32 s7, v204, s45
	v_readlane_b32 s8, v203, s45
	v_readlane_b32 s9, v206, s45
	v_fma_f32 v169, -s6, v164, v169
	v_fma_f32 v181, -s7, v172, v181
	v_fma_f32 v180, -s8, v156, v180
	v_fma_f32 v168, -s9, v176, v168
	v_mov_b32_e32 v165, v172
	s_nop 0
	v_readlane_b32 s6, v201, s66
	v_readlane_b32 s7, v204, s66
	v_readlane_b32 s8, v203, s66
	v_readlane_b32 s9, v206, s66
	v_fma_f32 v169, -s6, v150, v169
	v_fma_f32 v181, -s7, v178, v181
	v_fma_f32 v180, -s8, v148, v180
	v_fma_f32 v168, -s9, v174, v168
	s_nop 0
	s_nop 0
	v_readlane_b32 s6, v205, s45
	v_readlane_b32 s7, v208, s45
	v_readlane_b32 s8, v207, s45
	v_readlane_b32 s9, v209, s45
	v_fma_f32 v169, -s6, v146, v169
	v_fma_f32 v181, -s7, v170, v181
	v_fma_f32 v180, -s8, v144, v180
	v_fma_f32 v168, -s9, v166, v168
	s_nop 0
	s_nop 0
	v_readlane_b32 s6, v205, s66
	v_readlane_b32 s7, v208, s66
	v_readlane_b32 s8, v207, s66
	v_readlane_b32 s9, v209, s66
	v_fma_f32 v169, -s6, v142, v169
	v_fma_f32 v181, -s7, v158, v181
	v_fma_f32 v180, -s8, v140, v180
	v_fma_f32 v168, -s9, v152, v168
	s_nop 0
	s_nop 0
	s_nop 0
	s_nop 0
	s_nop 0
	s_nop 0
	s_nop 0
	s_nop 0
	s_nop 0
	s_nop 0
	s_nop 0
	s_nop 0
	s_nop 0
	s_nop 0
	s_nop 0
	s_nop 0
	s_nop 0
	v_pk_add_f32 v[168:169], v[180:181], v[168:169]
	s_nop 0
	v_pk_add_f32 v[180:181], v[168:169], v[168:169] op_sel:[0,1] op_sel_hi:[1,0]
	v_mov_b32_e32 v169, v123
	v_mov_b32_e32 v168, v123
	s_waitcnt lgkmcnt(0)
	v_sub_f32_e32 v163, v163, v247
	ds_read_b32 v246, v249 offset:52
	s_nop 0
	v_readlane_b32 s6, v202, s14
	v_readlane_b32 s7, v201, s39
	v_readlane_b32 s8, v204, s39
	v_readlane_b32 s9, v203, s39
	v_fma_f32 v163, -s6, v180, v163
	v_fma_f32 v169, -s7, v164, v169
	v_fma_f32 v168, -s8, v172, v168
	v_fma_f32 v162, -s9, v156, v162
	s_nop 0
	s_nop 0
	v_readlane_b32 s6, v206, s39
	v_readlane_b32 s7, v201, s14
	v_readlane_b32 s8, v204, s14
	v_readlane_b32 s9, v203, s14
	v_fma_f32 v163, -s6, v176, v163
	v_fma_f32 v169, -s7, v150, v169
	v_fma_f32 v168, -s8, v178, v168
	v_fma_f32 v162, -s9, v148, v162
	s_nop 0
	s_nop 0
	v_readlane_b32 s6, v206, s14
	v_readlane_b32 s7, v205, s39
	v_readlane_b32 s8, v208, s39
	v_readlane_b32 s9, v207, s39
	v_fma_f32 v163, -s6, v174, v163
	v_fma_f32 v169, -s7, v146, v169
	v_fma_f32 v168, -s8, v170, v168
	v_fma_f32 v162, -s9, v144, v162
	s_nop 0
	s_nop 0
	v_readlane_b32 s6, v209, s39
	v_readlane_b32 s7, v205, s14
	v_readlane_b32 s8, v208, s14
	v_readlane_b32 s9, v207, s14
	v_fma_f32 v163, -s6, v166, v163
	v_fma_f32 v169, -s7, v142, v169
	v_fma_f32 v168, -s8, v158, v168
	v_fma_f32 v162, -s9, v140, v162
	s_nop 0
	s_nop 0
	v_readlane_b32 s6, v209, s14
	s_nop 1
	v_fma_f32 v163, -s6, v152, v163
	s_nop 0
	s_nop 0
	s_nop 0
	s_nop 0
	s_nop 0
	s_nop 0
	s_nop 0
	s_nop 0
	s_nop 0
	s_nop 0
	s_nop 0
	s_nop 0
	s_nop 0
	s_nop 0
	s_nop 0
	s_nop 0
	s_nop 1
	s_nop 0
	v_pk_add_f32 v[162:163], v[168:169], v[162:163]
	v_mov_b32_e32 v169, v123
	v_mov_b32_e32 v168, v123
	v_pk_add_f32 v[162:163], v[162:163], v[162:163] op_sel:[0,1] op_sel_hi:[1,0]
	s_nop 0
	s_waitcnt lgkmcnt(0)
	v_sub_f32_e32 v161, v161, v246
	ds_read_b32 v247, v249 offset:48
	s_nop 0
	v_readlane_b32 s6, v199, s11
	v_readlane_b32 s7, v202, s11
	v_readlane_b32 s8, v201, s38
	v_readlane_b32 s9, v204, s38
	v_fma_f32 v161, -s6, v162, v161
	v_fma_f32 v169, -s7, v180, v169
	v_fma_f32 v168, -s8, v164, v168
	v_fma_f32 v160, -s9, v172, v160
	v_mov_b32_e32 v163, v180
	s_nop 0
	v_readlane_b32 s6, v203, s38
	v_readlane_b32 s7, v206, s38
	v_readlane_b32 s8, v201, s11
	v_readlane_b32 s9, v204, s11
	v_fma_f32 v161, -s6, v156, v161
	v_fma_f32 v169, -s7, v176, v169
	v_fma_f32 v168, -s8, v150, v168
	v_fma_f32 v160, -s9, v178, v160
	s_nop 0
	s_nop 0
	v_readlane_b32 s6, v203, s11
	v_readlane_b32 s7, v206, s11
	v_readlane_b32 s8, v205, s38
	v_readlane_b32 s9, v208, s38
	v_fma_f32 v161, -s6, v148, v161
	v_fma_f32 v169, -s7, v174, v169
	v_fma_f32 v168, -s8, v146, v168
	v_fma_f32 v160, -s9, v170, v160
	s_nop 0
	s_nop 0
	v_readlane_b32 s6, v207, s38
	v_readlane_b32 s7, v209, s38
	v_readlane_b32 s8, v205, s11
	v_readlane_b32 s9, v208, s11
	v_fma_f32 v161, -s6, v144, v161
	v_fma_f32 v169, -s7, v166, v169
	v_fma_f32 v168, -s8, v142, v168
	v_fma_f32 v160, -s9, v158, v160
	s_nop 0
	s_nop 0
	v_readlane_b32 s6, v207, s11
	v_readlane_b32 s7, v209, s11
	s_nop 0
	v_fma_f32 v161, -s6, v140, v161
	v_fma_f32 v169, -s7, v152, v169
	s_nop 0
	s_nop 0
	s_nop 0
	s_nop 0
	s_nop 0
	s_nop 0
	s_nop 0
	s_nop 0
	s_nop 0
	s_nop 0
	s_nop 0
	s_nop 0
	s_nop 0
	s_nop 0
	s_nop 0
	s_nop 0
	s_nop 1
	s_nop 0
	s_nop 0
	s_nop 1
	s_nop 0
	v_pk_add_f32 v[160:161], v[168:169], v[160:161]
	s_nop 0
	v_pk_add_f32 v[184:185], v[160:161], v[160:161] op_sel:[0,1] op_sel_hi:[1,0]
	v_mov_b32_e32 v161, v123
	v_mov_b32_e32 v160, v123
	s_waitcnt lgkmcnt(0)
	v_sub_f32_e32 v155, v155, v247
	ds_read_b32 v246, v249 offset:44
	s_nop 0
	v_readlane_b32 s6, v200, s27
	v_readlane_b32 s7, v199, s27
	v_readlane_b32 s8, v202, s27
	v_readlane_b32 s9, v201, s43
	v_fma_f32 v155, -s6, v184, v155
	v_fma_f32 v161, -s7, v162, v161
	v_fma_f32 v160, -s8, v180, v160
	v_fma_f32 v154, -s9, v164, v154
	s_nop 0
	s_nop 0
	v_readlane_b32 s6, v204, s43
	v_readlane_b32 s7, v203, s43
	v_readlane_b32 s8, v206, s43
	v_readlane_b32 s9, v201, s27
	v_fma_f32 v155, -s6, v172, v155
	v_fma_f32 v161, -s7, v156, v161
	v_fma_f32 v160, -s8, v176, v160
	v_fma_f32 v154, -s9, v150, v154
	s_nop 0
	s_nop 0
	v_readlane_b32 s6, v204, s27
	v_readlane_b32 s7, v203, s27
	v_readlane_b32 s8, v206, s27
	v_readlane_b32 s9, v205, s43
	v_fma_f32 v155, -s6, v178, v155
	v_fma_f32 v161, -s7, v148, v161
	v_fma_f32 v160, -s8, v174, v160
	v_fma_f32 v154, -s9, v146, v154
	s_nop 0
	s_nop 0
	v_readlane_b32 s6, v208, s43
	v_readlane_b32 s7, v207, s43
	v_readlane_b32 s8, v209, s43
	v_readlane_b32 s9, v205, s27
	v_fma_f32 v155, -s6, v170, v155
	v_fma_f32 v161, -s7, v144, v161
	v_fma_f32 v160, -s8, v166, v160
	v_fma_f32 v154, -s9, v142, v154
	s_nop 0
	s_nop 0
	v_readlane_b32 s6, v208, s27
	v_readlane_b32 s7, v207, s27
	v_readlane_b32 s8, v209, s27
	v_fma_f32 v155, -s6, v158, v155
	v_fma_f32 v161, -s7, v140, v161
	v_fma_f32 v160, -s8, v152, v160
	s_nop 0
	s_nop 0
	s_nop 0
	s_nop 0
	s_nop 0
	s_nop 0
	s_nop 0
	s_nop 0
	s_nop 0
	s_nop 0
	s_nop 0
	s_nop 0
	s_nop 0
	s_nop 0
	s_nop 0
	s_nop 0
	s_nop 1
	s_nop 0
	s_nop 0
	s_nop 1
	s_nop 0
	s_nop 0
	s_nop 1
	s_nop 0
	v_pk_add_f32 v[154:155], v[160:161], v[154:155]
	v_mov_b32_e32 v161, v123
	v_mov_b32_e32 v160, v123
	v_pk_add_f32 v[154:155], v[154:155], v[154:155] op_sel:[0,1] op_sel_hi:[1,0]
	s_nop 0
	s_waitcnt lgkmcnt(0)
	v_sub_f32_e32 v85, v85, v246
	ds_read_b32 v247, v249 offset:40
	s_nop 0
	v_readlane_b32 s6, v197, s67
	v_readlane_b32 s7, v200, s67
	v_readlane_b32 s8, v199, s67
	v_readlane_b32 s9, v202, s67
	v_fma_f32 v85, -s6, v154, v85
	v_fma_f32 v161, -s7, v184, v161
	v_fma_f32 v160, -s8, v162, v160
	v_fma_f32 v84, -s9, v180, v84
	v_mov_b32_e32 v155, v184
	s_nop 0
	v_readlane_b32 s6, v201, s42
	v_readlane_b32 s7, v204, s42
	v_readlane_b32 s8, v203, s42
	v_readlane_b32 s9, v206, s42
	v_fma_f32 v85, -s6, v164, v85
	v_fma_f32 v161, -s7, v172, v161
	v_fma_f32 v160, -s8, v156, v160
	v_fma_f32 v84, -s9, v176, v84
	s_nop 0
	s_nop 0
	v_readlane_b32 s6, v201, s67
	v_readlane_b32 s7, v204, s67
	v_readlane_b32 s8, v203, s67
	v_readlane_b32 s9, v206, s67
	v_fma_f32 v85, -s6, v150, v85
	v_fma_f32 v161, -s7, v178, v161
	v_fma_f32 v160, -s8, v148, v160
	v_fma_f32 v84, -s9, v174, v84
	s_nop 0
	s_nop 0
	v_readlane_b32 s6, v205, s42
	v_readlane_b32 s7, v208, s42
	v_readlane_b32 s8, v207, s42
	v_readlane_b32 s9, v209, s42
	v_fma_f32 v85, -s6, v146, v85
	v_fma_f32 v161, -s7, v170, v161
	v_fma_f32 v160, -s8, v144, v160
	v_fma_f32 v84, -s9, v166, v84
	s_nop 0
	s_nop 0
	v_readlane_b32 s6, v205, s67
	v_readlane_b32 s7, v208, s67
	v_readlane_b32 s8, v207, s67
	v_readlane_b32 s9, v209, s67
	v_fma_f32 v85, -s6, v142, v85
	v_fma_f32 v161, -s7, v158, v161
	v_fma_f32 v160, -s8, v140, v160
	v_fma_f32 v84, -s9, v152, v84
	s_nop 0
	s_nop 0
	s_nop 0
	s_nop 0
	s_nop 0
	s_nop 0
	s_nop 0
	s_nop 0
	s_nop 0
	s_nop 0
	s_nop 0
	s_nop 0
	s_nop 0
	s_nop 0
	s_nop 0
	s_nop 0
	s_nop 0
	v_pk_add_f32 v[84:85], v[160:161], v[84:85]
	v_mov_b32_e32 v161, v123
	v_mov_b32_e32 v160, v123
	v_pk_add_f32 v[84:85], v[84:85], v[84:85] op_sel:[0,1] op_sel_hi:[1,0]
	s_nop 0
	s_waitcnt lgkmcnt(0)
	v_sub_f32_e32 v83, v83, v247
	ds_read_b32 v246, v249 offset:36
	s_nop 0
	v_readlane_b32 s6, v202, s46
	v_readlane_b32 s7, v197, s2
	v_readlane_b32 s8, v200, s2
	v_readlane_b32 s9, v199, s2
	v_fma_f32 v83, -s6, v84, v83
	v_fma_f32 v161, -s7, v154, v161
	v_fma_f32 v160, -s8, v184, v160
	v_fma_f32 v82, -s9, v162, v82
	s_nop 0
	s_nop 0
	v_readlane_b32 s6, v202, s2
	v_readlane_b32 s7, v201, s46
	v_readlane_b32 s8, v204, s46
	v_readlane_b32 s9, v203, s46
	v_fma_f32 v83, -s6, v180, v83
	v_fma_f32 v161, -s7, v164, v161
	v_fma_f32 v160, -s8, v172, v160
	v_fma_f32 v82, -s9, v156, v82
	s_nop 0
	s_nop 0
	v_readlane_b32 s6, v206, s46
	v_readlane_b32 s7, v201, s2
	v_readlane_b32 s8, v204, s2
	v_readlane_b32 s9, v203, s2
	v_fma_f32 v83, -s6, v176, v83
	v_fma_f32 v161, -s7, v150, v161
	v_fma_f32 v160, -s8, v178, v160
	v_fma_f32 v82, -s9, v148, v82
	s_nop 0
	s_nop 0
	v_readlane_b32 s6, v206, s2
	v_readlane_b32 s7, v205, s46
	v_readlane_b32 s8, v208, s46
	v_readlane_b32 s9, v207, s46
	v_fma_f32 v83, -s6, v174, v83
	v_fma_f32 v161, -s7, v146, v161
	v_fma_f32 v160, -s8, v170, v160
	v_fma_f32 v82, -s9, v144, v82
	s_nop 0
	s_nop 0
	v_readlane_b32 s6, v209, s46
	v_readlane_b32 s7, v205, s2
	v_readlane_b32 s8, v208, s2
	v_readlane_b32 s9, v207, s2
	v_fma_f32 v83, -s6, v166, v83
	v_fma_f32 v161, -s7, v142, v161
	v_fma_f32 v160, -s8, v158, v160
	v_fma_f32 v82, -s9, v140, v82
	s_nop 0
	s_nop 0
	v_readlane_b32 s6, v209, s2
	s_nop 1
	v_fma_f32 v83, -s6, v152, v83
	s_nop 0
	s_nop 0
	s_nop 0
	s_nop 0
	s_nop 0
	s_nop 0
	s_nop 0
	s_nop 0
	s_nop 0
	s_nop 0
	s_nop 0
	s_nop 0
	s_nop 0
	s_nop 0
	s_nop 0
	s_nop 0
	s_nop 1
	s_nop 0
	v_pk_add_f32 v[82:83], v[160:161], v[82:83]
	s_nop 0
	v_pk_add_f32 v[160:161], v[82:83], v[82:83] op_sel:[0,1] op_sel_hi:[1,0]
	v_mov_b32_e32 v83, v123
	v_mov_b32_e32 v82, v123
	s_waitcnt lgkmcnt(0)
	v_sub_f32_e32 v79, v79, v246
	ds_read_b32 v247, v249 offset:32
	s_nop 0
	v_readlane_b32 s6, v199, s37
	v_readlane_b32 s7, v202, s37
	v_readlane_b32 s8, v197, s18
	v_readlane_b32 s9, v200, s18
	v_fma_f32 v79, -s6, v160, v79
	v_fma_f32 v83, -s7, v84, v83
	v_fma_f32 v82, -s8, v154, v82
	v_fma_f32 v78, -s9, v184, v78
	v_mov_b32_e32 v161, v84
	s_nop 0
	v_readlane_b32 s6, v199, s18
	v_readlane_b32 s7, v202, s18
	v_readlane_b32 s8, v201, s37
	v_readlane_b32 s9, v204, s37
	v_fma_f32 v79, -s6, v162, v79
	v_fma_f32 v83, -s7, v180, v83
	v_fma_f32 v82, -s8, v164, v82
	v_fma_f32 v78, -s9, v172, v78
	s_nop 0
	s_nop 0
	v_readlane_b32 s6, v203, s37
	v_readlane_b32 s7, v206, s37
	v_readlane_b32 s8, v201, s18
	v_readlane_b32 s9, v204, s18
	v_fma_f32 v79, -s6, v156, v79
	v_fma_f32 v83, -s7, v176, v83
	v_fma_f32 v82, -s8, v150, v82
	v_fma_f32 v78, -s9, v178, v78
	s_nop 0
	s_nop 0
	v_readlane_b32 s6, v203, s18
	v_readlane_b32 s7, v206, s18
	v_readlane_b32 s8, v205, s37
	v_readlane_b32 s9, v208, s37
	v_fma_f32 v79, -s6, v148, v79
	v_fma_f32 v83, -s7, v174, v83
	v_fma_f32 v82, -s8, v146, v82
	v_fma_f32 v78, -s9, v170, v78
	s_nop 0
	s_nop 0
	v_readlane_b32 s6, v207, s37
	v_readlane_b32 s7, v209, s37
	v_readlane_b32 s8, v205, s18
	v_readlane_b32 s9, v208, s18
	v_fma_f32 v79, -s6, v144, v79
	v_fma_f32 v83, -s7, v166, v83
	v_fma_f32 v82, -s8, v142, v82
	v_fma_f32 v78, -s9, v158, v78
	s_nop 0
	s_nop 0
	v_readlane_b32 s6, v207, s18
	v_readlane_b32 s7, v209, s18
	s_nop 0
	v_fma_f32 v79, -s6, v140, v79
	v_fma_f32 v83, -s7, v152, v83
	s_nop 0
	s_nop 0
	s_nop 0
	s_nop 0
	s_nop 0
	s_nop 0
	s_nop 0
	s_nop 0
	s_nop 0
	s_nop 0
	s_nop 0
	s_nop 0
	s_nop 0
	s_nop 0
	s_nop 0
	s_nop 0
	s_nop 1
	s_nop 0
	s_nop 0
	s_nop 1
	s_nop 0
	v_pk_add_f32 v[78:79], v[82:83], v[78:79]
	v_mov_b32_e32 v83, v123
	v_mov_b32_e32 v82, v123
	v_pk_add_f32 v[78:79], v[78:79], v[78:79] op_sel:[0,1] op_sel_hi:[1,0]
	s_nop 0
	s_waitcnt lgkmcnt(0)
	v_sub_f32_e32 v75, v75, v247
	ds_read_b32 v246, v249 offset:28
	s_nop 0
	v_readlane_b32 s6, v200, s40
	v_readlane_b32 s7, v199, s40
	v_readlane_b32 s8, v202, s40
	v_readlane_b32 s9, v197, s19
	v_fma_f32 v75, -s6, v78, v75
	v_fma_f32 v83, -s7, v160, v83
	v_fma_f32 v82, -s8, v84, v82
	v_fma_f32 v74, -s9, v154, v74
	s_nop 0
	s_nop 0
	v_readlane_b32 s6, v200, s19
	v_readlane_b32 s7, v199, s19
	v_readlane_b32 s8, v202, s19
	v_readlane_b32 s9, v201, s40
	v_fma_f32 v75, -s6, v184, v75
	v_fma_f32 v83, -s7, v162, v83
	v_fma_f32 v82, -s8, v180, v82
	v_fma_f32 v74, -s9, v164, v74
	s_nop 0
	s_nop 0
	v_readlane_b32 s6, v204, s40
	v_readlane_b32 s7, v203, s40
	v_readlane_b32 s8, v206, s40
	v_readlane_b32 s9, v201, s19
	v_fma_f32 v75, -s6, v172, v75
	v_fma_f32 v83, -s7, v156, v83
	v_fma_f32 v82, -s8, v176, v82
	v_fma_f32 v74, -s9, v150, v74
	s_nop 0
	s_nop 0
	v_readlane_b32 s6, v204, s19
	v_readlane_b32 s7, v203, s19
	v_readlane_b32 s8, v206, s19
	v_readlane_b32 s9, v205, s40
	v_fma_f32 v75, -s6, v178, v75
	v_fma_f32 v83, -s7, v148, v83
	v_fma_f32 v82, -s8, v174, v82
	v_fma_f32 v74, -s9, v146, v74
	s_nop 0
	s_nop 0
	v_readlane_b32 s6, v208, s40
	v_readlane_b32 s7, v207, s40
	v_readlane_b32 s8, v209, s40
	v_readlane_b32 s9, v205, s19
	v_fma_f32 v75, -s6, v170, v75
	v_fma_f32 v83, -s7, v144, v83
	v_fma_f32 v82, -s8, v166, v82
	v_fma_f32 v74, -s9, v142, v74
	s_nop 0
	s_nop 0
	v_readlane_b32 s6, v208, s19
	v_readlane_b32 s7, v207, s19
	v_readlane_b32 s8, v209, s19
	v_fma_f32 v75, -s6, v158, v75
	v_fma_f32 v83, -s7, v140, v83
	v_fma_f32 v82, -s8, v152, v82
	s_nop 0
	s_nop 0
	s_nop 0
	s_nop 0
	s_nop 0
	s_nop 0
	s_nop 0
	s_nop 0
	s_nop 0
	s_nop 0
	s_nop 0
	s_nop 0
	s_nop 0
	s_nop 0
	s_nop 0
	s_nop 0
	s_nop 1
	s_nop 0
	s_nop 0
	s_nop 1
	s_nop 0
	s_nop 0
	s_nop 1
	s_nop 0
	v_pk_add_f32 v[74:75], v[82:83], v[74:75]
	s_nop 0
	v_pk_add_f32 v[168:169], v[74:75], v[74:75] op_sel:[0,1] op_sel_hi:[1,0]
	v_mov_b32_e32 v75, v123
	v_mov_b32_e32 v74, v123
	s_waitcnt lgkmcnt(0)
	v_sub_f32_e32 v71, v71, v246
	ds_read_b32 v247, v249 offset:24
	s_nop 0
	v_readlane_b32 s6, v197, s44
	v_readlane_b32 s7, v200, s44
	v_readlane_b32 s8, v199, s44
	v_readlane_b32 s9, v202, s44
	v_fma_f32 v71, -s6, v168, v71
	v_fma_f32 v75, -s7, v78, v75
	v_fma_f32 v74, -s8, v160, v74
	v_fma_f32 v70, -s9, v84, v70
	v_mov_b32_e32 v169, v78
	s_nop 0
	v_readlane_b32 s6, v197, s68
	v_readlane_b32 s7, v200, s68
	v_readlane_b32 s8, v199, s68
	v_readlane_b32 s9, v202, s68
	v_fma_f32 v71, -s6, v154, v71
	v_fma_f32 v75, -s7, v184, v75
	v_fma_f32 v74, -s8, v162, v74
	v_fma_f32 v70, -s9, v180, v70
	s_nop 0
	s_nop 0
	v_readlane_b32 s6, v201, s44
	v_readlane_b32 s7, v204, s44
	v_readlane_b32 s8, v203, s44
	v_readlane_b32 s9, v206, s44
	v_fma_f32 v71, -s6, v164, v71
	v_fma_f32 v75, -s7, v172, v75
	v_fma_f32 v74, -s8, v156, v74
	v_fma_f32 v70, -s9, v176, v70
	s_nop 0
	s_nop 0
	v_readlane_b32 s6, v201, s68
	v_readlane_b32 s7, v204, s68
	v_readlane_b32 s8, v203, s68
	v_readlane_b32 s9, v206, s68
	v_fma_f32 v71, -s6, v150, v71
	v_fma_f32 v75, -s7, v178, v75
	v_fma_f32 v74, -s8, v148, v74
	v_fma_f32 v70, -s9, v174, v70
	s_nop 0
	s_nop 0
	v_readlane_b32 s6, v205, s44
	v_readlane_b32 s7, v208, s44
	v_readlane_b32 s8, v207, s44
	v_readlane_b32 s9, v209, s44
	v_fma_f32 v71, -s6, v146, v71
	v_fma_f32 v75, -s7, v170, v75
	v_fma_f32 v74, -s8, v144, v74
	v_fma_f32 v70, -s9, v166, v70
	s_nop 0
	s_nop 0
	v_readlane_b32 s6, v205, s68
	v_readlane_b32 s7, v208, s68
	v_readlane_b32 s8, v207, s68
	v_readlane_b32 s9, v209, s68
	v_fma_f32 v71, -s6, v142, v71
	v_fma_f32 v75, -s7, v158, v75
	v_fma_f32 v74, -s8, v140, v74
	v_fma_f32 v70, -s9, v152, v70
	s_nop 0
	s_nop 0
	s_nop 0
	s_nop 0
	s_nop 0
	s_nop 0
	s_nop 0
	s_nop 0
	s_nop 0
	s_nop 0
	s_nop 0
	s_nop 0
	s_nop 0
	s_nop 0
	s_nop 0
	s_nop 0
	s_nop 0
	v_pk_add_f32 v[70:71], v[74:75], v[70:71]
	v_mov_b32_e32 v75, v123
	v_mov_b32_e32 v74, v123
	v_pk_add_f32 v[70:71], v[70:71], v[70:71] op_sel:[0,1] op_sel_hi:[1,0]
	s_nop 0
	s_waitcnt lgkmcnt(0)
	v_sub_f32_e32 v67, v67, v247
	ds_read_b32 v246, v249 offset:20
	s_nop 0
	v_readlane_b32 s6, v198, s3
	v_readlane_b32 s7, v197, s35
	v_readlane_b32 s8, v200, s35
	v_readlane_b32 s9, v199, s35
	v_fma_f32 v67, -s6, v70, v67
	v_fma_f32 v75, -s7, v168, v75
	v_fma_f32 v74, -s8, v78, v74
	v_fma_f32 v66, -s9, v160, v66
	s_nop 0
	s_nop 0
	v_readlane_b32 s6, v202, s35
	v_readlane_b32 s7, v197, s3
	v_readlane_b32 s8, v200, s3
	v_readlane_b32 s9, v199, s3
	v_fma_f32 v67, -s6, v84, v67
	v_fma_f32 v75, -s7, v154, v75
	v_fma_f32 v74, -s8, v184, v74
	v_fma_f32 v66, -s9, v162, v66
	s_nop 0
	s_nop 0
	v_readlane_b32 s6, v202, s3
	v_readlane_b32 s7, v201, s35
	v_readlane_b32 s8, v204, s35
	v_readlane_b32 s9, v203, s35
	v_fma_f32 v67, -s6, v180, v67
	v_fma_f32 v75, -s7, v164, v75
	v_fma_f32 v74, -s8, v172, v74
	v_fma_f32 v66, -s9, v156, v66
	s_nop 0
	s_nop 0
	v_readlane_b32 s6, v206, s35
	v_readlane_b32 s7, v201, s3
	v_readlane_b32 s8, v204, s3
	v_readlane_b32 s9, v203, s3
	v_fma_f32 v67, -s6, v176, v67
	v_fma_f32 v75, -s7, v150, v75
	v_fma_f32 v74, -s8, v178, v74
	v_fma_f32 v66, -s9, v148, v66
	s_nop 0
	s_nop 0
	v_readlane_b32 s6, v206, s3
	v_readlane_b32 s7, v205, s35
	v_readlane_b32 s8, v208, s35
	v_readlane_b32 s9, v207, s35
	v_fma_f32 v67, -s6, v174, v67
	v_fma_f32 v75, -s7, v146, v75
	v_fma_f32 v74, -s8, v170, v74
	v_fma_f32 v66, -s9, v144, v66
	s_nop 0
	s_nop 0
	v_readlane_b32 s6, v209, s35
	v_readlane_b32 s7, v205, s3
	v_readlane_b32 s8, v208, s3
	v_readlane_b32 s9, v207, s3
	v_fma_f32 v67, -s6, v166, v67
	v_fma_f32 v75, -s7, v142, v75
	v_fma_f32 v74, -s8, v158, v74
	v_fma_f32 v66, -s9, v140, v66
	s_nop 0
	s_nop 0
	v_readlane_b32 s6, v209, s3
	s_nop 1
	v_fma_f32 v67, -s6, v152, v67
	s_nop 0
	s_nop 0
	s_nop 0
	s_nop 0
	s_nop 0
	s_nop 0
	s_nop 0
	s_nop 0
	s_nop 0
	s_nop 0
	s_nop 0
	s_nop 0
	s_nop 0
	s_nop 0
	s_nop 0
	s_nop 0
	s_nop 1
	s_nop 0
	v_pk_add_f32 v[66:67], v[74:75], v[66:67]
	s_nop 0
	v_pk_add_f32 v[182:183], v[66:67], v[66:67] op_sel:[0,1] op_sel_hi:[1,0]
	v_mov_b32_e32 v67, v123
	v_mov_b32_e32 v66, v123
	s_waitcnt lgkmcnt(0)
	v_sub_f32_e32 v63, v63, v246
	ds_read_b32 v247, v249 offset:16
	s_nop 0
	v_readlane_b32 s6, v195, s16
	v_readlane_b32 s7, v198, s16
	v_readlane_b32 s8, v197, s30
	v_readlane_b32 s9, v200, s30
	v_fma_f32 v63, -s6, v182, v63
	v_fma_f32 v67, -s7, v70, v67
	v_fma_f32 v66, -s8, v168, v66
	v_fma_f32 v62, -s9, v78, v62
	v_mov_b32_e32 v183, v70
	s_nop 0
	v_readlane_b32 s6, v199, s30
	v_readlane_b32 s7, v202, s30
	v_readlane_b32 s8, v197, s16
	v_readlane_b32 s9, v200, s16
	v_fma_f32 v63, -s6, v160, v63
	v_fma_f32 v67, -s7, v84, v67
	v_fma_f32 v66, -s8, v154, v66
	v_fma_f32 v62, -s9, v184, v62
	s_nop 0
	s_nop 0
	v_readlane_b32 s6, v199, s16
	v_readlane_b32 s7, v202, s16
	v_readlane_b32 s8, v201, s30
	v_readlane_b32 s9, v204, s30
	v_fma_f32 v63, -s6, v162, v63
	v_fma_f32 v67, -s7, v180, v67
	v_fma_f32 v66, -s8, v164, v66
	v_fma_f32 v62, -s9, v172, v62
	s_nop 0
	s_nop 0
	v_readlane_b32 s6, v203, s30
	v_readlane_b32 s7, v206, s30
	v_readlane_b32 s8, v201, s16
	v_readlane_b32 s9, v204, s16
	v_fma_f32 v63, -s6, v156, v63
	v_fma_f32 v67, -s7, v176, v67
	v_fma_f32 v66, -s8, v150, v66
	v_fma_f32 v62, -s9, v178, v62
	s_nop 0
	s_nop 0
	v_readlane_b32 s6, v203, s16
	v_readlane_b32 s7, v206, s16
	v_readlane_b32 s8, v205, s30
	v_readlane_b32 s9, v208, s30
	v_fma_f32 v63, -s6, v148, v63
	v_fma_f32 v67, -s7, v174, v67
	v_fma_f32 v66, -s8, v146, v66
	v_fma_f32 v62, -s9, v170, v62
	s_nop 0
	s_nop 0
	v_readlane_b32 s6, v207, s30
	v_readlane_b32 s7, v209, s30
	v_readlane_b32 s8, v205, s16
	v_readlane_b32 s9, v208, s16
	v_fma_f32 v63, -s6, v144, v63
	v_fma_f32 v67, -s7, v166, v67
	v_fma_f32 v66, -s8, v142, v66
	v_fma_f32 v62, -s9, v158, v62
	s_nop 0
	s_nop 0
	v_readlane_b32 s6, v207, s16
	v_readlane_b32 s7, v209, s16
	s_nop 0
	v_fma_f32 v63, -s6, v140, v63
	v_fma_f32 v67, -s7, v152, v67
	s_nop 0
	s_nop 0
	s_nop 0
	s_nop 0
	s_nop 0
	s_nop 0
	s_nop 0
	s_nop 0
	s_nop 0
	s_nop 0
	s_nop 0
	s_nop 0
	s_nop 0
	s_nop 0
	s_nop 0
	s_nop 0
	s_nop 1
	s_nop 0
	s_nop 0
	s_nop 1
	s_nop 0
	v_pk_add_f32 v[62:63], v[66:67], v[62:63]
	v_mov_b32_e32 v67, v123
	v_mov_b32_e32 v66, v123
	v_pk_add_f32 v[62:63], v[62:63], v[62:63] op_sel:[0,1] op_sel_hi:[1,0]
	s_nop 0
	s_waitcnt lgkmcnt(0)
	v_sub_f32_e32 v29, v29, v247
	ds_read_b32 v246, v249 offset:12
	s_nop 0
	v_readlane_b32 s6, v196, s17
	v_readlane_b32 s7, v195, s17
	v_readlane_b32 s8, v198, s17
	v_readlane_b32 s9, v197, s36
	v_fma_f32 v29, -s6, v62, v29
	v_fma_f32 v67, -s7, v182, v67
	v_fma_f32 v66, -s8, v70, v66
	v_fma_f32 v28, -s9, v168, v28
	s_nop 0
	s_nop 0
	v_readlane_b32 s6, v200, s36
	v_readlane_b32 s7, v199, s36
	v_readlane_b32 s8, v202, s36
	v_readlane_b32 s9, v197, s17
	v_fma_f32 v29, -s6, v78, v29
	v_fma_f32 v67, -s7, v160, v67
	v_fma_f32 v66, -s8, v84, v66
	v_fma_f32 v28, -s9, v154, v28
	s_nop 0
	s_nop 0
	v_readlane_b32 s6, v200, s17
	v_readlane_b32 s7, v199, s17
	v_readlane_b32 s8, v202, s17
	v_readlane_b32 s9, v201, s36
	v_fma_f32 v29, -s6, v184, v29
	v_fma_f32 v67, -s7, v162, v67
	v_fma_f32 v66, -s8, v180, v66
	v_fma_f32 v28, -s9, v164, v28
	s_nop 0
	s_nop 0
	v_readlane_b32 s6, v204, s36
	v_readlane_b32 s7, v203, s36
	v_readlane_b32 s8, v206, s36
	v_readlane_b32 s9, v201, s17
	v_fma_f32 v29, -s6, v172, v29
	v_fma_f32 v67, -s7, v156, v67
	v_fma_f32 v66, -s8, v176, v66
	v_fma_f32 v28, -s9, v150, v28
	s_nop 0
	s_nop 0
	v_readlane_b32 s6, v204, s17
	v_readlane_b32 s7, v203, s17
	v_readlane_b32 s8, v206, s17
	v_readlane_b32 s9, v205, s36
	v_fma_f32 v29, -s6, v178, v29
	v_fma_f32 v67, -s7, v148, v67
	v_fma_f32 v66, -s8, v174, v66
	v_fma_f32 v28, -s9, v146, v28
	s_nop 0
	s_nop 0
	v_readlane_b32 s6, v208, s36
	v_readlane_b32 s7, v207, s36
	v_readlane_b32 s8, v209, s36
	v_readlane_b32 s9, v205, s17
	v_fma_f32 v29, -s6, v170, v29
	v_fma_f32 v67, -s7, v144, v67
	v_fma_f32 v66, -s8, v166, v66
	v_fma_f32 v28, -s9, v142, v28
	s_nop 0
	s_nop 0
	v_readlane_b32 s6, v208, s17
	v_readlane_b32 s7, v207, s17
	v_readlane_b32 s8, v209, s17
	v_fma_f32 v29, -s6, v158, v29
	v_fma_f32 v67, -s7, v140, v67
	v_fma_f32 v66, -s8, v152, v66
	s_nop 0
	s_nop 0
	s_nop 0
	s_nop 0
	s_nop 0
	s_nop 0
	s_nop 0
	s_nop 0
	s_nop 0
	s_nop 0
	s_nop 0
	s_nop 0
	s_nop 0
	s_nop 0
	s_nop 0
	s_nop 0
	s_nop 1
	s_nop 0
	s_nop 0
	s_nop 1
	s_nop 0
	s_nop 0
	s_nop 1
	s_nop 0
	v_pk_add_f32 v[28:29], v[66:67], v[28:29]
	s_nop 0
	v_pk_add_f32 v[186:187], v[28:29], v[28:29] op_sel:[0,1] op_sel_hi:[1,0]
	v_mov_b32_e32 v29, v123
	v_mov_b32_e32 v28, v123
	s_waitcnt lgkmcnt(0)
	v_sub_f32_e32 v25, v25, v246
	ds_read_b32 v247, v249 offset:8
	s_nop 0
	v_readlane_b32 s6, v194, s69
	v_readlane_b32 s7, v196, s69
	v_readlane_b32 s8, v195, s69
	v_readlane_b32 s9, v198, s69
	v_fma_f32 v25, -s6, v186, v25
	v_fma_f32 v29, -s7, v62, v29
	v_fma_f32 v28, -s8, v182, v28
	v_fma_f32 v24, -s9, v70, v24
	v_mov_b32_e32 v187, v62
	s_nop 0
	v_readlane_b32 s6, v197, s12
	v_readlane_b32 s7, v200, s12
	v_readlane_b32 s8, v199, s12
	v_readlane_b32 s9, v202, s12
	v_fma_f32 v25, -s6, v168, v25
	v_fma_f32 v29, -s7, v78, v29
	v_fma_f32 v28, -s8, v160, v28
	v_fma_f32 v24, -s9, v84, v24
	s_nop 0
	s_nop 0
	v_readlane_b32 s6, v197, s69
	v_readlane_b32 s7, v200, s69
	v_readlane_b32 s8, v199, s69
	v_readlane_b32 s9, v202, s69
	v_fma_f32 v25, -s6, v154, v25
	v_fma_f32 v29, -s7, v184, v29
	v_fma_f32 v28, -s8, v162, v28
	v_fma_f32 v24, -s9, v180, v24
	s_nop 0
	s_nop 0
	v_readlane_b32 s6, v201, s12
	v_readlane_b32 s7, v204, s12
	v_readlane_b32 s8, v203, s12
	v_readlane_b32 s9, v206, s12
	v_fma_f32 v25, -s6, v164, v25
	v_fma_f32 v29, -s7, v172, v29
	v_fma_f32 v28, -s8, v156, v28
	v_fma_f32 v24, -s9, v176, v24
	s_nop 0
	s_nop 0
	v_readlane_b32 s6, v201, s69
	v_readlane_b32 s7, v204, s69
	v_readlane_b32 s8, v203, s69
	v_readlane_b32 s9, v206, s69
	v_fma_f32 v25, -s6, v150, v25
	v_fma_f32 v29, -s7, v178, v29
	v_fma_f32 v28, -s8, v148, v28
	v_fma_f32 v24, -s9, v174, v24
	s_nop 0
	s_nop 0
	v_readlane_b32 s6, v205, s12
	v_readlane_b32 s7, v208, s12
	v_readlane_b32 s8, v207, s12
	v_readlane_b32 s9, v209, s12
	v_fma_f32 v25, -s6, v146, v25
	v_fma_f32 v29, -s7, v170, v29
	v_fma_f32 v28, -s8, v144, v28
	v_fma_f32 v24, -s9, v166, v24
	s_nop 0
	s_nop 0
	v_readlane_b32 s6, v205, s69
	v_readlane_b32 s7, v208, s69
	v_readlane_b32 s8, v207, s69
	v_readlane_b32 s9, v209, s69
	v_fma_f32 v25, -s6, v142, v25
	v_fma_f32 v29, -s7, v158, v29
	v_fma_f32 v28, -s8, v140, v28
	v_fma_f32 v24, -s9, v152, v24
	s_nop 0
	s_nop 0
	s_nop 0
	s_nop 0
	s_nop 0
	s_nop 0
	s_nop 0
	s_nop 0
	s_nop 0
	s_nop 0
	s_nop 0
	s_nop 0
	s_nop 0
	s_nop 0
	s_nop 0
	s_nop 0
	s_nop 0
	v_pk_add_f32 v[24:25], v[28:29], v[24:25]
	v_mov_b32_e32 v29, v123
	v_mov_b32_e32 v28, v123
	v_pk_add_f32 v[24:25], v[24:25], v[24:25] op_sel:[0,1] op_sel_hi:[1,0]
	s_nop 0
	s_waitcnt lgkmcnt(0)
	v_sub_f32_e32 v15, v15, v247
	ds_read_b32 v246, v249 offset:4
	s_nop 0
	v_readlane_b32 s6, v198, s15
	v_readlane_b32 s7, v194, s23
	v_readlane_b32 s8, v196, s23
	v_readlane_b32 s9, v195, s23
	v_fma_f32 v15, -s6, v24, v15
	v_fma_f32 v29, -s7, v186, v29
	v_fma_f32 v28, -s8, v62, v28
	v_fma_f32 v14, -s9, v182, v14
	s_nop 0
	s_nop 0
	v_readlane_b32 s6, v198, s23
	v_readlane_b32 s7, v197, s15
	v_readlane_b32 s8, v200, s15
	v_readlane_b32 s9, v199, s15
	v_fma_f32 v15, -s6, v70, v15
	v_fma_f32 v29, -s7, v168, v29
	v_fma_f32 v28, -s8, v78, v28
	v_fma_f32 v14, -s9, v160, v14
	s_nop 0
	s_nop 0
	v_readlane_b32 s6, v202, s15
	v_readlane_b32 s7, v197, s23
	v_readlane_b32 s8, v200, s23
	v_readlane_b32 s9, v199, s23
	v_fma_f32 v15, -s6, v84, v15
	v_fma_f32 v29, -s7, v154, v29
	v_fma_f32 v28, -s8, v184, v28
	v_fma_f32 v14, -s9, v162, v14
	s_nop 0
	s_nop 0
	v_readlane_b32 s6, v202, s23
	v_readlane_b32 s7, v201, s15
	v_readlane_b32 s8, v204, s15
	v_readlane_b32 s9, v203, s15
	v_fma_f32 v15, -s6, v180, v15
	v_fma_f32 v29, -s7, v164, v29
	v_fma_f32 v28, -s8, v172, v28
	v_fma_f32 v14, -s9, v156, v14
	s_nop 0
	s_nop 0
	v_readlane_b32 s6, v206, s15
	v_readlane_b32 s7, v201, s23
	v_readlane_b32 s8, v204, s23
	v_readlane_b32 s9, v203, s23
	v_fma_f32 v15, -s6, v176, v15
	v_fma_f32 v29, -s7, v150, v29
	v_fma_f32 v28, -s8, v178, v28
	v_fma_f32 v14, -s9, v148, v14
	s_nop 0
	s_nop 0
	v_readlane_b32 s6, v206, s23
	v_readlane_b32 s7, v205, s15
	v_readlane_b32 s8, v208, s15
	v_readlane_b32 s9, v207, s15
	v_fma_f32 v15, -s6, v174, v15
	v_fma_f32 v29, -s7, v146, v29
	v_fma_f32 v28, -s8, v170, v28
	v_fma_f32 v14, -s9, v144, v14
	s_nop 0
	s_nop 0
	v_readlane_b32 s6, v209, s15
	v_readlane_b32 s7, v205, s23
	v_readlane_b32 s8, v208, s23
	v_readlane_b32 s9, v207, s23
	v_fma_f32 v15, -s6, v166, v15
	v_fma_f32 v29, -s7, v142, v29
	v_fma_f32 v28, -s8, v158, v28
	v_fma_f32 v14, -s9, v140, v14
	s_nop 0
	s_nop 0
	v_readlane_b32 s6, v209, s23
	s_nop 1
	v_fma_f32 v15, -s6, v152, v15
	s_nop 0
	s_nop 0
	s_nop 0
	s_nop 0
	s_nop 0
	s_nop 0
	s_nop 0
	s_nop 0
	s_nop 0
	s_nop 0
	s_nop 0
	s_nop 0
	s_nop 0
	s_nop 0
	s_nop 0
	s_nop 0
	s_nop 1
	s_nop 0
	v_pk_add_f32 v[14:15], v[28:29], v[14:15]
	s_nop 0
	v_pk_add_f32 v[188:189], v[14:15], v[14:15] op_sel:[0,1] op_sel_hi:[1,0]
	v_mov_b32_e32 v15, v123
	v_mov_b32_e32 v14, v123
	s_waitcnt lgkmcnt(0)
	v_sub_f32_e32 v7, v7, v246
	ds_read_b32 v247, v249 offset:0
	s_nop 0
	v_readlane_b32 s6, v195, s26
	v_readlane_b32 s7, v198, s26
	v_readlane_b32 s8, v194, s10
	v_readlane_b32 s9, v196, s10
	v_fma_f32 v7, -s6, v188, v7
	v_fma_f32 v15, -s7, v24, v15
	v_fma_f32 v14, -s8, v186, v14
	v_fma_f32 v6, -s9, v62, v6
	v_mov_b32_e32 v189, v24
	s_nop 0
	v_readlane_b32 s6, v195, s10
	v_readlane_b32 s7, v198, s10
	v_readlane_b32 s8, v197, s26
	v_readlane_b32 s9, v200, s26
	v_fma_f32 v7, -s6, v182, v7
	v_fma_f32 v15, -s7, v70, v15
	v_fma_f32 v14, -s8, v168, v14
	v_fma_f32 v6, -s9, v78, v6
	s_nop 0
	s_nop 0
	v_readlane_b32 s6, v199, s26
	v_readlane_b32 s7, v202, s26
	v_readlane_b32 s8, v197, s10
	v_readlane_b32 s9, v200, s10
	v_fma_f32 v7, -s6, v160, v7
	v_fma_f32 v15, -s7, v84, v15
	v_fma_f32 v14, -s8, v154, v14
	v_fma_f32 v6, -s9, v184, v6
	s_nop 0
	s_nop 0
	v_readlane_b32 s6, v199, s10
	v_readlane_b32 s7, v202, s10
	v_readlane_b32 s8, v201, s26
	v_readlane_b32 s9, v204, s26
	v_fma_f32 v7, -s6, v162, v7
	v_fma_f32 v15, -s7, v180, v15
	v_fma_f32 v14, -s8, v164, v14
	v_fma_f32 v6, -s9, v172, v6
	s_nop 0
	s_nop 0
	v_readlane_b32 s6, v203, s26
	v_readlane_b32 s7, v206, s26
	v_readlane_b32 s8, v201, s10
	v_readlane_b32 s9, v204, s10
	v_fma_f32 v7, -s6, v156, v7
	v_fma_f32 v15, -s7, v176, v15
	v_fma_f32 v14, -s8, v150, v14
	v_fma_f32 v6, -s9, v178, v6
	s_nop 0
	s_nop 0
	v_readlane_b32 s6, v203, s10
	v_readlane_b32 s7, v206, s10
	v_readlane_b32 s8, v205, s26
	v_readlane_b32 s9, v208, s26
	v_fma_f32 v7, -s6, v148, v7
	v_fma_f32 v15, -s7, v174, v15
	v_fma_f32 v14, -s8, v146, v14
	v_fma_f32 v6, -s9, v170, v6
	s_nop 0
	s_nop 0
	v_readlane_b32 s6, v207, s26
	v_readlane_b32 s7, v209, s26
	v_readlane_b32 s8, v205, s10
	v_readlane_b32 s9, v208, s10
	v_fma_f32 v7, -s6, v144, v7
	v_fma_f32 v15, -s7, v166, v15
	v_fma_f32 v14, -s8, v142, v14
	v_fma_f32 v6, -s9, v158, v6
	s_nop 0
	s_nop 0
	v_readlane_b32 s6, v207, s10
	v_readlane_b32 s7, v209, s10
	s_nop 0
	v_fma_f32 v7, -s6, v140, v7
	v_fma_f32 v15, -s7, v152, v15
	s_nop 0
	s_nop 0
	s_nop 0
	s_nop 0
	s_nop 0
	s_nop 0
	s_nop 0
	s_nop 0
	s_nop 0
	s_nop 0
	s_nop 0
	s_nop 0
	s_nop 0
	s_nop 0
	s_nop 0
	s_nop 0
	s_nop 1
	s_nop 0
	s_nop 0
	s_nop 1
	s_nop 0
	v_pk_add_f32 v[6:7], v[14:15], v[6:7]
	v_mov_b32_e32 v15, v123
	v_mov_b32_e32 v14, v123
	v_pk_add_f32 v[6:7], v[6:7], v[6:7] op_sel:[0,1] op_sel_hi:[1,0]
	s_nop 0
	s_waitcnt lgkmcnt(0)
	v_sub_f32_e32 v3, v3, v247
	s_nop 0
	v_readlane_b32 s6, v196, s13
	v_readlane_b32 s7, v195, s13
	v_readlane_b32 s8, v198, s13
	v_readlane_b32 s9, v194, s31
	v_fma_f32 v3, -s6, v6, v3
	v_fma_f32 v15, -s7, v188, v15
	v_fma_f32 v14, -s8, v24, v14
	v_fma_f32 v2, -s9, v186, v2
	s_nop 0
	s_nop 0
	v_readlane_b32 s6, v196, s31
	v_readlane_b32 s7, v195, s31
	v_readlane_b32 s8, v198, s31
	v_readlane_b32 s9, v197, s13
	v_fma_f32 v3, -s6, v62, v3
	v_fma_f32 v15, -s7, v182, v15
	v_fma_f32 v14, -s8, v70, v14
	v_fma_f32 v2, -s9, v168, v2
	s_nop 0
	s_nop 0
	v_readlane_b32 s6, v200, s13
	v_readlane_b32 s7, v199, s13
	v_readlane_b32 s8, v202, s13
	v_readlane_b32 s9, v197, s31
	v_fma_f32 v3, -s6, v78, v3
	v_fma_f32 v15, -s7, v160, v15
	v_fma_f32 v14, -s8, v84, v14
	v_fma_f32 v2, -s9, v154, v2
	s_nop 0
	s_nop 0
	v_readlane_b32 s6, v200, s31
	v_readlane_b32 s7, v199, s31
	v_readlane_b32 s8, v202, s31
	v_readlane_b32 s9, v201, s13
	v_fma_f32 v3, -s6, v184, v3
	v_fma_f32 v15, -s7, v162, v15
	v_fma_f32 v14, -s8, v180, v14
	v_fma_f32 v2, -s9, v164, v2
	s_nop 0
	s_nop 0
	v_readlane_b32 s6, v204, s13
	v_readlane_b32 s7, v203, s13
	v_readlane_b32 s8, v206, s13
	v_readlane_b32 s9, v201, s31
	v_fma_f32 v3, -s6, v172, v3
	v_fma_f32 v15, -s7, v156, v15
	v_fma_f32 v14, -s8, v176, v14
	v_fma_f32 v2, -s9, v150, v2
	s_nop 0
	s_nop 0
	v_readlane_b32 s6, v204, s31
	v_readlane_b32 s7, v203, s31
	v_readlane_b32 s8, v206, s31
	v_readlane_b32 s9, v205, s13
	v_fma_f32 v3, -s6, v178, v3
	v_fma_f32 v15, -s7, v148, v15
	v_fma_f32 v14, -s8, v174, v14
	v_fma_f32 v2, -s9, v146, v2
	s_nop 0
	s_nop 0
	v_readlane_b32 s6, v208, s13
	v_readlane_b32 s7, v207, s13
	v_readlane_b32 s8, v209, s13
	v_readlane_b32 s9, v205, s31
	v_fma_f32 v3, -s6, v170, v3
	v_fma_f32 v15, -s7, v144, v15
	v_fma_f32 v14, -s8, v166, v14
	v_fma_f32 v2, -s9, v142, v2
	s_nop 0
	s_nop 0
	v_readlane_b32 s6, v208, s31
	v_readlane_b32 s7, v207, s31
	v_readlane_b32 s8, v209, s31
	v_fma_f32 v3, -s6, v158, v3
	v_fma_f32 v15, -s7, v140, v15
	v_fma_f32 v14, -s8, v152, v14
	s_nop 0
	s_nop 0
	s_nop 0
	s_nop 0
	s_nop 0
	s_nop 0
	s_nop 0
	s_nop 0
	s_nop 0
	s_nop 0
	s_nop 0
	s_nop 0
	s_nop 0
	s_nop 0
	s_nop 0
	s_nop 0
	s_nop 1
	s_nop 0
	s_nop 0
	s_nop 1
	s_nop 0
	s_nop 0
	s_nop 1
	s_nop 0
	v_pk_add_f32 v[2:3], v[14:15], v[2:3]
	s_nop 0
	v_pk_add_f32 v[152:153], v[2:3], v[2:3] op_sel:[0,1] op_sel_hi:[1,0]
	v_readlane_b32 s6, v193, 0
	v_readlane_b32 s7, v193, 1
	v_mov_b32_e32 v153, v6
	s_nop 0
	v_pk_mul_f32 v[2:3], v[152:153], s[6:7]
	v_readlane_b32 s6, v193, 8
	v_readlane_b32 s7, v193, 9
	v_cvt_pk_bf16_f32 v62, v2, v3
	s_nop 0
	v_pk_mul_f32 v[4:5], v[168:169], s[6:7]
	v_readlane_b32 s6, v193, 2
	v_readlane_b32 s7, v193, 3
	v_cvt_pk_bf16_f32 v66, v4, v5
	s_nop 1
	v_permlane32_swap_b32_e32 v62, v66
	v_pk_mul_f32 v[6:7], v[188:189], s[6:7]
	v_readlane_b32 s6, v193, 10
	v_readlane_b32 s7, v193, 11
	v_cvt_pk_bf16_f32 v63, v6, v7
	s_nop 0
	v_pk_mul_f32 v[8:9], v[160:161], s[6:7]
	v_readlane_b32 s6, v193, 4
	v_readlane_b32 s7, v193, 5
	v_cvt_pk_bf16_f32 v67, v8, v9
	s_nop 1
	v_permlane32_swap_b32_e32 v63, v67
	v_pk_mul_f32 v[10:11], v[186:187], s[6:7]
	v_readlane_b32 s6, v193, 12
	v_readlane_b32 s7, v193, 13
	v_cvt_pk_bf16_f32 v64, v10, v11
	s_nop 0
	v_pk_mul_f32 v[12:13], v[154:155], s[6:7]
	v_readlane_b32 s6, v193, 6
	v_readlane_b32 s7, v193, 7
	v_cvt_pk_bf16_f32 v68, v12, v13
	s_nop 1
	v_permlane32_swap_b32_e32 v64, v68
	v_pk_mul_f32 v[14:15], v[182:183], s[6:7]
	v_readlane_b32 s6, v193, 14
	v_readlane_b32 s7, v193, 15
	v_cvt_pk_bf16_f32 v65, v14, v15
	s_nop 0
	v_pk_mul_f32 v[16:17], v[162:163], s[6:7]
	v_readlane_b32 s6, v193, 16
	v_readlane_b32 s7, v193, 17
	v_cvt_pk_bf16_f32 v69, v16, v17
	s_nop 1
	v_permlane32_swap_b32_e32 v65, v69
	v_pk_mul_f32 v[2:3], v[164:165], s[6:7]
	v_readlane_b32 s6, v193, 24
	v_readlane_b32 s7, v193, 25
	v_cvt_pk_bf16_f32 v70, v2, v3
	s_nop 0
	v_pk_mul_f32 v[4:5], v[146:147], s[6:7]
	v_readlane_b32 s6, v193, 18
	v_readlane_b32 s7, v193, 19
	v_cvt_pk_bf16_f32 v74, v4, v5
	s_nop 1
	v_permlane32_swap_b32_e32 v70, v74
	v_pk_mul_f32 v[6:7], v[156:157], s[6:7]
	v_readlane_b32 s6, v193, 26
	v_readlane_b32 s7, v193, 27
	v_cvt_pk_bf16_f32 v71, v6, v7
	s_nop 0
	v_pk_mul_f32 v[8:9], v[144:145], s[6:7]
	v_readlane_b32 s6, v193, 20
	v_readlane_b32 s7, v193, 21
	v_cvt_pk_bf16_f32 v75, v8, v9
	s_nop 1
	v_permlane32_swap_b32_e32 v71, v75
	v_pk_mul_f32 v[10:11], v[150:151], s[6:7]
	v_readlane_b32 s6, v193, 28
	v_readlane_b32 s7, v193, 29
	v_cvt_pk_bf16_f32 v72, v10, v11
	s_nop 0
	v_pk_mul_f32 v[12:13], v[142:143], s[6:7]
	v_readlane_b32 s6, v193, 22
	v_readlane_b32 s7, v193, 23
	v_cvt_pk_bf16_f32 v76, v12, v13
	s_nop 1
	v_permlane32_swap_b32_e32 v72, v76
	v_pk_mul_f32 v[14:15], v[148:149], s[6:7]
	v_readlane_b32 s6, v193, 30
	v_readlane_b32 s7, v193, 31
	v_cvt_pk_bf16_f32 v73, v14, v15
	s_nop 0
	v_pk_mul_f32 v[16:17], v[140:141], s[6:7]
	v_readlane_b32 s6, v193, 32
	v_readlane_b32 s7, v193, 33
	v_cvt_pk_bf16_f32 v77, v16, v17
	s_nop 1
	v_permlane32_swap_b32_e32 v73, v77
	v_pk_mul_f32 v[2:3], v[138:139], s[6:7]
	v_readlane_b32 s6, v193, 40
	v_readlane_b32 s7, v193, 41
	v_cvt_pk_bf16_f32 v2, v2, v3
	s_nop 0
	v_pk_mul_f32 v[4:5], v[130:131], s[6:7]
	v_readlane_b32 s6, v193, 34
	v_readlane_b32 s7, v193, 35
	v_cvt_pk_bf16_f32 v78, v4, v5
	s_nop 1
	v_permlane32_swap_b32_e32 v2, v78
	v_pk_mul_f32 v[6:7], v[136:137], s[6:7]
	v_readlane_b32 s6, v193, 42
	v_readlane_b32 s7, v193, 43
	v_cvt_pk_bf16_f32 v3, v6, v7
	s_nop 0
	v_pk_mul_f32 v[8:9], v[128:129], s[6:7]
	v_readlane_b32 s6, v193, 36
	v_readlane_b32 s7, v193, 37
	v_cvt_pk_bf16_f32 v79, v8, v9
	s_nop 1
	v_permlane32_swap_b32_e32 v3, v79
	v_pk_mul_f32 v[10:11], v[134:135], s[6:7]
	v_readlane_b32 s6, v193, 44
	v_readlane_b32 s7, v193, 45
	v_cvt_pk_bf16_f32 v6, v10, v11
	s_nop 0
	v_pk_mul_f32 v[12:13], v[118:119], s[6:7]
	v_readlane_b32 s6, v193, 38
	v_readlane_b32 s7, v193, 39
	v_cvt_pk_bf16_f32 v80, v12, v13
	s_nop 1
	v_permlane32_swap_b32_e32 v6, v80
	v_pk_mul_f32 v[14:15], v[132:133], s[6:7]
	v_readlane_b32 s6, v193, 46
	v_readlane_b32 s7, v193, 47
	v_cvt_pk_bf16_f32 v7, v14, v15
	s_nop 0
	v_pk_mul_f32 v[16:17], v[116:117], s[6:7]
	v_readlane_b32 s6, v193, 48
	v_readlane_b32 s7, v193, 49
	v_cvt_pk_bf16_f32 v81, v16, v17
	s_nop 1
	v_permlane32_swap_b32_e32 v7, v81
	v_pk_mul_f32 v[2:3], v[114:115], s[6:7]
	v_readlane_b32 s6, v193, 56
	v_readlane_b32 s7, v193, 57
	v_cvt_pk_bf16_f32 v2, v2, v3
	s_nop 0
	v_pk_mul_f32 v[4:5], v[94:95], s[6:7]
	v_readlane_b32 s6, v193, 50
	v_readlane_b32 s7, v193, 51
	v_cvt_pk_bf16_f32 v82, v4, v5
	s_nop 1
	v_permlane32_swap_b32_e32 v2, v82
	v_pk_mul_f32 v[6:7], v[110:111], s[6:7]
	v_readlane_b32 s6, v193, 58
	v_readlane_b32 s7, v193, 59
	v_cvt_pk_bf16_f32 v3, v6, v7
	s_nop 0
	v_pk_mul_f32 v[8:9], v[92:93], s[6:7]
	v_readlane_b32 s6, v193, 52
	v_readlane_b32 s7, v193, 53
	v_cvt_pk_bf16_f32 v83, v8, v9
	s_nop 1
	v_permlane32_swap_b32_e32 v3, v83
	v_pk_mul_f32 v[10:11], v[104:105], s[6:7]
	v_readlane_b32 s6, v193, 60
	v_readlane_b32 s7, v193, 61
	v_cvt_pk_bf16_f32 v6, v10, v11
	s_nop 0
	v_pk_mul_f32 v[12:13], v[90:91], s[6:7]
	v_readlane_b32 s6, v193, 54
	v_readlane_b32 s7, v193, 55
	v_cvt_pk_bf16_f32 v84, v12, v13
	s_nop 1
	v_permlane32_swap_b32_e32 v6, v84
	v_pk_mul_f32 v[14:15], v[96:97], s[6:7]
	v_readlane_b32 s6, v193, 62
	v_readlane_b32 s7, v193, 63
	v_cvt_pk_bf16_f32 v7, v14, v15
	s_nop 0
	v_pk_mul_f32 v[16:17], v[88:89], s[6:7]
	s_mov_b32 s7, 0x26400000
	v_cvt_pk_bf16_f32 v85, v16, v17
	s_nop 1
	v_permlane32_swap_b32_e32 v7, v85
	s_waitcnt vmcnt(5)
	v_mfma_f32_32x32x16_bf16 v[2:17], v[62:65], v[18:21], 0
	s_mov_b32 s6, 0x9002000
	v_mfma_f32_32x32x16_bf16 v[18:33], v[66:69], v[18:21], 0
	v_mfma_f32_32x32x16_bf16 v[18:33], v[74:77], v[58:61], v[18:33]
	v_mfma_f32_32x32x16_bf16 v[18:33], v[78:81], v[54:57], v[18:33]
	v_mfma_f32_32x32x16_bf16 v[2:17], v[70:73], v[58:61], v[2:17]
	s_waitcnt vmcnt(4)
	v_mfma_f32_32x32x16_bf16 v[18:33], v[82:85], v[50:53], v[18:33]
	v_add_co_u32_e32 v50, vcc, s7, v126
	s_nop 8
	v_cvt_pk_bf16_f32 v2, v2, v3
	v_cvt_pk_bf16_f32 v3, v4, v5
	v_cvt_pk_bf16_f32 v4, v6, v7
	v_cvt_pk_bf16_f32 v5, v8, v9
	v_addc_co_u32_e32 v51, vcc, 0, v127, vcc
	global_store_dwordx4 v[50:51], v[2:5], off
	v_add_co_u32_e32 v6, vcc, s7, v120
	s_nop 0
	v_cvt_pk_bf16_f32 v2, v10, v11
	v_cvt_pk_bf16_f32 v3, v12, v13
	v_cvt_pk_bf16_f32 v4, v14, v15
	v_cvt_pk_bf16_f32 v5, v16, v17
	global_store_dwordx4 v[50:51], v[2:5], off offset:16
	v_addc_co_u32_e32 v7, vcc, 0, v121, vcc
	s_nop 0
	v_cvt_pk_bf16_f32 v2, v18, v19
	v_cvt_pk_bf16_f32 v3, v20, v21
	v_cvt_pk_bf16_f32 v4, v22, v23
	v_cvt_pk_bf16_f32 v5, v24, v25
	global_store_dwordx4 v[6:7], v[2:5], off
	s_nop 1
	v_cvt_pk_bf16_f32 v2, v26, v27
	v_cvt_pk_bf16_f32 v3, v28, v29
	v_cvt_pk_bf16_f32 v4, v30, v31
	v_cvt_pk_bf16_f32 v5, v32, v33
	global_store_dwordx4 v[6:7], v[2:5], off offset:16
	s_waitcnt vmcnt(7)
	v_mfma_f32_32x32x16_bf16 v[18:33], v[62:65], v[46:49], 0
	v_mfma_f32_32x32x16_bf16 v[2:17], v[66:69], v[46:49], 0
	s_waitcnt vmcnt(6)
	v_mfma_f32_32x32x16_bf16 v[2:17], v[74:77], v[42:45], v[2:17]
	s_waitcnt vmcnt(5)
	v_mfma_f32_32x32x16_bf16 v[2:17], v[78:81], v[38:41], v[2:17]
	s_waitcnt vmcnt(4)
	v_mfma_f32_32x32x16_bf16 v[2:17], v[82:85], v[34:37], v[2:17]
	v_mfma_f32_32x32x16_bf16 v[18:33], v[70:73], v[42:45], v[18:33]
	s_nop 10
	v_cvt_pk_bf16_f32 v2, v2, v3
	v_cvt_pk_bf16_f32 v3, v4, v5
	v_cvt_pk_bf16_f32 v4, v6, v7
	v_add_co_u32_e32 v6, vcc, s7, v112
	v_cvt_pk_bf16_f32 v5, v8, v9
	s_nop 0
	v_addc_co_u32_e32 v7, vcc, 0, v113, vcc
	v_cvt_pk_bf16_f32 v18, v18, v19
	v_cvt_pk_bf16_f32 v19, v20, v21
	v_cvt_pk_bf16_f32 v20, v22, v23
	v_cvt_pk_bf16_f32 v21, v24, v25
	v_add_co_u32_e32 v38, vcc, s6, v98
	global_store_dwordx4 v[50:51], v[18:21], off offset:2048
	s_nop 0
	v_addc_co_u32_e32 v39, vcc, 0, v99, vcc
	v_cvt_pk_bf16_f32 v18, v26, v27
	v_cvt_pk_bf16_f32 v19, v28, v29
	v_cvt_pk_bf16_f32 v20, v30, v31
	v_cvt_pk_bf16_f32 v21, v32, v33
	s_mov_b32 s6, 0x9003000
	global_store_dwordx4 v[50:51], v[18:21], off offset:2064
	global_store_dwordx4 v[6:7], v[2:5], off
	v_add_co_u32_e32 v40, vcc, s6, v98
	s_nop 0
	v_cvt_pk_bf16_f32 v2, v10, v11
	v_cvt_pk_bf16_f32 v3, v12, v13
	v_cvt_pk_bf16_f32 v4, v14, v15
	v_cvt_pk_bf16_f32 v5, v16, v17
	global_store_dwordx4 v[6:7], v[2:5], off offset:16
	v_addc_co_u32_e32 v41, vcc, 0, v99, vcc
	global_load_dwordx4 v[2:5], v[40:41], off offset:-4096
	global_load_dwordx4 v[34:37], v[38:39], off offset:32
	s_waitcnt vmcnt(1)
	v_mfma_f32_32x32x16_bf16 v[18:33], v[62:65], v[2:5], 0
	v_mfma_f32_32x32x16_bf16 v[2:17], v[66:69], v[2:5], 0
	s_waitcnt vmcnt(0)
	v_mfma_f32_32x32x16_bf16 v[18:33], v[70:73], v[34:37], v[18:33]
	v_mfma_f32_32x32x16_bf16 v[2:17], v[74:77], v[34:37], v[2:17]
	global_load_dwordx4 v[34:37], v[38:39], off offset:64
	s_nop 9
	v_cvt_pk_bf16_f32 v18, v18, v19
	v_cvt_pk_bf16_f32 v19, v20, v21
	v_cvt_pk_bf16_f32 v20, v22, v23
	v_add_co_u32_e32 v22, vcc, s7, v108
	v_cvt_pk_bf16_f32 v21, v24, v25
	s_waitcnt vmcnt(0)
	v_mfma_f32_32x32x16_bf16 v[2:17], v[78:81], v[34:37], v[2:17]
	global_load_dwordx4 v[34:37], v[38:39], off offset:96
	v_addc_co_u32_e32 v23, vcc, 0, v109, vcc
	global_store_dwordx4 v[22:23], v[18:21], off
	s_nop 1
	v_cvt_pk_bf16_f32 v18, v26, v27
	s_waitcnt vmcnt(1)
	v_mfma_f32_32x32x16_bf16 v[2:17], v[82:85], v[34:37], v[2:17]
	v_cvt_pk_bf16_f32 v19, v28, v29
	v_cvt_pk_bf16_f32 v20, v30, v31
	v_cvt_pk_bf16_f32 v21, v32, v33
	global_store_dwordx4 v[22:23], v[18:21], off offset:16
	s_nop 7
	v_cvt_pk_bf16_f32 v2, v2, v3
	v_cvt_pk_bf16_f32 v3, v4, v5
	v_cvt_pk_bf16_f32 v4, v6, v7
	v_add_co_u32_e32 v6, vcc, s7, v106
	v_cvt_pk_bf16_f32 v5, v8, v9
	s_nop 0
	v_addc_co_u32_e32 v7, vcc, 0, v107, vcc
	global_store_dwordx4 v[6:7], v[2:5], off
	s_nop 1
	v_cvt_pk_bf16_f32 v2, v10, v11
	v_cvt_pk_bf16_f32 v3, v12, v13
	v_cvt_pk_bf16_f32 v4, v14, v15
	v_cvt_pk_bf16_f32 v5, v16, v17
	global_store_dwordx4 v[6:7], v[2:5], off offset:16
	global_load_dwordx4 v[2:5], v[40:41], off
	s_nop 0
	global_load_dwordx4 v[34:37], v[40:41], off offset:32
	s_waitcnt vmcnt(1)
	v_mfma_f32_32x32x16_bf16 v[18:33], v[62:65], v[2:5], 0
	v_mfma_f32_32x32x16_bf16 v[2:17], v[66:69], v[2:5], 0
	s_waitcnt vmcnt(0)
	v_mfma_f32_32x32x16_bf16 v[18:33], v[70:73], v[34:37], v[18:33]
	v_mfma_f32_32x32x16_bf16 v[2:17], v[74:77], v[34:37], v[2:17]
	global_load_dwordx4 v[34:37], v[40:41], off offset:64
	s_nop 9
	v_cvt_pk_bf16_f32 v18, v18, v19
	v_cvt_pk_bf16_f32 v19, v20, v21
	v_cvt_pk_bf16_f32 v20, v22, v23
	v_add_co_u32_e32 v22, vcc, s7, v102
	v_cvt_pk_bf16_f32 v21, v24, v25
	s_waitcnt vmcnt(0)
	v_mfma_f32_32x32x16_bf16 v[2:17], v[78:81], v[34:37], v[2:17]
	global_load_dwordx4 v[34:37], v[40:41], off offset:96
	v_addc_co_u32_e32 v23, vcc, 0, v103, vcc
	global_store_dwordx4 v[22:23], v[18:21], off
	s_nop 1
	v_cvt_pk_bf16_f32 v18, v26, v27
	s_waitcnt vmcnt(1)
	v_mfma_f32_32x32x16_bf16 v[2:17], v[82:85], v[34:37], v[2:17]
	v_cvt_pk_bf16_f32 v19, v28, v29
	v_cvt_pk_bf16_f32 v20, v30, v31
	v_cvt_pk_bf16_f32 v21, v32, v33
	global_store_dwordx4 v[22:23], v[18:21], off offset:16
	s_nop 7
	v_cvt_pk_bf16_f32 v2, v2, v3
	v_cvt_pk_bf16_f32 v3, v4, v5
	v_cvt_pk_bf16_f32 v4, v6, v7
	v_add_co_u32_e32 v6, vcc, s7, v100
	v_cvt_pk_bf16_f32 v5, v8, v9
	s_nop 0
	v_addc_co_u32_e32 v7, vcc, 0, v101, vcc
	global_store_dwordx4 v[6:7], v[2:5], off
	s_nop 1
	v_cvt_pk_bf16_f32 v2, v10, v11
	v_cvt_pk_bf16_f32 v3, v12, v13
	v_cvt_pk_bf16_f32 v4, v14, v15
	v_cvt_pk_bf16_f32 v5, v16, v17
	global_store_dwordx4 v[6:7], v[2:5], off offset:16
	v_readlane_b32 s6, v210, 0
	v_readlane_b32 s7, v210, 1
	s_lshl_b64 s[4:5], s[4:5], 20
	v_readlane_b32 s8, v250, 17
	v_pk_mul_f32 v[2:3], v[152:153], s[6:7]
	v_readlane_b32 s6, v210, 8
	v_readlane_b32 s7, v210, 9
	v_cvt_pk_bf16_f32 v34, v2, v3
	s_nop 0
	v_pk_mul_f32 v[4:5], v[168:169], s[6:7]
	v_readlane_b32 s6, v210, 2
	v_readlane_b32 s7, v210, 3
	v_cvt_pk_bf16_f32 v38, v4, v5
	s_nop 1
	v_permlane32_swap_b32_e32 v34, v38
	v_pk_mul_f32 v[6:7], v[188:189], s[6:7]
	v_readlane_b32 s6, v210, 10
	v_readlane_b32 s7, v210, 11
	v_cvt_pk_bf16_f32 v35, v6, v7
	s_nop 0
	v_pk_mul_f32 v[8:9], v[160:161], s[6:7]
	v_readlane_b32 s6, v210, 4
	v_readlane_b32 s7, v210, 5
	v_cvt_pk_bf16_f32 v39, v8, v9
	s_nop 1
	v_permlane32_swap_b32_e32 v35, v39
	v_pk_mul_f32 v[10:11], v[186:187], s[6:7]
	v_readlane_b32 s6, v210, 12
	v_readlane_b32 s7, v210, 13
	v_cvt_pk_bf16_f32 v36, v10, v11
	s_nop 0
	v_pk_mul_f32 v[12:13], v[154:155], s[6:7]
	v_readlane_b32 s6, v210, 6
	v_readlane_b32 s7, v210, 7
	v_cvt_pk_bf16_f32 v40, v12, v13
	s_nop 1
	v_permlane32_swap_b32_e32 v36, v40
	v_pk_mul_f32 v[14:15], v[182:183], s[6:7]
	v_readlane_b32 s6, v210, 14
	v_readlane_b32 s7, v210, 15
	v_cvt_pk_bf16_f32 v37, v14, v15
	s_nop 0
	v_pk_mul_f32 v[16:17], v[162:163], s[6:7]
	v_readlane_b32 s6, v210, 16
	v_readlane_b32 s7, v210, 17
	v_cvt_pk_bf16_f32 v41, v16, v17
	s_nop 1
	v_permlane32_swap_b32_e32 v37, v41
	v_pk_mul_f32 v[2:3], v[164:165], s[6:7]
	v_readlane_b32 s6, v210, 24
	v_readlane_b32 s7, v210, 25
	v_cvt_pk_bf16_f32 v42, v2, v3
	s_nop 0
	v_pk_mul_f32 v[4:5], v[146:147], s[6:7]
	v_readlane_b32 s6, v210, 18
	v_readlane_b32 s7, v210, 19
	v_cvt_pk_bf16_f32 v46, v4, v5
	s_nop 1
	v_permlane32_swap_b32_e32 v42, v46
	v_pk_mul_f32 v[6:7], v[156:157], s[6:7]
	v_readlane_b32 s6, v210, 26
	v_readlane_b32 s7, v210, 27
	v_cvt_pk_bf16_f32 v43, v6, v7
	s_nop 0
	v_pk_mul_f32 v[8:9], v[144:145], s[6:7]
	v_readlane_b32 s6, v210, 20
	v_readlane_b32 s7, v210, 21
	v_cvt_pk_bf16_f32 v47, v8, v9
	s_nop 1
	v_permlane32_swap_b32_e32 v43, v47
	v_pk_mul_f32 v[10:11], v[150:151], s[6:7]
	v_readlane_b32 s6, v210, 28
	v_readlane_b32 s7, v210, 29
	v_cvt_pk_bf16_f32 v44, v10, v11
	s_nop 0
	v_pk_mul_f32 v[12:13], v[142:143], s[6:7]
	v_readlane_b32 s6, v210, 22
	v_readlane_b32 s7, v210, 23
	v_cvt_pk_bf16_f32 v48, v12, v13
	s_nop 1
	v_permlane32_swap_b32_e32 v44, v48
	v_pk_mul_f32 v[14:15], v[148:149], s[6:7]
	v_readlane_b32 s6, v210, 30
	v_readlane_b32 s7, v210, 31
	v_cvt_pk_bf16_f32 v45, v14, v15
	s_nop 0
	v_pk_mul_f32 v[16:17], v[140:141], s[6:7]
	v_readlane_b32 s6, v210, 32
	v_readlane_b32 s7, v210, 33
	v_cvt_pk_bf16_f32 v49, v16, v17
	s_nop 1
	v_permlane32_swap_b32_e32 v45, v49
	v_pk_mul_f32 v[2:3], v[138:139], s[6:7]
	v_readlane_b32 s6, v210, 40
	v_readlane_b32 s7, v210, 41
	v_cvt_pk_bf16_f32 v2, v2, v3
	s_nop 0
	v_pk_mul_f32 v[4:5], v[130:131], s[6:7]
	v_readlane_b32 s6, v210, 34
	v_readlane_b32 s7, v210, 35
	v_cvt_pk_bf16_f32 v50, v4, v5
	s_nop 1
	v_permlane32_swap_b32_e32 v2, v50
	v_pk_mul_f32 v[6:7], v[136:137], s[6:7]
	v_readlane_b32 s6, v210, 42
	v_readlane_b32 s7, v210, 43
	v_cvt_pk_bf16_f32 v3, v6, v7
	s_nop 0
	v_pk_mul_f32 v[8:9], v[128:129], s[6:7]
	v_readlane_b32 s6, v210, 36
	v_readlane_b32 s7, v210, 37
	v_cvt_pk_bf16_f32 v51, v8, v9
	s_nop 1
	v_permlane32_swap_b32_e32 v3, v51
	v_pk_mul_f32 v[10:11], v[134:135], s[6:7]
	v_readlane_b32 s6, v210, 44
	v_readlane_b32 s7, v210, 45
	v_cvt_pk_bf16_f32 v6, v10, v11
	s_nop 0
	v_pk_mul_f32 v[12:13], v[118:119], s[6:7]
	v_readlane_b32 s6, v210, 38
	v_readlane_b32 s7, v210, 39
	v_cvt_pk_bf16_f32 v52, v12, v13
	s_nop 1
	v_permlane32_swap_b32_e32 v6, v52
	v_pk_mul_f32 v[14:15], v[132:133], s[6:7]
	v_readlane_b32 s6, v210, 46
	v_readlane_b32 s7, v210, 47
	v_cvt_pk_bf16_f32 v7, v14, v15
	s_nop 0
	v_pk_mul_f32 v[16:17], v[116:117], s[6:7]
	v_readlane_b32 s6, v210, 48
	v_readlane_b32 s7, v210, 49
	v_cvt_pk_bf16_f32 v53, v16, v17
	s_nop 1
	v_permlane32_swap_b32_e32 v7, v53
	v_pk_mul_f32 v[2:3], v[114:115], s[6:7]
	v_readlane_b32 s6, v210, 56
	v_readlane_b32 s7, v210, 57
	v_cvt_pk_bf16_f32 v2, v2, v3
	s_nop 0
	v_pk_mul_f32 v[4:5], v[94:95], s[6:7]
	v_readlane_b32 s6, v210, 50
	v_readlane_b32 s7, v210, 51
	v_cvt_pk_bf16_f32 v54, v4, v5
	s_nop 1
	v_permlane32_swap_b32_e32 v2, v54
	v_pk_mul_f32 v[6:7], v[110:111], s[6:7]
	v_readlane_b32 s6, v210, 58
	v_readlane_b32 s7, v210, 59
	v_cvt_pk_bf16_f32 v3, v6, v7
	v_lshlrev_b32_e32 v2, 8, v192
	v_pk_mul_f32 v[8:9], v[92:93], s[6:7]
	v_readlane_b32 s6, v210, 52
	v_readlane_b32 s7, v210, 53
	v_cvt_pk_bf16_f32 v55, v8, v9
	s_nop 1
	v_permlane32_swap_b32_e32 v3, v55
	v_pk_mul_f32 v[10:11], v[104:105], s[6:7]
	v_readlane_b32 s6, v210, 60
	v_readlane_b32 s7, v210, 61
	v_mov_b32_e32 v3, v123
	v_lshl_add_u64 v[2:3], v[2:3], 0, v[124:125]
	v_pk_mul_f32 v[12:13], v[90:91], s[6:7]
	v_readlane_b32 s6, v210, 54
	v_readlane_b32 s7, v210, 55
	v_lshl_add_u64 v[64:65], s[0:1], 0, v[2:3]
	v_cvt_pk_bf16_f32 v6, v10, v11
	v_pk_mul_f32 v[14:15], v[96:97], s[6:7]
	v_readlane_b32 s6, v210, 62
	v_readlane_b32 s7, v210, 63
	v_cvt_pk_bf16_f32 v7, v14, v15
	v_cvt_pk_bf16_f32 v56, v12, v13
	v_pk_mul_f32 v[16:17], v[88:89], s[6:7]
	v_readlane_b32 s6, v250, 3
	s_add_u32 s4, s6, s4
	v_readlane_b32 s6, v250, 4
	s_addc_u32 s5, s6, s5
	v_readlane_b32 s6, v250, 13
	s_lshl_b32 s6, s6, 14
	s_add_u32 s4, s4, s6
	s_addc_u32 s5, s5, 0
	v_lshl_add_u64 v[62:63], s[4:5], 0, v[86:87]
	v_lshl_add_u64 v[66:67], v[62:63], 0, v[122:123]
	v_mov_b32_e32 v142, 0x1000
	v_mov_b32_e32 v143, 0
	v_lshl_add_u64 v[130:131], v[66:67], 0, v[142:143]
	v_lshl_add_u64 v[134:135], v[130:131], 0, v[142:143]
	v_lshl_add_u64 v[138:139], v[134:135], 0, v[142:143]
	global_load_dwordx4 v[202:205], v[66:67], off
	global_load_dwordx4 v[208:211], v[66:67], off offset:32
	global_load_dwordx4 v[212:215], v[66:67], off offset:64
	global_load_dwordx4 v[216:219], v[66:67], off offset:96
	global_load_dwordx4 v[220:223], v[130:131], off
	global_load_dwordx4 v[234:237], v[130:131], off offset:32
	global_load_dwordx4 v[238:241], v[130:131], off offset:64
	global_load_dwordx4 v[242:245], v[130:131], off offset:96
	s_nop 0
	s_nop 0
	v_cvt_pk_bf16_f32 v57, v16, v17
	v_permlane32_swap_b32_e32 v6, v56
	s_nop 0
	v_permlane32_swap_b32_e32 v7, v57
	s_nop 0
	s_waitcnt vmcnt(7)
	v_mfma_f32_32x32x16_bf16 v[18:33], v[202:205], v[34:37], 0
	s_mov_b32 s0, 0x2e400000
	v_readlane_b32 s7, v250, 15
	v_mfma_f32_32x32x16_bf16 v[2:17], v[202:205], v[38:41], 0
	s_nop 0
	s_waitcnt vmcnt(6)
	v_mfma_f32_32x32x16_bf16 v[18:33], v[208:211], v[42:45], v[18:33]
	v_mfma_f32_32x32x16_bf16 v[2:17], v[208:211], v[46:49], v[2:17]
	s_nop 0
	s_nop 9
	v_cvt_pk_bf16_f32 v18, v18, v19
	v_cvt_pk_bf16_f32 v19, v20, v21
	s_nop 0
	s_waitcnt vmcnt(5)
	v_mfma_f32_32x32x16_bf16 v[2:17], v[212:215], v[50:53], v[2:17]
	s_nop 0
	s_nop 0
	s_waitcnt vmcnt(4)
	v_mfma_f32_32x32x16_bf16 v[2:17], v[216:219], v[54:57], v[2:17]
	v_add_co_u32_e32 v58, vcc, s0, v64
	s_mov_b32 s0, 0x2e402000
	s_nop 0
	v_addc_co_u32_e32 v59, vcc, 0, v65, vcc
	v_add_co_u32_e32 v60, vcc, s0, v64
	s_nop 6
	v_cvt_pk_bf16_f32 v2, v2, v3
	v_cvt_pk_bf16_f32 v3, v4, v5
	v_addc_co_u32_e32 v61, vcc, 0, v65, vcc
	global_store_dwordx2 v[60:61], v[2:3], off
	v_cvt_pk_bf16_f32 v2, v22, v23
	v_cvt_pk_bf16_f32 v3, v24, v25
	global_store_dwordx2 v[58:59], v[2:3], off offset:16
	v_cvt_pk_bf16_f32 v2, v6, v7
	v_cvt_pk_bf16_f32 v3, v8, v9
	global_store_dwordx2 v[60:61], v[2:3], off offset:16
	v_cvt_pk_bf16_f32 v2, v26, v27
	v_cvt_pk_bf16_f32 v3, v28, v29
	global_store_dwordx2 v[58:59], v[2:3], off offset:32
	v_cvt_pk_bf16_f32 v2, v10, v11
	v_cvt_pk_bf16_f32 v3, v12, v13
	global_store_dwordx2 v[60:61], v[2:3], off offset:32
	v_cvt_pk_bf16_f32 v2, v30, v31
	v_cvt_pk_bf16_f32 v3, v32, v33
	global_store_dwordx2 v[58:59], v[2:3], off offset:48
	v_cvt_pk_bf16_f32 v2, v14, v15
	v_cvt_pk_bf16_f32 v3, v16, v17
	global_store_dwordx2 v[60:61], v[2:3], off offset:48
	v_or_b32_e32 v2, 0x1000, v122
	v_mov_b32_e32 v3, v123
	global_store_dwordx2 v[58:59], v[18:19], off
	v_lshl_add_u64 v[68:69], v[62:63], 0, v[2:3]
	global_load_dwordx4 v[202:205], v[134:135], off
	global_load_dwordx4 v[208:211], v[134:135], off offset:32
	global_load_dwordx4 v[212:215], v[134:135], off offset:64
	global_load_dwordx4 v[216:219], v[134:135], off offset:96
	s_nop 0
	s_nop 0
	s_nop 0
	s_waitcnt vmcnt(15)
	v_mfma_f32_32x32x16_bf16 v[18:33], v[220:223], v[34:37], 0
	v_readlane_b32 s0, v250, 9
	v_readlane_b32 s1, v250, 10
	s_add_i32 s33, s33, s0
	v_readlane_b32 s0, v250, 5
	v_readlane_b32 s1, v250, 6
	s_add_u32 s24, s24, s0
	s_addc_u32 s25, s25, s1
	v_mfma_f32_32x32x16_bf16 v[2:17], v[220:223], v[38:41], 0
	v_readlane_b32 s0, v250, 7
	v_readlane_b32 s1, v250, 8
	s_add_u32 s28, s28, s0
	s_addc_u32 s29, s29, s1
	v_readlane_b32 s0, v250, 11
	v_readlane_b32 s1, v250, 12
	s_add_u32 s7, s7, s0
	s_nop 0
	s_waitcnt vmcnt(14)
	v_mfma_f32_32x32x16_bf16 v[18:33], v[234:237], v[42:45], v[18:33]
	s_addc_u32 s8, s8, s1
	s_cmpk_lt_i32 s33, 0x2000
	v_mfma_f32_32x32x16_bf16 v[2:17], v[234:237], v[46:49], v[2:17]
	s_nop 0
	s_nop 7
	v_cvt_pk_bf16_f32 v18, v18, v19
	v_cvt_pk_bf16_f32 v19, v20, v21
	s_nop 0
	s_waitcnt vmcnt(13)
	v_mfma_f32_32x32x16_bf16 v[2:17], v[238:241], v[50:53], v[2:17]
	s_nop 0
	s_nop 0
	global_store_dwordx2 v[58:59], v[18:19], off offset:64
	s_nop 0
	s_waitcnt vmcnt(13)
	v_mfma_f32_32x32x16_bf16 v[2:17], v[242:245], v[54:57], v[2:17]
	s_nop 11
	v_cvt_pk_bf16_f32 v2, v2, v3
	v_cvt_pk_bf16_f32 v3, v4, v5
	global_store_dwordx2 v[60:61], v[2:3], off offset:64
	v_cvt_pk_bf16_f32 v2, v22, v23
	v_cvt_pk_bf16_f32 v3, v24, v25
	global_store_dwordx2 v[58:59], v[2:3], off offset:80
	v_cvt_pk_bf16_f32 v2, v6, v7
	v_cvt_pk_bf16_f32 v3, v8, v9
	global_store_dwordx2 v[60:61], v[2:3], off offset:80
	v_cvt_pk_bf16_f32 v2, v26, v27
	v_cvt_pk_bf16_f32 v3, v28, v29
	global_store_dwordx2 v[58:59], v[2:3], off offset:96
	v_cvt_pk_bf16_f32 v2, v10, v11
	v_cvt_pk_bf16_f32 v3, v12, v13
	global_store_dwordx2 v[60:61], v[2:3], off offset:96
	v_cvt_pk_bf16_f32 v2, v30, v31
	v_cvt_pk_bf16_f32 v3, v32, v33
	global_store_dwordx2 v[58:59], v[2:3], off offset:112
	v_cvt_pk_bf16_f32 v2, v14, v15
	v_cvt_pk_bf16_f32 v3, v16, v17
	global_store_dwordx2 v[60:61], v[2:3], off offset:112
	v_or_b32_e32 v2, 0x2000, v122
	v_mov_b32_e32 v3, v123
	v_lshl_add_u64 v[68:69], v[62:63], 0, v[2:3]
	global_load_dwordx4 v[220:223], v[138:139], off
	global_load_dwordx4 v[234:237], v[138:139], off offset:32
	global_load_dwordx4 v[238:241], v[138:139], off offset:64
	global_load_dwordx4 v[242:245], v[138:139], off offset:96
	s_nop 0
	s_nop 0
	s_nop 0
	s_waitcnt vmcnt(15)
	v_mfma_f32_32x32x16_bf16 v[18:33], v[202:205], v[34:37], 0
	v_or_b32_e32 v122, 0x3000, v122
	v_lshl_add_u64 v[62:63], v[62:63], 0, v[122:123]
	v_mfma_f32_32x32x16_bf16 v[2:17], v[202:205], v[38:41], 0
	s_nop 0
	s_waitcnt vmcnt(14)
	v_mfma_f32_32x32x16_bf16 v[18:33], v[208:211], v[42:45], v[18:33]
	v_mfma_f32_32x32x16_bf16 v[2:17], v[208:211], v[46:49], v[2:17]
	s_nop 0
	s_nop 9
	v_cvt_pk_bf16_f32 v18, v18, v19
	v_cvt_pk_bf16_f32 v19, v20, v21
	s_nop 0
	s_waitcnt vmcnt(13)
	v_mfma_f32_32x32x16_bf16 v[2:17], v[212:215], v[50:53], v[2:17]
	s_nop 0
	s_nop 0
	global_store_dwordx2 v[58:59], v[18:19], off offset:128
	s_nop 0
	s_waitcnt vmcnt(13)
	v_mfma_f32_32x32x16_bf16 v[2:17], v[216:219], v[54:57], v[2:17]
	s_nop 11
	v_cvt_pk_bf16_f32 v2, v2, v3
	v_cvt_pk_bf16_f32 v3, v4, v5
	global_store_dwordx2 v[60:61], v[2:3], off offset:128
	v_cvt_pk_bf16_f32 v2, v22, v23
	v_cvt_pk_bf16_f32 v3, v24, v25
	global_store_dwordx2 v[58:59], v[2:3], off offset:144
	v_cvt_pk_bf16_f32 v2, v6, v7
	v_cvt_pk_bf16_f32 v3, v8, v9
	global_store_dwordx2 v[60:61], v[2:3], off offset:144
	v_cvt_pk_bf16_f32 v2, v26, v27
	v_cvt_pk_bf16_f32 v3, v28, v29
	global_store_dwordx2 v[58:59], v[2:3], off offset:160
	v_cvt_pk_bf16_f32 v2, v10, v11
	v_cvt_pk_bf16_f32 v3, v12, v13
	global_store_dwordx2 v[60:61], v[2:3], off offset:160
	v_cvt_pk_bf16_f32 v2, v30, v31
	v_cvt_pk_bf16_f32 v3, v32, v33
	global_store_dwordx2 v[58:59], v[2:3], off offset:176
	v_cvt_pk_bf16_f32 v2, v14, v15
	v_cvt_pk_bf16_f32 v3, v16, v17
	global_store_dwordx2 v[60:61], v[2:3], off offset:176
	s_nop 0
	s_nop 0
	s_waitcnt vmcnt(11)
	v_mfma_f32_32x32x16_bf16 v[18:33], v[220:223], v[34:37], 0
	s_nop 0
	v_mfma_f32_32x32x16_bf16 v[2:17], v[220:223], v[38:41], 0
	s_nop 0
	s_waitcnt vmcnt(10)
	v_mfma_f32_32x32x16_bf16 v[18:33], v[234:237], v[42:45], v[18:33]
	s_nop 11
	v_cvt_pk_bf16_f32 v18, v18, v19
	v_mfma_f32_32x32x16_bf16 v[2:17], v[234:237], v[46:49], v[2:17]
	s_nop 0
	v_cvt_pk_bf16_f32 v19, v20, v21
	s_nop 0
	s_waitcnt vmcnt(9)
	v_mfma_f32_32x32x16_bf16 v[2:17], v[238:241], v[50:53], v[2:17]
	s_nop 0
	s_nop 0
	global_store_dwordx2 v[58:59], v[18:19], off offset:192
	s_nop 0
	s_waitcnt vmcnt(9)
	v_mfma_f32_32x32x16_bf16 v[2:17], v[242:245], v[54:57], v[2:17]
	s_nop 11
	v_cvt_pk_bf16_f32 v2, v2, v3
	v_cvt_pk_bf16_f32 v3, v4, v5
	global_store_dwordx2 v[60:61], v[2:3], off offset:192
	v_cvt_pk_bf16_f32 v2, v22, v23
	v_cvt_pk_bf16_f32 v3, v24, v25
	global_store_dwordx2 v[58:59], v[2:3], off offset:208
	v_cvt_pk_bf16_f32 v2, v6, v7
	v_cvt_pk_bf16_f32 v3, v8, v9
	global_store_dwordx2 v[60:61], v[2:3], off offset:208
	v_cvt_pk_bf16_f32 v2, v26, v27
	v_cvt_pk_bf16_f32 v3, v28, v29
	global_store_dwordx2 v[58:59], v[2:3], off offset:224
	v_cvt_pk_bf16_f32 v2, v10, v11
	v_cvt_pk_bf16_f32 v3, v12, v13
	global_store_dwordx2 v[60:61], v[2:3], off offset:224
	v_cvt_pk_bf16_f32 v2, v30, v31
	v_cvt_pk_bf16_f32 v3, v32, v33
	global_store_dwordx2 v[58:59], v[2:3], off offset:240
	v_cvt_pk_bf16_f32 v2, v14, v15
	v_cvt_pk_bf16_f32 v3, v16, v17
	global_store_dwordx2 v[60:61], v[2:3], off offset:240
	s_waitcnt lgkmcnt(0)
	s_cbranch_scc0 .LBB0_782

	.amdhsa_kernel _Z3fwd4Args
		.amdhsa_group_segment_fixed_size 0
		.amdhsa_private_segment_fixed_size 0
		.amdhsa_kernarg_size 448
		.amdhsa_user_sgpr_count 2
		.amdhsa_user_sgpr_dispatch_ptr 0
		.amdhsa_user_sgpr_queue_ptr 0
		.amdhsa_user_sgpr_kernarg_segment_ptr 1
		.amdhsa_user_sgpr_dispatch_id 0
		.amdhsa_user_sgpr_kernarg_preload_length 0
		.amdhsa_user_sgpr_kernarg_preload_offset 0
		.amdhsa_user_sgpr_private_segment_size 0
		.amdhsa_uses_dynamic_stack 0
		.amdhsa_enable_private_segment 0
		.amdhsa_system_sgpr_workgroup_id_x 1
		.amdhsa_system_sgpr_workgroup_id_y 0
		.amdhsa_system_sgpr_workgroup_id_z 0
		.amdhsa_system_sgpr_workgroup_info 0
		.amdhsa_system_vgpr_workitem_id 0
		.amdhsa_next_free_vgpr 256
		.amdhsa_next_free_sgpr 99
		.amdhsa_accum_offset 256
		.amdhsa_reserve_vcc 1
		.amdhsa_float_round_mode_32 0
		.amdhsa_float_round_mode_16_64 0
		.amdhsa_float_denorm_mode_32 3
		.amdhsa_float_denorm_mode_16_64 3
		.amdhsa_dx10_clamp 1
		.amdhsa_ieee_mode 1
		.amdhsa_fp16_overflow 0
		.amdhsa_tg_split 0
		.amdhsa_exception_fp_ieee_invalid_op 0
		.amdhsa_exception_fp_denorm_src 0
		.amdhsa_exception_fp_ieee_div_zero 0
		.amdhsa_exception_fp_ieee_overflow 0
		.amdhsa_exception_fp_ieee_underflow 0
		.amdhsa_exception_fp_ieee_inexact 0
		.amdhsa_exception_int_div_zero 0
	.end_amdhsa_kernel

amdhsa.kernels:
  - .agpr_count:     0
    .args:
      - .offset:         0
        .size:           192
        .value_kind:     by_value
      - .offset:         192
        .size:           4
        .value_kind:     hidden_block_count_x
      - .offset:         196
        .size:           4
        .value_kind:     hidden_block_count_y
      - .offset:         200
        .size:           4
        .value_kind:     hidden_block_count_z
      - .offset:         204
        .size:           2
        .value_kind:     hidden_group_size_x
      - .offset:         206
        .size:           2
        .value_kind:     hidden_group_size_y
      - .offset:         208
        .size:           2
        .value_kind:     hidden_group_size_z
      - .offset:         210
        .size:           2
        .value_kind:     hidden_remainder_x
      - .offset:         212
        .size:           2
        .value_kind:     hidden_remainder_y
      - .offset:         214
        .size:           2
        .value_kind:     hidden_remainder_z
      - .offset:         232
        .size:           8
        .value_kind:     hidden_global_offset_x
      - .offset:         240
        .size:           8
        .value_kind:     hidden_global_offset_y
      - .offset:         248
        .size:           8
        .value_kind:     hidden_global_offset_z
      - .offset:         256
        .size:           2
        .value_kind:     hidden_grid_dims
      - .offset:         312
        .size:           4
        .value_kind:     hidden_dynamic_lds_size
    .group_segment_fixed_size: 0
    .kernarg_segment_align: 8
    .kernarg_segment_size: 448
    .language:       OpenCL C
    .language_version:
      - 2
      - 0
    .max_flat_workgroup_size: 512
    .name:           _Z3fwd4Args
    .private_segment_fixed_size: 0
    .sgpr_count:     105
    .sgpr_spill_count: 171
    .symbol:         _Z3fwd4Args.kd
    .uniform_work_group_size: 1
    .uses_dynamic_stack: false
    .vgpr_count:     256
    .vgpr_spill_count: 0
    .wavefront_size: 64
